# LDS-DMA issue rebalanced 3+5 per K-loop load-segment pair (one piece moved from each 6-piece segment to the head of the next), closing waits vmcnt(7)
# baseline (speedup 1.0000x reference)
.LBB0_163:
	s_cmp_eq_i32 s55, -2
	s_cbranch_scc1 .Lbal_first_21
	s_mov_b32 m0, s46
	s_nop 0
	global_load_lds_dwordx4 v205, s[100:101]
.Lbal_first_21:
	ds_read_b128 v[144:147], v151
	ds_read_b128 v[156:159], v151 offset:1024
	ds_read_b128 v[160:163], v151 offset:2048
	ds_read_b128 v[164:167], v151 offset:3072
	ds_read_b128 v[168:171], v152
	ds_read_b128 v[172:175], v152 offset:1024
	ds_read_b128 v[176:179], v152 offset:2048
	ds_read_b128 v[180:183], v152 offset:3072
	s_add_u32 s26, s24, 0xfffc0080
	s_addc_u32 s27, s25, -1
	s_cmp_eq_u32 s55, 12
	s_cselect_b32 s29, s19, s27
	s_cselect_b32 s28, s51, s26
	s_cselect_b32 s27, s17, s54
	s_cselect_b32 s26, s52, s53
	s_add_i32 m0, s38, 0xc000
	ds_read_b128 v[184:187], v153
	ds_read_b128 v[188:191], v153 offset:1024
	ds_read_b128 v[192:195], v153 offset:2048
	ds_read_b128 v[196:199], v153 offset:3072
	ds_read_b128 v[200:203], v153 offset:4096
	ds_read_b128 v[208:211], v153 offset:5120
	ds_read_b128 v[212:215], v153 offset:6144
	ds_read_b128 v[216:219], v153 offset:7168
	global_load_lds_dwordx4 v138, s[24:25]
	s_add_i32 m0, s38, 0xe000
	s_nop 0
	global_load_lds_dwordx4 v136, s[24:25]
	s_waitcnt vmcnt(8)
	s_waitcnt lgkmcnt(0)
	s_barrier
	s_waitcnt lgkmcnt(0)
	v_mfma_f32_16x16x32_bf16 v[124:127], v[144:147], v[184:187], v[124:127]
	v_mfma_f32_16x16x32_bf16 v[120:123], v[160:163], v[184:187], v[120:123]
	v_mfma_f32_16x16x32_bf16 v[108:111], v[144:147], v[192:195], v[108:111]
	v_mfma_f32_16x16x32_bf16 v[104:107], v[160:163], v[192:195], v[104:107]
	v_mfma_f32_16x16x32_bf16 v[92:95], v[144:147], v[200:203], v[92:95]
	v_mfma_f32_16x16x32_bf16 v[88:91], v[160:163], v[200:203], v[88:91]
	v_mfma_f32_16x16x32_bf16 v[76:79], v[144:147], v[212:215], v[76:79]
	v_mfma_f32_16x16x32_bf16 v[72:75], v[160:163], v[212:215], v[72:75]
	v_mfma_f32_16x16x32_bf16 v[124:127], v[156:159], v[188:191], v[124:127]
	v_mfma_f32_16x16x32_bf16 v[120:123], v[164:167], v[188:191], v[120:123]
	v_mfma_f32_16x16x32_bf16 v[108:111], v[156:159], v[196:199], v[108:111]
	v_mfma_f32_16x16x32_bf16 v[104:107], v[164:167], v[196:199], v[104:107]
	v_mfma_f32_16x16x32_bf16 v[92:95], v[156:159], v[208:211], v[92:95]
	v_mfma_f32_16x16x32_bf16 v[88:91], v[164:167], v[208:211], v[88:91]
	v_mfma_f32_16x16x32_bf16 v[76:79], v[156:159], v[216:219], v[76:79]
	v_mfma_f32_16x16x32_bf16 v[72:75], v[164:167], v[216:219], v[72:75]
	v_mfma_f32_16x16x32_bf16 v[116:119], v[168:171], v[184:187], v[116:119]
	v_mfma_f32_16x16x32_bf16 v[112:115], v[176:179], v[184:187], v[112:115]
	v_mfma_f32_16x16x32_bf16 v[100:103], v[168:171], v[192:195], v[100:103]
	v_mfma_f32_16x16x32_bf16 v[96:99], v[176:179], v[192:195], v[96:99]
	v_mfma_f32_16x16x32_bf16 v[84:87], v[168:171], v[200:203], v[84:87]
	v_mfma_f32_16x16x32_bf16 v[80:83], v[176:179], v[200:203], v[80:83]
	v_mfma_f32_16x16x32_bf16 v[68:71], v[168:171], v[212:215], v[68:71]
	v_mfma_f32_16x16x32_bf16 v[64:67], v[176:179], v[212:215], v[64:67]
	v_mfma_f32_16x16x32_bf16 v[116:119], v[172:175], v[188:191], v[116:119]
	v_mfma_f32_16x16x32_bf16 v[112:115], v[180:183], v[188:191], v[112:115]
	v_mfma_f32_16x16x32_bf16 v[100:103], v[172:175], v[196:199], v[100:103]
	v_mfma_f32_16x16x32_bf16 v[96:99], v[180:183], v[196:199], v[96:99]
	v_mfma_f32_16x16x32_bf16 v[84:87], v[172:175], v[208:211], v[84:87]
	v_mfma_f32_16x16x32_bf16 v[80:83], v[180:183], v[208:211], v[80:83]
	v_mfma_f32_16x16x32_bf16 v[68:71], v[172:175], v[216:219], v[68:71]
	v_mfma_f32_16x16x32_bf16 v[64:67], v[180:183], v[216:219], v[64:67]
	s_barrier
	s_add_i32 s56, s48, s35
	s_mov_b32 m0, s56
	ds_read_b128 v[184:187], v153 offset:16384
	ds_read_b128 v[188:191], v153 offset:17408
	ds_read_b128 v[192:195], v153 offset:18432
	ds_read_b128 v[196:199], v153 offset:19456
	ds_read_b128 v[200:203], v153 offset:20480
	ds_read_b128 v[208:211], v153 offset:21504
	ds_read_b128 v[212:215], v153 offset:22528
	ds_read_b128 v[216:219], v153 offset:23552
	global_load_lds_dwordx4 v132, s[26:27]
	s_add_i32 m0, s56, 0x2000
	s_add_u32 s56, s26, 0x40000
	s_mov_b64 s[98:99], s[26:27]
	s_addc_u32 s57, s27, 0
	s_add_i32 s58, s49, s35
	global_load_lds_dwordx4 v128, s[26:27]
	s_mov_b32 m0, s58
	s_mov_b64 s[100:101], s[28:29]
	global_load_lds_dwordx4 v132, s[56:57]
	s_add_i32 m0, s58, 0x2000
	s_nop 0
	global_load_lds_dwordx4 v128, s[56:57]
	s_mov_b32 m0, s38
	s_nop 0
	global_load_lds_dwordx4 v134, s[28:29]
	s_waitcnt vmcnt(7)
	s_waitcnt lgkmcnt(0)
	s_barrier
	s_waitcnt lgkmcnt(0)
	v_mfma_f32_16x16x32_bf16 v[60:63], v[144:147], v[184:187], v[60:63]
	v_mfma_f32_16x16x32_bf16 v[56:59], v[160:163], v[184:187], v[56:59]
	v_mfma_f32_16x16x32_bf16 v[44:47], v[144:147], v[192:195], v[44:47]
	v_mfma_f32_16x16x32_bf16 v[40:43], v[160:163], v[192:195], v[40:43]
	v_mfma_f32_16x16x32_bf16 v[28:31], v[144:147], v[200:203], v[28:31]
	v_mfma_f32_16x16x32_bf16 v[24:27], v[160:163], v[200:203], v[24:27]
	v_mfma_f32_16x16x32_bf16 v[12:15], v[144:147], v[212:215], v[12:15]
	v_mfma_f32_16x16x32_bf16 v[8:11], v[160:163], v[212:215], v[8:11]
	v_mfma_f32_16x16x32_bf16 v[60:63], v[156:159], v[188:191], v[60:63]
	v_mfma_f32_16x16x32_bf16 v[56:59], v[164:167], v[188:191], v[56:59]
	v_mfma_f32_16x16x32_bf16 v[44:47], v[156:159], v[196:199], v[44:47]
	v_mfma_f32_16x16x32_bf16 v[40:43], v[164:167], v[196:199], v[40:43]
	v_mfma_f32_16x16x32_bf16 v[28:31], v[156:159], v[208:211], v[28:31]
	v_mfma_f32_16x16x32_bf16 v[24:27], v[164:167], v[208:211], v[24:27]
	v_mfma_f32_16x16x32_bf16 v[12:15], v[156:159], v[216:219], v[12:15]
	v_mfma_f32_16x16x32_bf16 v[8:11], v[164:167], v[216:219], v[8:11]
	v_mfma_f32_16x16x32_bf16 v[52:55], v[168:171], v[184:187], v[52:55]
	v_mfma_f32_16x16x32_bf16 v[48:51], v[176:179], v[184:187], v[48:51]
	v_mfma_f32_16x16x32_bf16 v[36:39], v[168:171], v[192:195], v[36:39]
	v_mfma_f32_16x16x32_bf16 v[32:35], v[176:179], v[192:195], v[32:35]
	v_mfma_f32_16x16x32_bf16 v[20:23], v[168:171], v[200:203], v[20:23]
	v_mfma_f32_16x16x32_bf16 v[16:19], v[176:179], v[200:203], v[16:19]
	v_mfma_f32_16x16x32_bf16 v[4:7], v[168:171], v[212:215], v[4:7]
	v_mfma_f32_16x16x32_bf16 v[0:3], v[176:179], v[212:215], v[0:3]
	v_mfma_f32_16x16x32_bf16 v[52:55], v[172:175], v[188:191], v[52:55]
	v_mfma_f32_16x16x32_bf16 v[48:51], v[180:183], v[188:191], v[48:51]
	v_mfma_f32_16x16x32_bf16 v[36:39], v[172:175], v[196:199], v[36:39]
	v_mfma_f32_16x16x32_bf16 v[32:35], v[180:183], v[196:199], v[32:35]
	v_mfma_f32_16x16x32_bf16 v[20:23], v[172:175], v[208:211], v[20:23]
	v_mfma_f32_16x16x32_bf16 v[16:19], v[180:183], v[208:211], v[16:19]
	v_mfma_f32_16x16x32_bf16 v[4:7], v[172:175], v[216:219], v[4:7]
	v_mfma_f32_16x16x32_bf16 v[0:3], v[180:183], v[216:219], v[0:3]
	s_barrier
	s_mov_b32 m0, s39
	s_nop 0
	global_load_lds_dwordx4 v130, s[28:29]
	s_add_i32 s56, 0, 0x18000
	s_add_i32 s57, 0, 0x1c000
	v_add_u32_e32 v164, s56, v149
	v_add_u32_e32 v180, s57, v149
	ds_read_b128 v[144:147], v164
	ds_read_b128 v[156:159], v164 offset:1024
	ds_read_b128 v[160:163], v164 offset:2048
	ds_read_b128 v[164:167], v164 offset:3072
	ds_read_b128 v[168:171], v180
	ds_read_b128 v[172:175], v180 offset:1024
	ds_read_b128 v[176:179], v180 offset:2048
	ds_read_b128 v[180:183], v180 offset:3072
	s_add_u32 s28, s28, 0x40000
	s_addc_u32 s29, s29, 0
	s_mov_b32 m0, s40
	ds_read_b128 v[184:187], v153 offset:32768
	ds_read_b128 v[188:191], v153 offset:33792
	ds_read_b128 v[192:195], v153 offset:34816
	ds_read_b128 v[196:199], v153 offset:35840
	ds_read_b128 v[200:203], v153 offset:36864
	ds_read_b128 v[208:211], v153 offset:37888
	ds_read_b128 v[212:215], v153 offset:38912
	ds_read_b128 v[216:219], v153 offset:39936
	global_load_lds_dwordx4 v134, s[28:29]
	s_mov_b32 m0, s41
	s_nop 0
	global_load_lds_dwordx4 v130, s[28:29]
	s_waitcnt vmcnt(8)
	s_waitcnt lgkmcnt(0)
	s_barrier
	s_waitcnt lgkmcnt(0)
	v_mfma_f32_16x16x32_bf16 v[124:127], v[144:147], v[184:187], v[124:127]
	v_mfma_f32_16x16x32_bf16 v[120:123], v[160:163], v[184:187], v[120:123]
	v_mfma_f32_16x16x32_bf16 v[108:111], v[144:147], v[192:195], v[108:111]
	v_mfma_f32_16x16x32_bf16 v[104:107], v[160:163], v[192:195], v[104:107]
	v_mfma_f32_16x16x32_bf16 v[92:95], v[144:147], v[200:203], v[92:95]
	v_mfma_f32_16x16x32_bf16 v[88:91], v[160:163], v[200:203], v[88:91]
	v_mfma_f32_16x16x32_bf16 v[76:79], v[144:147], v[212:215], v[76:79]
	v_mfma_f32_16x16x32_bf16 v[72:75], v[160:163], v[212:215], v[72:75]
	v_mfma_f32_16x16x32_bf16 v[124:127], v[156:159], v[188:191], v[124:127]
	v_mfma_f32_16x16x32_bf16 v[120:123], v[164:167], v[188:191], v[120:123]
	v_mfma_f32_16x16x32_bf16 v[108:111], v[156:159], v[196:199], v[108:111]
	v_mfma_f32_16x16x32_bf16 v[104:107], v[164:167], v[196:199], v[104:107]
	v_mfma_f32_16x16x32_bf16 v[92:95], v[156:159], v[208:211], v[92:95]
	v_mfma_f32_16x16x32_bf16 v[88:91], v[164:167], v[208:211], v[88:91]
	v_mfma_f32_16x16x32_bf16 v[76:79], v[156:159], v[216:219], v[76:79]
	v_mfma_f32_16x16x32_bf16 v[72:75], v[164:167], v[216:219], v[72:75]
	v_mfma_f32_16x16x32_bf16 v[116:119], v[168:171], v[184:187], v[116:119]
	v_mfma_f32_16x16x32_bf16 v[112:115], v[176:179], v[184:187], v[112:115]
	v_mfma_f32_16x16x32_bf16 v[100:103], v[168:171], v[192:195], v[100:103]
	v_mfma_f32_16x16x32_bf16 v[96:99], v[176:179], v[192:195], v[96:99]
	v_mfma_f32_16x16x32_bf16 v[84:87], v[168:171], v[200:203], v[84:87]
	v_mfma_f32_16x16x32_bf16 v[80:83], v[176:179], v[200:203], v[80:83]
	v_mfma_f32_16x16x32_bf16 v[68:71], v[168:171], v[212:215], v[68:71]
	v_mfma_f32_16x16x32_bf16 v[64:67], v[176:179], v[212:215], v[64:67]
	v_mfma_f32_16x16x32_bf16 v[116:119], v[172:175], v[188:191], v[116:119]
	v_mfma_f32_16x16x32_bf16 v[112:115], v[180:183], v[188:191], v[112:115]
	v_mfma_f32_16x16x32_bf16 v[100:103], v[172:175], v[196:199], v[100:103]
	v_mfma_f32_16x16x32_bf16 v[96:99], v[180:183], v[196:199], v[96:99]
	v_mfma_f32_16x16x32_bf16 v[84:87], v[172:175], v[208:211], v[84:87]
	v_mfma_f32_16x16x32_bf16 v[80:83], v[180:183], v[208:211], v[80:83]
	v_mfma_f32_16x16x32_bf16 v[68:71], v[172:175], v[216:219], v[68:71]
	v_mfma_f32_16x16x32_bf16 v[64:67], v[180:183], v[216:219], v[64:67]
	s_barrier
	s_add_i32 s28, s56, s35
	s_mov_b32 m0, s28
	ds_read_b128 v[184:187], v153 offset:49152
	ds_read_b128 v[188:191], v153 offset:50176
	ds_read_b128 v[192:195], v153 offset:51200
	ds_read_b128 v[196:199], v153 offset:52224
	ds_read_b128 v[200:203], v153 offset:53248
	ds_read_b128 v[208:211], v153 offset:54272
	ds_read_b128 v[212:215], v153 offset:55296
	ds_read_b128 v[216:219], v153 offset:56320
	global_load_lds_dwordx4 v220, s[26:27]
	s_add_i32 m0, s28, 0x2000
	s_add_u32 s26, s26, 0x40080
	s_addc_u32 s27, s27, 0
	s_add_i32 s28, s57, s35
	global_load_lds_dwordx4 v204, s[98:99]
	s_mov_b32 m0, s28
	s_nop 0
	global_load_lds_dwordx4 v132, s[26:27]
	s_add_i32 m0, s28, 0x2000
	s_nop 0
	global_load_lds_dwordx4 v128, s[26:27]
	s_mov_b32 m0, s45
	s_nop 0
	global_load_lds_dwordx4 v221, s[100:101]
	s_cmp_lg_u32 s55, 12
	s_cbranch_scc1 .Lbal_last_21
	s_mov_b32 m0, s46
	s_nop 0
	global_load_lds_dwordx4 v205, s[100:101]
.Lbal_last_21:
	s_waitcnt vmcnt(7)
	s_waitcnt lgkmcnt(0)
	s_barrier
	s_waitcnt lgkmcnt(0)
	v_mfma_f32_16x16x32_bf16 v[60:63], v[144:147], v[184:187], v[60:63]
	v_mfma_f32_16x16x32_bf16 v[56:59], v[160:163], v[184:187], v[56:59]
	v_mfma_f32_16x16x32_bf16 v[44:47], v[144:147], v[192:195], v[44:47]
	v_mfma_f32_16x16x32_bf16 v[40:43], v[160:163], v[192:195], v[40:43]
	v_mfma_f32_16x16x32_bf16 v[28:31], v[144:147], v[200:203], v[28:31]
	v_mfma_f32_16x16x32_bf16 v[24:27], v[160:163], v[200:203], v[24:27]
	v_mfma_f32_16x16x32_bf16 v[12:15], v[144:147], v[212:215], v[12:15]
	v_mfma_f32_16x16x32_bf16 v[8:11], v[160:163], v[212:215], v[8:11]
	v_mfma_f32_16x16x32_bf16 v[60:63], v[156:159], v[188:191], v[60:63]
	v_mfma_f32_16x16x32_bf16 v[56:59], v[164:167], v[188:191], v[56:59]
	v_mfma_f32_16x16x32_bf16 v[44:47], v[156:159], v[196:199], v[44:47]
	v_mfma_f32_16x16x32_bf16 v[40:43], v[164:167], v[196:199], v[40:43]
	v_mfma_f32_16x16x32_bf16 v[28:31], v[156:159], v[208:211], v[28:31]
	v_mfma_f32_16x16x32_bf16 v[24:27], v[164:167], v[208:211], v[24:27]
	v_mfma_f32_16x16x32_bf16 v[12:15], v[156:159], v[216:219], v[12:15]
	v_mfma_f32_16x16x32_bf16 v[8:11], v[164:167], v[216:219], v[8:11]
	v_mfma_f32_16x16x32_bf16 v[52:55], v[168:171], v[184:187], v[52:55]
	v_mfma_f32_16x16x32_bf16 v[48:51], v[176:179], v[184:187], v[48:51]
	v_mfma_f32_16x16x32_bf16 v[36:39], v[168:171], v[192:195], v[36:39]
	v_mfma_f32_16x16x32_bf16 v[32:35], v[176:179], v[192:195], v[32:35]
	v_mfma_f32_16x16x32_bf16 v[20:23], v[168:171], v[200:203], v[20:23]
	v_mfma_f32_16x16x32_bf16 v[16:19], v[176:179], v[200:203], v[16:19]
	v_mfma_f32_16x16x32_bf16 v[4:7], v[168:171], v[212:215], v[4:7]
	v_mfma_f32_16x16x32_bf16 v[0:3], v[176:179], v[212:215], v[0:3]
	v_mfma_f32_16x16x32_bf16 v[52:55], v[172:175], v[188:191], v[52:55]
	v_mfma_f32_16x16x32_bf16 v[48:51], v[180:183], v[188:191], v[48:51]
	v_mfma_f32_16x16x32_bf16 v[36:39], v[172:175], v[196:199], v[36:39]
	v_mfma_f32_16x16x32_bf16 v[32:35], v[180:183], v[196:199], v[32:35]
	v_mfma_f32_16x16x32_bf16 v[20:23], v[172:175], v[208:211], v[20:23]
	v_mfma_f32_16x16x32_bf16 v[16:19], v[180:183], v[208:211], v[16:19]
	v_mfma_f32_16x16x32_bf16 v[4:7], v[172:175], v[216:219], v[4:7]
	v_mfma_f32_16x16x32_bf16 v[0:3], v[180:183], v[216:219], v[0:3]
	s_barrier
	s_add_i32 s55, s55, 2
	s_add_u32 s53, s53, 0x100
	s_addc_u32 s54, s54, 0
	s_add_u32 s24, s24, 0x100
	s_addc_u32 s25, s25, 0
	s_cmp_gt_u32 s55, 13
	s_cbranch_scc0 .LBB0_163
	s_setprio 0
	s_and_b64 vcc, exec, s[14:15]
	s_cbranch_vccz .LBB0_166
	s_barrier

.LBB0_606:
	s_cmp_eq_i32 s58, -2
	s_cbranch_scc1 .Lbal_first_20
	s_mov_b32 m0, s50
	s_nop 0
	global_load_lds_dwordx4 v213, s[36:37]
.Lbal_first_20:
	ds_read_b128 v[140:143], v147
	ds_read_b128 v[150:153], v147 offset:1024
	ds_read_b128 v[154:157], v147 offset:2048
	ds_read_b128 v[158:161], v147 offset:3072
	ds_read_b128 v[162:165], v148
	ds_read_b128 v[166:169], v148 offset:1024
	ds_read_b128 v[170:173], v148 offset:2048
	ds_read_b128 v[174:177], v148 offset:3072
	s_add_u32 s30, s28, 0x100
	s_addc_u32 s31, s29, 0
	s_cmp_eq_u32 s58, 12
	s_cselect_b32 s37, s21, s31
	s_cselect_b32 s36, s27, s30
	s_cselect_b32 s35, s19, s57
	s_cselect_b32 s34, s55, s56
	s_add_i32 m0, s44, 0xc000
	ds_read_b128 v[178:181], v149
	ds_read_b128 v[182:185], v149 offset:1024
	ds_read_b128 v[186:189], v149 offset:2048
	ds_read_b128 v[190:193], v149 offset:3072
	ds_read_b128 v[194:197], v149 offset:4096
	ds_read_b128 v[198:201], v149 offset:5120
	ds_read_b128 v[202:205], v149 offset:6144
	ds_read_b128 v[208:211], v149 offset:7168
	global_load_lds_dwordx4 v134, s[28:29]
	s_add_i32 m0, s44, 0xe000
	s_nop 0
	global_load_lds_dwordx4 v132, s[28:29]
	s_waitcnt vmcnt(8)
	s_waitcnt lgkmcnt(0)
	s_barrier
	s_waitcnt lgkmcnt(0)
	v_mfma_f32_16x16x32_bf16 v[124:127], v[140:143], v[178:181], v[124:127]
	v_mfma_f32_16x16x32_bf16 v[120:123], v[154:157], v[178:181], v[120:123]
	v_mfma_f32_16x16x32_bf16 v[108:111], v[140:143], v[186:189], v[108:111]
	v_mfma_f32_16x16x32_bf16 v[104:107], v[154:157], v[186:189], v[104:107]
	v_mfma_f32_16x16x32_bf16 v[92:95], v[140:143], v[194:197], v[92:95]
	v_mfma_f32_16x16x32_bf16 v[88:91], v[154:157], v[194:197], v[88:91]
	v_mfma_f32_16x16x32_bf16 v[76:79], v[140:143], v[202:205], v[76:79]
	v_mfma_f32_16x16x32_bf16 v[72:75], v[154:157], v[202:205], v[72:75]
	v_mfma_f32_16x16x32_bf16 v[124:127], v[150:153], v[182:185], v[124:127]
	v_mfma_f32_16x16x32_bf16 v[120:123], v[158:161], v[182:185], v[120:123]
	v_mfma_f32_16x16x32_bf16 v[108:111], v[150:153], v[190:193], v[108:111]
	v_mfma_f32_16x16x32_bf16 v[104:107], v[158:161], v[190:193], v[104:107]
	v_mfma_f32_16x16x32_bf16 v[92:95], v[150:153], v[198:201], v[92:95]
	v_mfma_f32_16x16x32_bf16 v[88:91], v[158:161], v[198:201], v[88:91]
	v_mfma_f32_16x16x32_bf16 v[76:79], v[150:153], v[208:211], v[76:79]
	v_mfma_f32_16x16x32_bf16 v[72:75], v[158:161], v[208:211], v[72:75]
	v_mfma_f32_16x16x32_bf16 v[116:119], v[162:165], v[178:181], v[116:119]
	v_mfma_f32_16x16x32_bf16 v[112:115], v[170:173], v[178:181], v[112:115]
	v_mfma_f32_16x16x32_bf16 v[100:103], v[162:165], v[186:189], v[100:103]
	v_mfma_f32_16x16x32_bf16 v[96:99], v[170:173], v[186:189], v[96:99]
	v_mfma_f32_16x16x32_bf16 v[84:87], v[162:165], v[194:197], v[84:87]
	v_mfma_f32_16x16x32_bf16 v[80:83], v[170:173], v[194:197], v[80:83]
	v_mfma_f32_16x16x32_bf16 v[68:71], v[162:165], v[202:205], v[68:71]
	v_mfma_f32_16x16x32_bf16 v[64:67], v[170:173], v[202:205], v[64:67]
	v_mfma_f32_16x16x32_bf16 v[116:119], v[166:169], v[182:185], v[116:119]
	v_mfma_f32_16x16x32_bf16 v[112:115], v[174:177], v[182:185], v[112:115]
	v_mfma_f32_16x16x32_bf16 v[100:103], v[166:169], v[190:193], v[100:103]
	v_mfma_f32_16x16x32_bf16 v[96:99], v[174:177], v[190:193], v[96:99]
	v_mfma_f32_16x16x32_bf16 v[84:87], v[166:169], v[198:201], v[84:87]
	v_mfma_f32_16x16x32_bf16 v[80:83], v[174:177], v[198:201], v[80:83]
	v_mfma_f32_16x16x32_bf16 v[68:71], v[166:169], v[208:211], v[68:71]
	v_mfma_f32_16x16x32_bf16 v[64:67], v[174:177], v[208:211], v[64:67]
	s_barrier
	s_add_i32 s28, s52, s43
	s_mov_b32 m0, s28
	ds_read_b128 v[178:181], v149 offset:16384
	ds_read_b128 v[182:185], v149 offset:17408
	ds_read_b128 v[186:189], v149 offset:18432
	ds_read_b128 v[190:193], v149 offset:19456
	ds_read_b128 v[194:197], v149 offset:20480
	ds_read_b128 v[198:201], v149 offset:21504
	ds_read_b128 v[202:205], v149 offset:22528
	ds_read_b128 v[208:211], v149 offset:23552
	global_load_lds_dwordx4 v128, s[34:35]
	s_add_i32 m0, s28, 0x2000
	s_add_u32 s28, s34, 0x40000
	s_mov_b64 s[98:99], s[34:35]
	s_addc_u32 s29, s35, 0
	s_add_i32 s59, s53, s43
	global_load_lds_dwordx4 v130, s[34:35]
	s_mov_b32 m0, s59
	s_nop 0
	global_load_lds_dwordx4 v128, s[28:29]
	s_add_i32 m0, s59, 0x2000
	s_nop 0
	global_load_lds_dwordx4 v130, s[28:29]
	s_mov_b32 m0, s44
	s_nop 0
	global_load_lds_dwordx4 v128, s[36:37]
	s_waitcnt vmcnt(7)
	s_waitcnt lgkmcnt(0)
	s_barrier
	s_waitcnt lgkmcnt(0)
	v_mfma_f32_16x16x32_bf16 v[60:63], v[140:143], v[178:181], v[60:63]
	v_mfma_f32_16x16x32_bf16 v[56:59], v[154:157], v[178:181], v[56:59]
	v_mfma_f32_16x16x32_bf16 v[44:47], v[140:143], v[186:189], v[44:47]
	v_mfma_f32_16x16x32_bf16 v[40:43], v[154:157], v[186:189], v[40:43]
	v_mfma_f32_16x16x32_bf16 v[28:31], v[140:143], v[194:197], v[28:31]
	v_mfma_f32_16x16x32_bf16 v[24:27], v[154:157], v[194:197], v[24:27]
	v_mfma_f32_16x16x32_bf16 v[12:15], v[140:143], v[202:205], v[12:15]
	v_mfma_f32_16x16x32_bf16 v[8:11], v[154:157], v[202:205], v[8:11]
	v_mfma_f32_16x16x32_bf16 v[60:63], v[150:153], v[182:185], v[60:63]
	v_mfma_f32_16x16x32_bf16 v[56:59], v[158:161], v[182:185], v[56:59]
	v_mfma_f32_16x16x32_bf16 v[44:47], v[150:153], v[190:193], v[44:47]
	v_mfma_f32_16x16x32_bf16 v[40:43], v[158:161], v[190:193], v[40:43]
	v_mfma_f32_16x16x32_bf16 v[28:31], v[150:153], v[198:201], v[28:31]
	v_mfma_f32_16x16x32_bf16 v[24:27], v[158:161], v[198:201], v[24:27]
	v_mfma_f32_16x16x32_bf16 v[12:15], v[150:153], v[208:211], v[12:15]
	v_mfma_f32_16x16x32_bf16 v[8:11], v[158:161], v[208:211], v[8:11]
	v_mfma_f32_16x16x32_bf16 v[52:55], v[162:165], v[178:181], v[52:55]
	v_mfma_f32_16x16x32_bf16 v[48:51], v[170:173], v[178:181], v[48:51]
	v_mfma_f32_16x16x32_bf16 v[36:39], v[162:165], v[186:189], v[36:39]
	v_mfma_f32_16x16x32_bf16 v[32:35], v[170:173], v[186:189], v[32:35]
	v_mfma_f32_16x16x32_bf16 v[20:23], v[162:165], v[194:197], v[20:23]
	v_mfma_f32_16x16x32_bf16 v[16:19], v[170:173], v[194:197], v[16:19]
	v_mfma_f32_16x16x32_bf16 v[4:7], v[162:165], v[202:205], v[4:7]
	v_mfma_f32_16x16x32_bf16 v[0:3], v[170:173], v[202:205], v[0:3]
	v_mfma_f32_16x16x32_bf16 v[52:55], v[166:169], v[182:185], v[52:55]
	v_mfma_f32_16x16x32_bf16 v[48:51], v[174:177], v[182:185], v[48:51]
	v_mfma_f32_16x16x32_bf16 v[36:39], v[166:169], v[190:193], v[36:39]
	v_mfma_f32_16x16x32_bf16 v[32:35], v[174:177], v[190:193], v[32:35]
	v_mfma_f32_16x16x32_bf16 v[20:23], v[166:169], v[198:201], v[20:23]
	v_mfma_f32_16x16x32_bf16 v[16:19], v[174:177], v[198:201], v[16:19]
	v_mfma_f32_16x16x32_bf16 v[4:7], v[166:169], v[208:211], v[4:7]
	v_mfma_f32_16x16x32_bf16 v[0:3], v[174:177], v[208:211], v[0:3]
	s_barrier
	s_mov_b32 m0, s45
	s_nop 0
	global_load_lds_dwordx4 v130, s[36:37]
	s_add_i32 s59, 0, 0x18000
	s_add_i32 s60, 0, 0x1c000
	v_add_u32_e32 v158, s59, v145
	v_add_u32_e32 v174, s60, v145
	ds_read_b128 v[140:143], v158
	ds_read_b128 v[150:153], v158 offset:1024
	ds_read_b128 v[154:157], v158 offset:2048
	ds_read_b128 v[158:161], v158 offset:3072
	ds_read_b128 v[162:165], v174
	ds_read_b128 v[166:169], v174 offset:1024
	ds_read_b128 v[170:173], v174 offset:2048
	ds_read_b128 v[174:177], v174 offset:3072
	s_add_u32 s28, s36, 0x40000
	s_addc_u32 s29, s37, 0
	s_mov_b32 m0, s46
	ds_read_b128 v[178:181], v149 offset:32768
	ds_read_b128 v[182:185], v149 offset:33792
	ds_read_b128 v[186:189], v149 offset:34816
	ds_read_b128 v[190:193], v149 offset:35840
	ds_read_b128 v[194:197], v149 offset:36864
	ds_read_b128 v[198:201], v149 offset:37888
	ds_read_b128 v[202:205], v149 offset:38912
	ds_read_b128 v[208:211], v149 offset:39936
	global_load_lds_dwordx4 v128, s[28:29]
	s_mov_b32 m0, s47
	s_nop 0
	global_load_lds_dwordx4 v130, s[28:29]
	s_waitcnt vmcnt(8)
	s_waitcnt lgkmcnt(0)
	s_barrier
	s_waitcnt lgkmcnt(0)
	v_mfma_f32_16x16x32_bf16 v[124:127], v[140:143], v[178:181], v[124:127]
	v_mfma_f32_16x16x32_bf16 v[120:123], v[154:157], v[178:181], v[120:123]
	v_mfma_f32_16x16x32_bf16 v[108:111], v[140:143], v[186:189], v[108:111]
	v_mfma_f32_16x16x32_bf16 v[104:107], v[154:157], v[186:189], v[104:107]
	v_mfma_f32_16x16x32_bf16 v[92:95], v[140:143], v[194:197], v[92:95]
	v_mfma_f32_16x16x32_bf16 v[88:91], v[154:157], v[194:197], v[88:91]
	v_mfma_f32_16x16x32_bf16 v[76:79], v[140:143], v[202:205], v[76:79]
	v_mfma_f32_16x16x32_bf16 v[72:75], v[154:157], v[202:205], v[72:75]
	v_mfma_f32_16x16x32_bf16 v[124:127], v[150:153], v[182:185], v[124:127]
	v_mfma_f32_16x16x32_bf16 v[120:123], v[158:161], v[182:185], v[120:123]
	v_mfma_f32_16x16x32_bf16 v[108:111], v[150:153], v[190:193], v[108:111]
	v_mfma_f32_16x16x32_bf16 v[104:107], v[158:161], v[190:193], v[104:107]
	v_mfma_f32_16x16x32_bf16 v[92:95], v[150:153], v[198:201], v[92:95]
	v_mfma_f32_16x16x32_bf16 v[88:91], v[158:161], v[198:201], v[88:91]
	v_mfma_f32_16x16x32_bf16 v[76:79], v[150:153], v[208:211], v[76:79]
	v_mfma_f32_16x16x32_bf16 v[72:75], v[158:161], v[208:211], v[72:75]
	v_mfma_f32_16x16x32_bf16 v[116:119], v[162:165], v[178:181], v[116:119]
	v_mfma_f32_16x16x32_bf16 v[112:115], v[170:173], v[178:181], v[112:115]
	v_mfma_f32_16x16x32_bf16 v[100:103], v[162:165], v[186:189], v[100:103]
	v_mfma_f32_16x16x32_bf16 v[96:99], v[170:173], v[186:189], v[96:99]
	v_mfma_f32_16x16x32_bf16 v[84:87], v[162:165], v[194:197], v[84:87]
	v_mfma_f32_16x16x32_bf16 v[80:83], v[170:173], v[194:197], v[80:83]
	v_mfma_f32_16x16x32_bf16 v[68:71], v[162:165], v[202:205], v[68:71]
	v_mfma_f32_16x16x32_bf16 v[64:67], v[170:173], v[202:205], v[64:67]
	v_mfma_f32_16x16x32_bf16 v[116:119], v[166:169], v[182:185], v[116:119]
	v_mfma_f32_16x16x32_bf16 v[112:115], v[174:177], v[182:185], v[112:115]
	v_mfma_f32_16x16x32_bf16 v[100:103], v[166:169], v[190:193], v[100:103]
	v_mfma_f32_16x16x32_bf16 v[96:99], v[174:177], v[190:193], v[96:99]
	v_mfma_f32_16x16x32_bf16 v[84:87], v[166:169], v[198:201], v[84:87]
	v_mfma_f32_16x16x32_bf16 v[80:83], v[174:177], v[198:201], v[80:83]
	v_mfma_f32_16x16x32_bf16 v[68:71], v[166:169], v[208:211], v[68:71]
	v_mfma_f32_16x16x32_bf16 v[64:67], v[174:177], v[208:211], v[64:67]
	s_barrier
	s_add_i32 s28, s59, s43
	s_mov_b32 m0, s28
	ds_read_b128 v[178:181], v149 offset:49152
	ds_read_b128 v[182:185], v149 offset:50176
	ds_read_b128 v[186:189], v149 offset:51200
	ds_read_b128 v[190:193], v149 offset:52224
	ds_read_b128 v[194:197], v149 offset:53248
	ds_read_b128 v[198:201], v149 offset:54272
	ds_read_b128 v[202:205], v149 offset:55296
	ds_read_b128 v[208:211], v149 offset:56320
	global_load_lds_dwordx4 v212, s[34:35]
	s_add_i32 m0, s28, 0x2000
	s_add_u32 s28, s34, 0x40080
	s_addc_u32 s29, s35, 0
	s_add_i32 s34, s60, s43
	global_load_lds_dwordx4 v213, s[98:99]
	s_mov_b32 m0, s34
	s_nop 0
	global_load_lds_dwordx4 v128, s[28:29]
	s_add_i32 m0, s34, 0x2000
	s_nop 0
	global_load_lds_dwordx4 v130, s[28:29]
	s_mov_b32 m0, s49
	s_nop 0
	global_load_lds_dwordx4 v212, s[36:37]
	s_cmp_lg_u32 s58, 12
	s_cbranch_scc1 .Lbal_last_20
	s_mov_b32 m0, s50
	s_nop 0
	global_load_lds_dwordx4 v213, s[36:37]
.Lbal_last_20:
	s_waitcnt vmcnt(7)
	s_waitcnt lgkmcnt(0)
	s_barrier
	s_waitcnt lgkmcnt(0)
	v_mfma_f32_16x16x32_bf16 v[60:63], v[140:143], v[178:181], v[60:63]
	v_mfma_f32_16x16x32_bf16 v[56:59], v[154:157], v[178:181], v[56:59]
	v_mfma_f32_16x16x32_bf16 v[44:47], v[140:143], v[186:189], v[44:47]
	v_mfma_f32_16x16x32_bf16 v[40:43], v[154:157], v[186:189], v[40:43]
	v_mfma_f32_16x16x32_bf16 v[28:31], v[140:143], v[194:197], v[28:31]
	v_mfma_f32_16x16x32_bf16 v[24:27], v[154:157], v[194:197], v[24:27]
	v_mfma_f32_16x16x32_bf16 v[12:15], v[140:143], v[202:205], v[12:15]
	v_mfma_f32_16x16x32_bf16 v[8:11], v[154:157], v[202:205], v[8:11]
	v_mfma_f32_16x16x32_bf16 v[60:63], v[150:153], v[182:185], v[60:63]
	v_mfma_f32_16x16x32_bf16 v[56:59], v[158:161], v[182:185], v[56:59]
	v_mfma_f32_16x16x32_bf16 v[44:47], v[150:153], v[190:193], v[44:47]
	v_mfma_f32_16x16x32_bf16 v[40:43], v[158:161], v[190:193], v[40:43]
	v_mfma_f32_16x16x32_bf16 v[28:31], v[150:153], v[198:201], v[28:31]
	v_mfma_f32_16x16x32_bf16 v[24:27], v[158:161], v[198:201], v[24:27]
	v_mfma_f32_16x16x32_bf16 v[12:15], v[150:153], v[208:211], v[12:15]
	v_mfma_f32_16x16x32_bf16 v[8:11], v[158:161], v[208:211], v[8:11]
	v_mfma_f32_16x16x32_bf16 v[52:55], v[162:165], v[178:181], v[52:55]
	v_mfma_f32_16x16x32_bf16 v[48:51], v[170:173], v[178:181], v[48:51]
	v_mfma_f32_16x16x32_bf16 v[36:39], v[162:165], v[186:189], v[36:39]
	v_mfma_f32_16x16x32_bf16 v[32:35], v[170:173], v[186:189], v[32:35]
	v_mfma_f32_16x16x32_bf16 v[20:23], v[162:165], v[194:197], v[20:23]
	v_mfma_f32_16x16x32_bf16 v[16:19], v[170:173], v[194:197], v[16:19]
	v_mfma_f32_16x16x32_bf16 v[4:7], v[162:165], v[202:205], v[4:7]
	v_mfma_f32_16x16x32_bf16 v[0:3], v[170:173], v[202:205], v[0:3]
	v_mfma_f32_16x16x32_bf16 v[52:55], v[166:169], v[182:185], v[52:55]
	v_mfma_f32_16x16x32_bf16 v[48:51], v[174:177], v[182:185], v[48:51]
	v_mfma_f32_16x16x32_bf16 v[36:39], v[166:169], v[190:193], v[36:39]
	v_mfma_f32_16x16x32_bf16 v[32:35], v[174:177], v[190:193], v[32:35]
	v_mfma_f32_16x16x32_bf16 v[20:23], v[166:169], v[198:201], v[20:23]
	v_mfma_f32_16x16x32_bf16 v[16:19], v[174:177], v[198:201], v[16:19]
	v_mfma_f32_16x16x32_bf16 v[4:7], v[166:169], v[208:211], v[4:7]
	v_mfma_f32_16x16x32_bf16 v[0:3], v[174:177], v[208:211], v[0:3]
	s_barrier
	s_add_i32 s58, s58, 2
	s_add_u32 s56, s56, 0x100
	s_addc_u32 s57, s57, 0
	s_cmp_gt_u32 s58, 13
	s_mov_b64 s[28:29], s[30:31]
	s_cbranch_scc0 .LBB0_606
	s_setprio 0
	s_and_b64 vcc, exec, s[16:17]
	s_cbranch_vccz .LBB0_609
	s_barrier

.LBB0_699:
	s_cmp_eq_i32 s53, -2
	s_cbranch_scc1 .Lbal_first_19
	s_mov_b32 m0, s45
	s_nop 0
	global_load_lds_dwordx4 v220, s[100:101]
.Lbal_first_19:
	ds_read_b128 v[144:147], v151
	ds_read_b128 v[156:159], v151 offset:1024
	ds_read_b128 v[160:163], v151 offset:2048
	ds_read_b128 v[164:167], v151 offset:3072
	ds_read_b128 v[168:171], v152
	ds_read_b128 v[172:175], v152 offset:1024
	ds_read_b128 v[176:179], v152 offset:2048
	ds_read_b128 v[180:183], v152 offset:3072
	s_add_u32 s28, s26, 0xfffc0080
	s_addc_u32 s29, s27, -1
	s_cmp_eq_u32 s53, 12
	s_cselect_b32 s31, s21, s29
	s_cselect_b32 s30, s49, s28
	s_cselect_b32 s29, s19, s52
	s_cselect_b32 s28, s50, s51
	s_add_i32 m0, s39, 0xc000
	ds_read_b128 v[184:187], v153
	ds_read_b128 v[188:191], v153 offset:1024
	ds_read_b128 v[192:195], v153 offset:2048
	ds_read_b128 v[196:199], v153 offset:3072
	ds_read_b128 v[200:203], v153 offset:4096
	ds_read_b128 v[208:211], v153 offset:5120
	ds_read_b128 v[212:215], v153 offset:6144
	ds_read_b128 v[216:219], v153 offset:7168
	global_load_lds_dwordx4 v138, s[26:27]
	s_add_i32 m0, s39, 0xe000
	s_nop 0
	global_load_lds_dwordx4 v136, s[26:27]
	s_waitcnt vmcnt(8)
	s_waitcnt lgkmcnt(0)
	s_barrier
	s_waitcnt lgkmcnt(0)
	v_mfma_f32_16x16x32_bf16 v[124:127], v[144:147], v[184:187], v[124:127]
	v_mfma_f32_16x16x32_bf16 v[120:123], v[160:163], v[184:187], v[120:123]
	v_mfma_f32_16x16x32_bf16 v[108:111], v[144:147], v[192:195], v[108:111]
	v_mfma_f32_16x16x32_bf16 v[104:107], v[160:163], v[192:195], v[104:107]
	v_mfma_f32_16x16x32_bf16 v[92:95], v[144:147], v[200:203], v[92:95]
	v_mfma_f32_16x16x32_bf16 v[88:91], v[160:163], v[200:203], v[88:91]
	v_mfma_f32_16x16x32_bf16 v[76:79], v[144:147], v[212:215], v[76:79]
	v_mfma_f32_16x16x32_bf16 v[72:75], v[160:163], v[212:215], v[72:75]
	v_mfma_f32_16x16x32_bf16 v[124:127], v[156:159], v[188:191], v[124:127]
	v_mfma_f32_16x16x32_bf16 v[120:123], v[164:167], v[188:191], v[120:123]
	v_mfma_f32_16x16x32_bf16 v[108:111], v[156:159], v[196:199], v[108:111]
	v_mfma_f32_16x16x32_bf16 v[104:107], v[164:167], v[196:199], v[104:107]
	v_mfma_f32_16x16x32_bf16 v[92:95], v[156:159], v[208:211], v[92:95]
	v_mfma_f32_16x16x32_bf16 v[88:91], v[164:167], v[208:211], v[88:91]
	v_mfma_f32_16x16x32_bf16 v[76:79], v[156:159], v[216:219], v[76:79]
	v_mfma_f32_16x16x32_bf16 v[72:75], v[164:167], v[216:219], v[72:75]
	v_mfma_f32_16x16x32_bf16 v[116:119], v[168:171], v[184:187], v[116:119]
	v_mfma_f32_16x16x32_bf16 v[112:115], v[176:179], v[184:187], v[112:115]
	v_mfma_f32_16x16x32_bf16 v[100:103], v[168:171], v[192:195], v[100:103]
	v_mfma_f32_16x16x32_bf16 v[96:99], v[176:179], v[192:195], v[96:99]
	v_mfma_f32_16x16x32_bf16 v[84:87], v[168:171], v[200:203], v[84:87]
	v_mfma_f32_16x16x32_bf16 v[80:83], v[176:179], v[200:203], v[80:83]
	v_mfma_f32_16x16x32_bf16 v[68:71], v[168:171], v[212:215], v[68:71]
	v_mfma_f32_16x16x32_bf16 v[64:67], v[176:179], v[212:215], v[64:67]
	v_mfma_f32_16x16x32_bf16 v[116:119], v[172:175], v[188:191], v[116:119]
	v_mfma_f32_16x16x32_bf16 v[112:115], v[180:183], v[188:191], v[112:115]
	v_mfma_f32_16x16x32_bf16 v[100:103], v[172:175], v[196:199], v[100:103]
	v_mfma_f32_16x16x32_bf16 v[96:99], v[180:183], v[196:199], v[96:99]
	v_mfma_f32_16x16x32_bf16 v[84:87], v[172:175], v[208:211], v[84:87]
	v_mfma_f32_16x16x32_bf16 v[80:83], v[180:183], v[208:211], v[80:83]
	v_mfma_f32_16x16x32_bf16 v[68:71], v[172:175], v[216:219], v[68:71]
	v_mfma_f32_16x16x32_bf16 v[64:67], v[180:183], v[216:219], v[64:67]
	s_barrier
	s_add_i32 s54, s46, s38
	s_mov_b32 m0, s54
	ds_read_b128 v[184:187], v153 offset:16384
	ds_read_b128 v[188:191], v153 offset:17408
	ds_read_b128 v[192:195], v153 offset:18432
	ds_read_b128 v[196:199], v153 offset:19456
	ds_read_b128 v[200:203], v153 offset:20480
	ds_read_b128 v[208:211], v153 offset:21504
	ds_read_b128 v[212:215], v153 offset:22528
	ds_read_b128 v[216:219], v153 offset:23552
	global_load_lds_dwordx4 v130, s[28:29]
	s_add_i32 m0, s54, 0x2000
	s_add_u32 s54, s28, 0x40000
	s_mov_b64 s[98:99], s[28:29]
	s_addc_u32 s55, s29, 0
	s_add_i32 s56, s47, s38
	global_load_lds_dwordx4 v134, s[28:29]
	s_mov_b32 m0, s56
	s_mov_b64 s[100:101], s[30:31]
	global_load_lds_dwordx4 v130, s[54:55]
	s_add_i32 m0, s56, 0x2000
	s_nop 0
	global_load_lds_dwordx4 v134, s[54:55]
	s_mov_b32 m0, s39
	s_nop 0
	global_load_lds_dwordx4 v128, s[30:31]
	s_waitcnt vmcnt(7)
	s_waitcnt lgkmcnt(0)
	s_barrier
	s_waitcnt lgkmcnt(0)
	v_mfma_f32_16x16x32_bf16 v[60:63], v[144:147], v[184:187], v[60:63]
	v_mfma_f32_16x16x32_bf16 v[56:59], v[160:163], v[184:187], v[56:59]
	v_mfma_f32_16x16x32_bf16 v[44:47], v[144:147], v[192:195], v[44:47]
	v_mfma_f32_16x16x32_bf16 v[40:43], v[160:163], v[192:195], v[40:43]
	v_mfma_f32_16x16x32_bf16 v[28:31], v[144:147], v[200:203], v[28:31]
	v_mfma_f32_16x16x32_bf16 v[24:27], v[160:163], v[200:203], v[24:27]
	v_mfma_f32_16x16x32_bf16 v[12:15], v[144:147], v[212:215], v[12:15]
	v_mfma_f32_16x16x32_bf16 v[8:11], v[160:163], v[212:215], v[8:11]
	v_mfma_f32_16x16x32_bf16 v[60:63], v[156:159], v[188:191], v[60:63]
	v_mfma_f32_16x16x32_bf16 v[56:59], v[164:167], v[188:191], v[56:59]
	v_mfma_f32_16x16x32_bf16 v[44:47], v[156:159], v[196:199], v[44:47]
	v_mfma_f32_16x16x32_bf16 v[40:43], v[164:167], v[196:199], v[40:43]
	v_mfma_f32_16x16x32_bf16 v[28:31], v[156:159], v[208:211], v[28:31]
	v_mfma_f32_16x16x32_bf16 v[24:27], v[164:167], v[208:211], v[24:27]
	v_mfma_f32_16x16x32_bf16 v[12:15], v[156:159], v[216:219], v[12:15]
	v_mfma_f32_16x16x32_bf16 v[8:11], v[164:167], v[216:219], v[8:11]
	v_mfma_f32_16x16x32_bf16 v[52:55], v[168:171], v[184:187], v[52:55]
	v_mfma_f32_16x16x32_bf16 v[48:51], v[176:179], v[184:187], v[48:51]
	v_mfma_f32_16x16x32_bf16 v[36:39], v[168:171], v[192:195], v[36:39]
	v_mfma_f32_16x16x32_bf16 v[32:35], v[176:179], v[192:195], v[32:35]
	v_mfma_f32_16x16x32_bf16 v[20:23], v[168:171], v[200:203], v[20:23]
	v_mfma_f32_16x16x32_bf16 v[16:19], v[176:179], v[200:203], v[16:19]
	v_mfma_f32_16x16x32_bf16 v[4:7], v[168:171], v[212:215], v[4:7]
	v_mfma_f32_16x16x32_bf16 v[0:3], v[176:179], v[212:215], v[0:3]
	v_mfma_f32_16x16x32_bf16 v[52:55], v[172:175], v[188:191], v[52:55]
	v_mfma_f32_16x16x32_bf16 v[48:51], v[180:183], v[188:191], v[48:51]
	v_mfma_f32_16x16x32_bf16 v[36:39], v[172:175], v[196:199], v[36:39]
	v_mfma_f32_16x16x32_bf16 v[32:35], v[180:183], v[196:199], v[32:35]
	v_mfma_f32_16x16x32_bf16 v[20:23], v[172:175], v[208:211], v[20:23]
	v_mfma_f32_16x16x32_bf16 v[16:19], v[180:183], v[208:211], v[16:19]
	v_mfma_f32_16x16x32_bf16 v[4:7], v[172:175], v[216:219], v[4:7]
	v_mfma_f32_16x16x32_bf16 v[0:3], v[180:183], v[216:219], v[0:3]
	s_barrier
	s_mov_b32 m0, s40
	s_nop 0
	global_load_lds_dwordx4 v132, s[30:31]
	s_add_i32 s54, 0, 0x18000
	v_add_u32_e32 v155, s54, v149
	s_add_i32 s55, 0, 0x1c000
	ds_read_b128 v[144:147], v155
	ds_read_b128 v[156:159], v155 offset:1024
	ds_read_b128 v[160:163], v155 offset:2048
	ds_read_b128 v[164:167], v155 offset:3072
	v_add_u32_e32 v155, s55, v149
	ds_read_b128 v[168:171], v155
	ds_read_b128 v[172:175], v155 offset:1024
	ds_read_b128 v[176:179], v155 offset:2048
	ds_read_b128 v[180:183], v155 offset:3072
	s_add_u32 s30, s30, 0x40000
	s_addc_u32 s31, s31, 0
	s_mov_b32 m0, s41
	ds_read_b128 v[184:187], v153 offset:32768
	ds_read_b128 v[188:191], v153 offset:33792
	ds_read_b128 v[192:195], v153 offset:34816
	ds_read_b128 v[196:199], v153 offset:35840
	ds_read_b128 v[200:203], v153 offset:36864
	ds_read_b128 v[208:211], v153 offset:37888
	ds_read_b128 v[212:215], v153 offset:38912
	ds_read_b128 v[216:219], v153 offset:39936
	global_load_lds_dwordx4 v128, s[30:31]
	s_mov_b32 m0, s42
	s_nop 0
	global_load_lds_dwordx4 v132, s[30:31]
	s_waitcnt vmcnt(8)
	s_waitcnt lgkmcnt(0)
	s_barrier
	s_waitcnt lgkmcnt(0)
	v_mfma_f32_16x16x32_bf16 v[124:127], v[144:147], v[184:187], v[124:127]
	v_mfma_f32_16x16x32_bf16 v[120:123], v[160:163], v[184:187], v[120:123]
	v_mfma_f32_16x16x32_bf16 v[108:111], v[144:147], v[192:195], v[108:111]
	v_mfma_f32_16x16x32_bf16 v[104:107], v[160:163], v[192:195], v[104:107]
	v_mfma_f32_16x16x32_bf16 v[92:95], v[144:147], v[200:203], v[92:95]
	v_mfma_f32_16x16x32_bf16 v[88:91], v[160:163], v[200:203], v[88:91]
	v_mfma_f32_16x16x32_bf16 v[76:79], v[144:147], v[212:215], v[76:79]
	v_mfma_f32_16x16x32_bf16 v[72:75], v[160:163], v[212:215], v[72:75]
	v_mfma_f32_16x16x32_bf16 v[124:127], v[156:159], v[188:191], v[124:127]
	v_mfma_f32_16x16x32_bf16 v[120:123], v[164:167], v[188:191], v[120:123]
	v_mfma_f32_16x16x32_bf16 v[108:111], v[156:159], v[196:199], v[108:111]
	v_mfma_f32_16x16x32_bf16 v[104:107], v[164:167], v[196:199], v[104:107]
	v_mfma_f32_16x16x32_bf16 v[92:95], v[156:159], v[208:211], v[92:95]
	v_mfma_f32_16x16x32_bf16 v[88:91], v[164:167], v[208:211], v[88:91]
	v_mfma_f32_16x16x32_bf16 v[76:79], v[156:159], v[216:219], v[76:79]
	v_mfma_f32_16x16x32_bf16 v[72:75], v[164:167], v[216:219], v[72:75]
	v_mfma_f32_16x16x32_bf16 v[116:119], v[168:171], v[184:187], v[116:119]
	v_mfma_f32_16x16x32_bf16 v[112:115], v[176:179], v[184:187], v[112:115]
	v_mfma_f32_16x16x32_bf16 v[100:103], v[168:171], v[192:195], v[100:103]
	v_mfma_f32_16x16x32_bf16 v[96:99], v[176:179], v[192:195], v[96:99]
	v_mfma_f32_16x16x32_bf16 v[84:87], v[168:171], v[200:203], v[84:87]
	v_mfma_f32_16x16x32_bf16 v[80:83], v[176:179], v[200:203], v[80:83]
	v_mfma_f32_16x16x32_bf16 v[68:71], v[168:171], v[212:215], v[68:71]
	v_mfma_f32_16x16x32_bf16 v[64:67], v[176:179], v[212:215], v[64:67]
	v_mfma_f32_16x16x32_bf16 v[116:119], v[172:175], v[188:191], v[116:119]
	v_mfma_f32_16x16x32_bf16 v[112:115], v[180:183], v[188:191], v[112:115]
	v_mfma_f32_16x16x32_bf16 v[100:103], v[172:175], v[196:199], v[100:103]
	v_mfma_f32_16x16x32_bf16 v[96:99], v[180:183], v[196:199], v[96:99]
	v_mfma_f32_16x16x32_bf16 v[84:87], v[172:175], v[208:211], v[84:87]
	v_mfma_f32_16x16x32_bf16 v[80:83], v[180:183], v[208:211], v[80:83]
	v_mfma_f32_16x16x32_bf16 v[68:71], v[172:175], v[216:219], v[68:71]
	v_mfma_f32_16x16x32_bf16 v[64:67], v[180:183], v[216:219], v[64:67]
	s_barrier
	s_add_i32 s30, s54, s38
	s_mov_b32 m0, s30
	ds_read_b128 v[184:187], v153 offset:49152
	ds_read_b128 v[188:191], v153 offset:50176
	ds_read_b128 v[192:195], v153 offset:51200
	ds_read_b128 v[196:199], v153 offset:52224
	ds_read_b128 v[200:203], v153 offset:53248
	ds_read_b128 v[208:211], v153 offset:54272
	ds_read_b128 v[212:215], v153 offset:55296
	ds_read_b128 v[216:219], v153 offset:56320
	global_load_lds_dwordx4 v205, s[28:29]
	s_add_i32 m0, s30, 0x2000
	s_add_u32 s28, s28, 0x40080
	s_addc_u32 s29, s29, 0
	s_add_i32 s30, s55, s38
	global_load_lds_dwordx4 v221, s[98:99]
	s_mov_b32 m0, s30
	s_nop 0
	global_load_lds_dwordx4 v130, s[28:29]
	s_add_i32 m0, s30, 0x2000
	s_nop 0
	global_load_lds_dwordx4 v134, s[28:29]
	s_mov_b32 m0, s44
	s_nop 0
	global_load_lds_dwordx4 v204, s[100:101]
	s_cmp_lg_u32 s53, 12
	s_cbranch_scc1 .Lbal_last_19
	s_mov_b32 m0, s45
	s_nop 0
	global_load_lds_dwordx4 v220, s[100:101]
.Lbal_last_19:
	s_waitcnt vmcnt(7)
	s_waitcnt lgkmcnt(0)
	s_barrier
	s_waitcnt lgkmcnt(0)
	v_mfma_f32_16x16x32_bf16 v[60:63], v[144:147], v[184:187], v[60:63]
	v_mfma_f32_16x16x32_bf16 v[56:59], v[160:163], v[184:187], v[56:59]
	v_mfma_f32_16x16x32_bf16 v[44:47], v[144:147], v[192:195], v[44:47]
	v_mfma_f32_16x16x32_bf16 v[40:43], v[160:163], v[192:195], v[40:43]
	v_mfma_f32_16x16x32_bf16 v[28:31], v[144:147], v[200:203], v[28:31]
	v_mfma_f32_16x16x32_bf16 v[24:27], v[160:163], v[200:203], v[24:27]
	v_mfma_f32_16x16x32_bf16 v[12:15], v[144:147], v[212:215], v[12:15]
	v_mfma_f32_16x16x32_bf16 v[8:11], v[160:163], v[212:215], v[8:11]
	v_mfma_f32_16x16x32_bf16 v[60:63], v[156:159], v[188:191], v[60:63]
	v_mfma_f32_16x16x32_bf16 v[56:59], v[164:167], v[188:191], v[56:59]
	v_mfma_f32_16x16x32_bf16 v[44:47], v[156:159], v[196:199], v[44:47]
	v_mfma_f32_16x16x32_bf16 v[40:43], v[164:167], v[196:199], v[40:43]
	v_mfma_f32_16x16x32_bf16 v[28:31], v[156:159], v[208:211], v[28:31]
	v_mfma_f32_16x16x32_bf16 v[24:27], v[164:167], v[208:211], v[24:27]
	v_mfma_f32_16x16x32_bf16 v[12:15], v[156:159], v[216:219], v[12:15]
	v_mfma_f32_16x16x32_bf16 v[8:11], v[164:167], v[216:219], v[8:11]
	v_mfma_f32_16x16x32_bf16 v[52:55], v[168:171], v[184:187], v[52:55]
	v_mfma_f32_16x16x32_bf16 v[48:51], v[176:179], v[184:187], v[48:51]
	v_mfma_f32_16x16x32_bf16 v[36:39], v[168:171], v[192:195], v[36:39]
	v_mfma_f32_16x16x32_bf16 v[32:35], v[176:179], v[192:195], v[32:35]
	v_mfma_f32_16x16x32_bf16 v[20:23], v[168:171], v[200:203], v[20:23]
	v_mfma_f32_16x16x32_bf16 v[16:19], v[176:179], v[200:203], v[16:19]
	v_mfma_f32_16x16x32_bf16 v[4:7], v[168:171], v[212:215], v[4:7]
	v_mfma_f32_16x16x32_bf16 v[0:3], v[176:179], v[212:215], v[0:3]
	v_mfma_f32_16x16x32_bf16 v[52:55], v[172:175], v[188:191], v[52:55]
	v_mfma_f32_16x16x32_bf16 v[48:51], v[180:183], v[188:191], v[48:51]
	v_mfma_f32_16x16x32_bf16 v[36:39], v[172:175], v[196:199], v[36:39]
	v_mfma_f32_16x16x32_bf16 v[32:35], v[180:183], v[196:199], v[32:35]
	v_mfma_f32_16x16x32_bf16 v[20:23], v[172:175], v[208:211], v[20:23]
	v_mfma_f32_16x16x32_bf16 v[16:19], v[180:183], v[208:211], v[16:19]
	v_mfma_f32_16x16x32_bf16 v[4:7], v[172:175], v[216:219], v[4:7]
	v_mfma_f32_16x16x32_bf16 v[0:3], v[180:183], v[216:219], v[0:3]
	s_barrier
	s_add_i32 s53, s53, 2
	s_add_u32 s51, s51, 0x100
	s_addc_u32 s52, s52, 0
	s_add_u32 s26, s26, 0x100
	s_addc_u32 s27, s27, 0
	s_cmp_gt_u32 s53, 13
	s_cbranch_scc0 .LBB0_699
	s_setprio 0
	s_and_b64 vcc, exec, s[16:17]
	s_cbranch_vccz .LBB0_702
	s_barrier

.Lbal_first_18:
	ds_read_b128 v[140:143], v147
	ds_read_b128 v[150:153], v147 offset:1024
	ds_read_b128 v[154:157], v147 offset:2048
	ds_read_b128 v[158:161], v147 offset:3072
	ds_read_b128 v[162:165], v148
	ds_read_b128 v[166:169], v148 offset:1024
	ds_read_b128 v[170:173], v148 offset:2048
	ds_read_b128 v[174:177], v148 offset:3072
	s_add_u32 s30, s28, 0x100
	s_addc_u32 s31, s29, 0
	s_cmp_eq_u32 s58, 60
	s_cselect_b32 s37, s21, s31
	s_cselect_b32 s36, s27, s30
	s_cselect_b32 s35, s19, s57
	s_cselect_b32 s34, s55, s56
	s_add_i32 m0, s44, 0xc000
	ds_read_b128 v[178:181], v149
	ds_read_b128 v[182:185], v149 offset:1024
	ds_read_b128 v[186:189], v149 offset:2048
	ds_read_b128 v[190:193], v149 offset:3072
	ds_read_b128 v[194:197], v149 offset:4096
	ds_read_b128 v[198:201], v149 offset:5120
	ds_read_b128 v[202:205], v149 offset:6144
	ds_read_b128 v[208:211], v149 offset:7168
	global_load_lds_dwordx4 v134, s[28:29]
	s_add_i32 m0, s44, 0xe000
	s_nop 0
	global_load_lds_dwordx4 v132, s[28:29]
	s_waitcnt vmcnt(8)
	s_waitcnt lgkmcnt(0)
	s_barrier
	s_waitcnt lgkmcnt(0)
	v_mfma_f32_16x16x32_bf16 v[124:127], v[140:143], v[178:181], v[124:127]
	v_mfma_f32_16x16x32_bf16 v[120:123], v[154:157], v[178:181], v[120:123]
	v_mfma_f32_16x16x32_bf16 v[108:111], v[140:143], v[186:189], v[108:111]
	v_mfma_f32_16x16x32_bf16 v[104:107], v[154:157], v[186:189], v[104:107]
	v_mfma_f32_16x16x32_bf16 v[92:95], v[140:143], v[194:197], v[92:95]
	v_mfma_f32_16x16x32_bf16 v[88:91], v[154:157], v[194:197], v[88:91]
	v_mfma_f32_16x16x32_bf16 v[76:79], v[140:143], v[202:205], v[76:79]
	v_mfma_f32_16x16x32_bf16 v[72:75], v[154:157], v[202:205], v[72:75]
	v_mfma_f32_16x16x32_bf16 v[124:127], v[150:153], v[182:185], v[124:127]
	v_mfma_f32_16x16x32_bf16 v[120:123], v[158:161], v[182:185], v[120:123]
	v_mfma_f32_16x16x32_bf16 v[108:111], v[150:153], v[190:193], v[108:111]
	v_mfma_f32_16x16x32_bf16 v[104:107], v[158:161], v[190:193], v[104:107]
	v_mfma_f32_16x16x32_bf16 v[92:95], v[150:153], v[198:201], v[92:95]
	v_mfma_f32_16x16x32_bf16 v[88:91], v[158:161], v[198:201], v[88:91]
	v_mfma_f32_16x16x32_bf16 v[76:79], v[150:153], v[208:211], v[76:79]
	v_mfma_f32_16x16x32_bf16 v[72:75], v[158:161], v[208:211], v[72:75]
	v_mfma_f32_16x16x32_bf16 v[116:119], v[162:165], v[178:181], v[116:119]
	v_mfma_f32_16x16x32_bf16 v[112:115], v[170:173], v[178:181], v[112:115]
	v_mfma_f32_16x16x32_bf16 v[100:103], v[162:165], v[186:189], v[100:103]
	v_mfma_f32_16x16x32_bf16 v[96:99], v[170:173], v[186:189], v[96:99]
	v_mfma_f32_16x16x32_bf16 v[84:87], v[162:165], v[194:197], v[84:87]
	v_mfma_f32_16x16x32_bf16 v[80:83], v[170:173], v[194:197], v[80:83]
	v_mfma_f32_16x16x32_bf16 v[68:71], v[162:165], v[202:205], v[68:71]
	v_mfma_f32_16x16x32_bf16 v[64:67], v[170:173], v[202:205], v[64:67]
	v_mfma_f32_16x16x32_bf16 v[116:119], v[166:169], v[182:185], v[116:119]
	v_mfma_f32_16x16x32_bf16 v[112:115], v[174:177], v[182:185], v[112:115]
	v_mfma_f32_16x16x32_bf16 v[100:103], v[166:169], v[190:193], v[100:103]
	v_mfma_f32_16x16x32_bf16 v[96:99], v[174:177], v[190:193], v[96:99]
	v_mfma_f32_16x16x32_bf16 v[84:87], v[166:169], v[198:201], v[84:87]
	v_mfma_f32_16x16x32_bf16 v[80:83], v[174:177], v[198:201], v[80:83]
	v_mfma_f32_16x16x32_bf16 v[68:71], v[166:169], v[208:211], v[68:71]
	v_mfma_f32_16x16x32_bf16 v[64:67], v[174:177], v[208:211], v[64:67]
	s_barrier
	s_add_i32 s28, s52, s43
	s_mov_b32 m0, s28
	ds_read_b128 v[178:181], v149 offset:16384
	ds_read_b128 v[182:185], v149 offset:17408
	ds_read_b128 v[186:189], v149 offset:18432
	ds_read_b128 v[190:193], v149 offset:19456
	ds_read_b128 v[194:197], v149 offset:20480
	ds_read_b128 v[198:201], v149 offset:21504
	ds_read_b128 v[202:205], v149 offset:22528
	ds_read_b128 v[208:211], v149 offset:23552
	global_load_lds_dwordx4 v128, s[34:35]
	s_add_i32 m0, s28, 0x2000
	s_add_u32 s28, s34, 0x100000
	s_mov_b64 s[98:99], s[34:35]
	s_addc_u32 s29, s35, 0
	s_add_i32 s59, s53, s43
	global_load_lds_dwordx4 v130, s[34:35]
	s_mov_b32 m0, s59
	s_nop 0
	global_load_lds_dwordx4 v128, s[28:29]
	s_add_i32 m0, s59, 0x2000
	s_nop 0
	global_load_lds_dwordx4 v130, s[28:29]
	s_mov_b32 m0, s44
	s_nop 0
	global_load_lds_dwordx4 v128, s[36:37]
	s_waitcnt vmcnt(7)
	s_waitcnt lgkmcnt(0)
	s_barrier
	s_waitcnt lgkmcnt(0)
	v_mfma_f32_16x16x32_bf16 v[60:63], v[140:143], v[178:181], v[60:63]
	v_mfma_f32_16x16x32_bf16 v[56:59], v[154:157], v[178:181], v[56:59]
	v_mfma_f32_16x16x32_bf16 v[44:47], v[140:143], v[186:189], v[44:47]
	v_mfma_f32_16x16x32_bf16 v[40:43], v[154:157], v[186:189], v[40:43]
	v_mfma_f32_16x16x32_bf16 v[28:31], v[140:143], v[194:197], v[28:31]
	v_mfma_f32_16x16x32_bf16 v[24:27], v[154:157], v[194:197], v[24:27]
	v_mfma_f32_16x16x32_bf16 v[12:15], v[140:143], v[202:205], v[12:15]
	v_mfma_f32_16x16x32_bf16 v[8:11], v[154:157], v[202:205], v[8:11]
	v_mfma_f32_16x16x32_bf16 v[60:63], v[150:153], v[182:185], v[60:63]
	v_mfma_f32_16x16x32_bf16 v[56:59], v[158:161], v[182:185], v[56:59]
	v_mfma_f32_16x16x32_bf16 v[44:47], v[150:153], v[190:193], v[44:47]
	v_mfma_f32_16x16x32_bf16 v[40:43], v[158:161], v[190:193], v[40:43]
	v_mfma_f32_16x16x32_bf16 v[28:31], v[150:153], v[198:201], v[28:31]
	v_mfma_f32_16x16x32_bf16 v[24:27], v[158:161], v[198:201], v[24:27]
	v_mfma_f32_16x16x32_bf16 v[12:15], v[150:153], v[208:211], v[12:15]
	v_mfma_f32_16x16x32_bf16 v[8:11], v[158:161], v[208:211], v[8:11]
	v_mfma_f32_16x16x32_bf16 v[52:55], v[162:165], v[178:181], v[52:55]
	v_mfma_f32_16x16x32_bf16 v[48:51], v[170:173], v[178:181], v[48:51]
	v_mfma_f32_16x16x32_bf16 v[36:39], v[162:165], v[186:189], v[36:39]
	v_mfma_f32_16x16x32_bf16 v[32:35], v[170:173], v[186:189], v[32:35]
	v_mfma_f32_16x16x32_bf16 v[20:23], v[162:165], v[194:197], v[20:23]
	v_mfma_f32_16x16x32_bf16 v[16:19], v[170:173], v[194:197], v[16:19]
	v_mfma_f32_16x16x32_bf16 v[4:7], v[162:165], v[202:205], v[4:7]
	v_mfma_f32_16x16x32_bf16 v[0:3], v[170:173], v[202:205], v[0:3]
	v_mfma_f32_16x16x32_bf16 v[52:55], v[166:169], v[182:185], v[52:55]
	v_mfma_f32_16x16x32_bf16 v[48:51], v[174:177], v[182:185], v[48:51]
	v_mfma_f32_16x16x32_bf16 v[36:39], v[166:169], v[190:193], v[36:39]
	v_mfma_f32_16x16x32_bf16 v[32:35], v[174:177], v[190:193], v[32:35]
	v_mfma_f32_16x16x32_bf16 v[20:23], v[166:169], v[198:201], v[20:23]
	v_mfma_f32_16x16x32_bf16 v[16:19], v[174:177], v[198:201], v[16:19]
	v_mfma_f32_16x16x32_bf16 v[4:7], v[166:169], v[208:211], v[4:7]
	v_mfma_f32_16x16x32_bf16 v[0:3], v[174:177], v[208:211], v[0:3]
	s_barrier
	s_mov_b32 m0, s45
	s_nop 0
	global_load_lds_dwordx4 v130, s[36:37]
	s_add_i32 s59, 0, 0x18000
	s_add_i32 s60, 0, 0x1c000
	v_add_u32_e32 v158, s59, v145
	v_add_u32_e32 v174, s60, v145
	ds_read_b128 v[140:143], v158
	ds_read_b128 v[150:153], v158 offset:1024
	ds_read_b128 v[154:157], v158 offset:2048
	ds_read_b128 v[158:161], v158 offset:3072
	ds_read_b128 v[162:165], v174
	ds_read_b128 v[166:169], v174 offset:1024
	ds_read_b128 v[170:173], v174 offset:2048
	ds_read_b128 v[174:177], v174 offset:3072
	s_add_u32 s28, s36, 0x100000
	s_addc_u32 s29, s37, 0
	s_mov_b32 m0, s46
	ds_read_b128 v[178:181], v149 offset:32768
	ds_read_b128 v[182:185], v149 offset:33792
	ds_read_b128 v[186:189], v149 offset:34816
	ds_read_b128 v[190:193], v149 offset:35840
	ds_read_b128 v[194:197], v149 offset:36864
	ds_read_b128 v[198:201], v149 offset:37888
	ds_read_b128 v[202:205], v149 offset:38912
	ds_read_b128 v[208:211], v149 offset:39936
	global_load_lds_dwordx4 v128, s[28:29]
	s_mov_b32 m0, s47
	s_nop 0
	global_load_lds_dwordx4 v130, s[28:29]
	s_waitcnt vmcnt(8)
	s_waitcnt lgkmcnt(0)
	s_barrier
	s_waitcnt lgkmcnt(0)
	v_mfma_f32_16x16x32_bf16 v[124:127], v[140:143], v[178:181], v[124:127]
	v_mfma_f32_16x16x32_bf16 v[120:123], v[154:157], v[178:181], v[120:123]
	v_mfma_f32_16x16x32_bf16 v[108:111], v[140:143], v[186:189], v[108:111]
	v_mfma_f32_16x16x32_bf16 v[104:107], v[154:157], v[186:189], v[104:107]
	v_mfma_f32_16x16x32_bf16 v[92:95], v[140:143], v[194:197], v[92:95]
	v_mfma_f32_16x16x32_bf16 v[88:91], v[154:157], v[194:197], v[88:91]
	v_mfma_f32_16x16x32_bf16 v[76:79], v[140:143], v[202:205], v[76:79]
	v_mfma_f32_16x16x32_bf16 v[72:75], v[154:157], v[202:205], v[72:75]
	v_mfma_f32_16x16x32_bf16 v[124:127], v[150:153], v[182:185], v[124:127]
	v_mfma_f32_16x16x32_bf16 v[120:123], v[158:161], v[182:185], v[120:123]
	v_mfma_f32_16x16x32_bf16 v[108:111], v[150:153], v[190:193], v[108:111]
	v_mfma_f32_16x16x32_bf16 v[104:107], v[158:161], v[190:193], v[104:107]
	v_mfma_f32_16x16x32_bf16 v[92:95], v[150:153], v[198:201], v[92:95]
	v_mfma_f32_16x16x32_bf16 v[88:91], v[158:161], v[198:201], v[88:91]
	v_mfma_f32_16x16x32_bf16 v[76:79], v[150:153], v[208:211], v[76:79]
	v_mfma_f32_16x16x32_bf16 v[72:75], v[158:161], v[208:211], v[72:75]
	v_mfma_f32_16x16x32_bf16 v[116:119], v[162:165], v[178:181], v[116:119]
	v_mfma_f32_16x16x32_bf16 v[112:115], v[170:173], v[178:181], v[112:115]
	v_mfma_f32_16x16x32_bf16 v[100:103], v[162:165], v[186:189], v[100:103]
	v_mfma_f32_16x16x32_bf16 v[96:99], v[170:173], v[186:189], v[96:99]
	v_mfma_f32_16x16x32_bf16 v[84:87], v[162:165], v[194:197], v[84:87]
	v_mfma_f32_16x16x32_bf16 v[80:83], v[170:173], v[194:197], v[80:83]
	v_mfma_f32_16x16x32_bf16 v[68:71], v[162:165], v[202:205], v[68:71]
	v_mfma_f32_16x16x32_bf16 v[64:67], v[170:173], v[202:205], v[64:67]
	v_mfma_f32_16x16x32_bf16 v[116:119], v[166:169], v[182:185], v[116:119]
	v_mfma_f32_16x16x32_bf16 v[112:115], v[174:177], v[182:185], v[112:115]
	v_mfma_f32_16x16x32_bf16 v[100:103], v[166:169], v[190:193], v[100:103]
	v_mfma_f32_16x16x32_bf16 v[96:99], v[174:177], v[190:193], v[96:99]
	v_mfma_f32_16x16x32_bf16 v[84:87], v[166:169], v[198:201], v[84:87]
	v_mfma_f32_16x16x32_bf16 v[80:83], v[174:177], v[198:201], v[80:83]
	v_mfma_f32_16x16x32_bf16 v[68:71], v[166:169], v[208:211], v[68:71]
	v_mfma_f32_16x16x32_bf16 v[64:67], v[174:177], v[208:211], v[64:67]
	s_barrier
	s_add_i32 s28, s59, s43
	s_mov_b32 m0, s28
	ds_read_b128 v[178:181], v149 offset:49152
	ds_read_b128 v[182:185], v149 offset:50176
	ds_read_b128 v[186:189], v149 offset:51200
	ds_read_b128 v[190:193], v149 offset:52224
	ds_read_b128 v[194:197], v149 offset:53248
	ds_read_b128 v[198:201], v149 offset:54272
	ds_read_b128 v[202:205], v149 offset:55296
	ds_read_b128 v[208:211], v149 offset:56320
	global_load_lds_dwordx4 v212, s[34:35]
	s_add_i32 m0, s28, 0x2000
	s_add_u32 s28, s34, 0x100080
	s_addc_u32 s29, s35, 0
	s_add_i32 s34, s60, s43
	global_load_lds_dwordx4 v213, s[98:99]
	s_mov_b32 m0, s34
	s_nop 0
	global_load_lds_dwordx4 v128, s[28:29]
	s_add_i32 m0, s34, 0x2000
	s_nop 0
	global_load_lds_dwordx4 v130, s[28:29]
	s_mov_b32 m0, s49
	s_nop 0
	global_load_lds_dwordx4 v212, s[36:37]
	s_cmp_lg_u32 s58, 60
	s_cbranch_scc1 .Lbal_last_18
	s_mov_b32 m0, s50
	s_nop 0
	global_load_lds_dwordx4 v213, s[36:37]
.Lbal_last_18:
	s_waitcnt vmcnt(7)
	s_waitcnt lgkmcnt(0)
	s_barrier
	s_waitcnt lgkmcnt(0)
	v_mfma_f32_16x16x32_bf16 v[60:63], v[140:143], v[178:181], v[60:63]
	v_mfma_f32_16x16x32_bf16 v[56:59], v[154:157], v[178:181], v[56:59]
	v_mfma_f32_16x16x32_bf16 v[44:47], v[140:143], v[186:189], v[44:47]
	v_mfma_f32_16x16x32_bf16 v[40:43], v[154:157], v[186:189], v[40:43]
	v_mfma_f32_16x16x32_bf16 v[28:31], v[140:143], v[194:197], v[28:31]
	v_mfma_f32_16x16x32_bf16 v[24:27], v[154:157], v[194:197], v[24:27]
	v_mfma_f32_16x16x32_bf16 v[12:15], v[140:143], v[202:205], v[12:15]
	v_mfma_f32_16x16x32_bf16 v[8:11], v[154:157], v[202:205], v[8:11]
	v_mfma_f32_16x16x32_bf16 v[60:63], v[150:153], v[182:185], v[60:63]
	v_mfma_f32_16x16x32_bf16 v[56:59], v[158:161], v[182:185], v[56:59]
	v_mfma_f32_16x16x32_bf16 v[44:47], v[150:153], v[190:193], v[44:47]
	v_mfma_f32_16x16x32_bf16 v[40:43], v[158:161], v[190:193], v[40:43]
	v_mfma_f32_16x16x32_bf16 v[28:31], v[150:153], v[198:201], v[28:31]
	v_mfma_f32_16x16x32_bf16 v[24:27], v[158:161], v[198:201], v[24:27]
	v_mfma_f32_16x16x32_bf16 v[12:15], v[150:153], v[208:211], v[12:15]
	v_mfma_f32_16x16x32_bf16 v[8:11], v[158:161], v[208:211], v[8:11]
	v_mfma_f32_16x16x32_bf16 v[52:55], v[162:165], v[178:181], v[52:55]
	v_mfma_f32_16x16x32_bf16 v[48:51], v[170:173], v[178:181], v[48:51]
	v_mfma_f32_16x16x32_bf16 v[36:39], v[162:165], v[186:189], v[36:39]
	v_mfma_f32_16x16x32_bf16 v[32:35], v[170:173], v[186:189], v[32:35]
	v_mfma_f32_16x16x32_bf16 v[20:23], v[162:165], v[194:197], v[20:23]
	v_mfma_f32_16x16x32_bf16 v[16:19], v[170:173], v[194:197], v[16:19]
	v_mfma_f32_16x16x32_bf16 v[4:7], v[162:165], v[202:205], v[4:7]
	v_mfma_f32_16x16x32_bf16 v[0:3], v[170:173], v[202:205], v[0:3]
	v_mfma_f32_16x16x32_bf16 v[52:55], v[166:169], v[182:185], v[52:55]
	v_mfma_f32_16x16x32_bf16 v[48:51], v[174:177], v[182:185], v[48:51]
	v_mfma_f32_16x16x32_bf16 v[36:39], v[166:169], v[190:193], v[36:39]
	v_mfma_f32_16x16x32_bf16 v[32:35], v[174:177], v[190:193], v[32:35]
	v_mfma_f32_16x16x32_bf16 v[20:23], v[166:169], v[198:201], v[20:23]
	v_mfma_f32_16x16x32_bf16 v[16:19], v[174:177], v[198:201], v[16:19]
	v_mfma_f32_16x16x32_bf16 v[4:7], v[166:169], v[208:211], v[4:7]
	v_mfma_f32_16x16x32_bf16 v[0:3], v[174:177], v[208:211], v[0:3]
	s_barrier
	s_add_i32 s58, s58, 2
	s_add_u32 s56, s56, 0x100
	s_addc_u32 s57, s57, 0
	s_cmp_gt_u32 s58, 61
	s_mov_b64 s[28:29], s[30:31]
	s_cbranch_scc0 .LBB0_778
	s_setprio 0
	s_and_b64 vcc, exec, s[16:17]
	s_cbranch_vccz .LBB0_781
	s_barrier

.LBB0_895:
	s_cmp_eq_i32 s61, -2
	s_cbranch_scc1 .Lbal_first_17
	s_mov_b32 m0, s52
	s_nop 0
	global_load_lds_dwordx4 v149, s[100:101]
.Lbal_first_17:
	ds_read_b128 v[140:143], v153
	ds_read_b128 v[144:147], v153 offset:1024
	ds_read_b128 v[158:161], v153 offset:2048
	ds_read_b128 v[162:165], v153 offset:3072
	ds_read_b128 v[166:169], v154
	ds_read_b128 v[170:173], v154 offset:1024
	ds_read_b128 v[174:177], v154 offset:2048
	ds_read_b128 v[178:181], v154 offset:3072
	s_add_u32 s38, s36, 0xfffc0080
	s_addc_u32 s39, s37, -1
	s_cmp_eq_u32 s61, 12
	s_cselect_b32 s41, s3, s39
	s_cselect_b32 s40, s29, s38
	s_cselect_b32 s39, s27, s60
	s_cselect_b32 s38, s58, s59
	s_add_i32 m0, s46, 0xc000
	ds_read_b128 v[182:185], v155
	ds_read_b128 v[186:189], v155 offset:1024
	ds_read_b128 v[190:193], v155 offset:2048
	ds_read_b128 v[194:197], v155 offset:3072
	ds_read_b128 v[198:201], v155 offset:4096
	ds_read_b128 v[202:205], v155 offset:5120
	ds_read_b128 v[208:211], v155 offset:6144
	ds_read_b128 v[212:215], v155 offset:7168
	global_load_lds_dwordx4 v134, s[36:37]
	s_add_i32 m0, s46, 0xe000
	s_nop 0
	global_load_lds_dwordx4 v132, s[36:37]
	s_waitcnt vmcnt(8)
	s_waitcnt lgkmcnt(0)
	s_barrier
	s_waitcnt lgkmcnt(0)
	v_mfma_f32_16x16x32_bf16 v[124:127], v[140:143], v[182:185], v[124:127]
	v_mfma_f32_16x16x32_bf16 v[120:123], v[158:161], v[182:185], v[120:123]
	v_mfma_f32_16x16x32_bf16 v[108:111], v[140:143], v[190:193], v[108:111]
	v_mfma_f32_16x16x32_bf16 v[104:107], v[158:161], v[190:193], v[104:107]
	v_mfma_f32_16x16x32_bf16 v[92:95], v[140:143], v[198:201], v[92:95]
	v_mfma_f32_16x16x32_bf16 v[88:91], v[158:161], v[198:201], v[88:91]
	v_mfma_f32_16x16x32_bf16 v[76:79], v[140:143], v[208:211], v[76:79]
	v_mfma_f32_16x16x32_bf16 v[72:75], v[158:161], v[208:211], v[72:75]
	v_mfma_f32_16x16x32_bf16 v[124:127], v[144:147], v[186:189], v[124:127]
	v_mfma_f32_16x16x32_bf16 v[120:123], v[162:165], v[186:189], v[120:123]
	v_mfma_f32_16x16x32_bf16 v[108:111], v[144:147], v[194:197], v[108:111]
	v_mfma_f32_16x16x32_bf16 v[104:107], v[162:165], v[194:197], v[104:107]
	v_mfma_f32_16x16x32_bf16 v[92:95], v[144:147], v[202:205], v[92:95]
	v_mfma_f32_16x16x32_bf16 v[88:91], v[162:165], v[202:205], v[88:91]
	v_mfma_f32_16x16x32_bf16 v[76:79], v[144:147], v[212:215], v[76:79]
	v_mfma_f32_16x16x32_bf16 v[72:75], v[162:165], v[212:215], v[72:75]
	v_mfma_f32_16x16x32_bf16 v[116:119], v[166:169], v[182:185], v[116:119]
	v_mfma_f32_16x16x32_bf16 v[112:115], v[174:177], v[182:185], v[112:115]
	v_mfma_f32_16x16x32_bf16 v[100:103], v[166:169], v[190:193], v[100:103]
	v_mfma_f32_16x16x32_bf16 v[96:99], v[174:177], v[190:193], v[96:99]
	v_mfma_f32_16x16x32_bf16 v[84:87], v[166:169], v[198:201], v[84:87]
	v_mfma_f32_16x16x32_bf16 v[80:83], v[174:177], v[198:201], v[80:83]
	v_mfma_f32_16x16x32_bf16 v[68:71], v[166:169], v[208:211], v[68:71]
	v_mfma_f32_16x16x32_bf16 v[64:67], v[174:177], v[208:211], v[64:67]
	v_mfma_f32_16x16x32_bf16 v[116:119], v[170:173], v[186:189], v[116:119]
	v_mfma_f32_16x16x32_bf16 v[112:115], v[178:181], v[186:189], v[112:115]
	v_mfma_f32_16x16x32_bf16 v[100:103], v[170:173], v[194:197], v[100:103]
	v_mfma_f32_16x16x32_bf16 v[96:99], v[178:181], v[194:197], v[96:99]
	v_mfma_f32_16x16x32_bf16 v[84:87], v[170:173], v[202:205], v[84:87]
	v_mfma_f32_16x16x32_bf16 v[80:83], v[178:181], v[202:205], v[80:83]
	v_mfma_f32_16x16x32_bf16 v[68:71], v[170:173], v[212:215], v[68:71]
	v_mfma_f32_16x16x32_bf16 v[64:67], v[178:181], v[212:215], v[64:67]
	s_barrier
	s_add_i32 s62, s54, s45
	s_mov_b32 m0, s62
	ds_read_b128 v[182:185], v155 offset:16384
	ds_read_b128 v[186:189], v155 offset:17408
	ds_read_b128 v[190:193], v155 offset:18432
	ds_read_b128 v[194:197], v155 offset:19456
	ds_read_b128 v[198:201], v155 offset:20480
	ds_read_b128 v[202:205], v155 offset:21504
	ds_read_b128 v[208:211], v155 offset:22528
	ds_read_b128 v[212:215], v155 offset:23552
	global_load_lds_dwordx4 v128, s[38:39]
	s_add_i32 m0, s62, 0x2000
	s_add_u32 s62, s38, 0x40000
	s_mov_b64 s[98:99], s[38:39]
	s_addc_u32 s63, s39, 0
	s_add_i32 s64, s55, s45
	global_load_lds_dwordx4 v130, s[38:39]
	s_mov_b32 m0, s64
	s_mov_b64 s[100:101], s[40:41]
	global_load_lds_dwordx4 v128, s[62:63]
	s_add_i32 m0, s64, 0x2000
	s_nop 0
	global_load_lds_dwordx4 v130, s[62:63]
	s_mov_b32 m0, s46
	s_nop 0
	global_load_lds_dwordx4 v128, s[40:41]
	s_waitcnt vmcnt(7)
	s_waitcnt lgkmcnt(0)
	s_barrier
	s_waitcnt lgkmcnt(0)
	v_mfma_f32_16x16x32_bf16 v[60:63], v[140:143], v[182:185], v[60:63]
	v_mfma_f32_16x16x32_bf16 v[56:59], v[158:161], v[182:185], v[56:59]
	v_mfma_f32_16x16x32_bf16 v[44:47], v[140:143], v[190:193], v[44:47]
	v_mfma_f32_16x16x32_bf16 v[40:43], v[158:161], v[190:193], v[40:43]
	v_mfma_f32_16x16x32_bf16 v[28:31], v[140:143], v[198:201], v[28:31]
	v_mfma_f32_16x16x32_bf16 v[24:27], v[158:161], v[198:201], v[24:27]
	v_mfma_f32_16x16x32_bf16 v[12:15], v[140:143], v[208:211], v[12:15]
	v_mfma_f32_16x16x32_bf16 v[8:11], v[158:161], v[208:211], v[8:11]
	v_mfma_f32_16x16x32_bf16 v[60:63], v[144:147], v[186:189], v[60:63]
	v_mfma_f32_16x16x32_bf16 v[56:59], v[162:165], v[186:189], v[56:59]
	v_mfma_f32_16x16x32_bf16 v[44:47], v[144:147], v[194:197], v[44:47]
	v_mfma_f32_16x16x32_bf16 v[40:43], v[162:165], v[194:197], v[40:43]
	v_mfma_f32_16x16x32_bf16 v[28:31], v[144:147], v[202:205], v[28:31]
	v_mfma_f32_16x16x32_bf16 v[24:27], v[162:165], v[202:205], v[24:27]
	v_mfma_f32_16x16x32_bf16 v[12:15], v[144:147], v[212:215], v[12:15]
	v_mfma_f32_16x16x32_bf16 v[8:11], v[162:165], v[212:215], v[8:11]
	v_mfma_f32_16x16x32_bf16 v[52:55], v[166:169], v[182:185], v[52:55]
	v_mfma_f32_16x16x32_bf16 v[48:51], v[174:177], v[182:185], v[48:51]
	v_mfma_f32_16x16x32_bf16 v[36:39], v[166:169], v[190:193], v[36:39]
	v_mfma_f32_16x16x32_bf16 v[32:35], v[174:177], v[190:193], v[32:35]
	v_mfma_f32_16x16x32_bf16 v[20:23], v[166:169], v[198:201], v[20:23]
	v_mfma_f32_16x16x32_bf16 v[16:19], v[174:177], v[198:201], v[16:19]
	v_mfma_f32_16x16x32_bf16 v[4:7], v[166:169], v[208:211], v[4:7]
	v_mfma_f32_16x16x32_bf16 v[0:3], v[174:177], v[208:211], v[0:3]
	v_mfma_f32_16x16x32_bf16 v[52:55], v[170:173], v[186:189], v[52:55]
	v_mfma_f32_16x16x32_bf16 v[48:51], v[178:181], v[186:189], v[48:51]
	v_mfma_f32_16x16x32_bf16 v[36:39], v[170:173], v[194:197], v[36:39]
	v_mfma_f32_16x16x32_bf16 v[32:35], v[178:181], v[194:197], v[32:35]
	v_mfma_f32_16x16x32_bf16 v[20:23], v[170:173], v[202:205], v[20:23]
	v_mfma_f32_16x16x32_bf16 v[16:19], v[178:181], v[202:205], v[16:19]
	v_mfma_f32_16x16x32_bf16 v[4:7], v[170:173], v[212:215], v[4:7]
	v_mfma_f32_16x16x32_bf16 v[0:3], v[178:181], v[212:215], v[0:3]
	s_barrier
	s_mov_b32 m0, s47
	s_nop 0
	global_load_lds_dwordx4 v130, s[40:41]
	s_add_i32 s62, 0, 0x18000
	v_add_u32_e32 v157, s62, v151
	s_add_i32 s63, 0, 0x1c000
	ds_read_b128 v[140:143], v157
	ds_read_b128 v[144:147], v157 offset:1024
	ds_read_b128 v[158:161], v157 offset:2048
	ds_read_b128 v[162:165], v157 offset:3072
	v_add_u32_e32 v157, s63, v151
	ds_read_b128 v[166:169], v157
	ds_read_b128 v[170:173], v157 offset:1024
	ds_read_b128 v[174:177], v157 offset:2048
	ds_read_b128 v[178:181], v157 offset:3072
	s_add_u32 s40, s40, 0x40000
	s_addc_u32 s41, s41, 0
	s_mov_b32 m0, s48
	ds_read_b128 v[182:185], v155 offset:32768
	ds_read_b128 v[186:189], v155 offset:33792
	ds_read_b128 v[190:193], v155 offset:34816
	ds_read_b128 v[194:197], v155 offset:35840
	ds_read_b128 v[198:201], v155 offset:36864
	ds_read_b128 v[202:205], v155 offset:37888
	ds_read_b128 v[208:211], v155 offset:38912
	ds_read_b128 v[212:215], v155 offset:39936
	global_load_lds_dwordx4 v128, s[40:41]
	s_mov_b32 m0, s49
	s_nop 0
	global_load_lds_dwordx4 v130, s[40:41]
	s_waitcnt vmcnt(8)
	s_waitcnt lgkmcnt(0)
	s_barrier
	s_waitcnt lgkmcnt(0)
	v_mfma_f32_16x16x32_bf16 v[124:127], v[140:143], v[182:185], v[124:127]
	v_mfma_f32_16x16x32_bf16 v[120:123], v[158:161], v[182:185], v[120:123]
	v_mfma_f32_16x16x32_bf16 v[108:111], v[140:143], v[190:193], v[108:111]
	v_mfma_f32_16x16x32_bf16 v[104:107], v[158:161], v[190:193], v[104:107]
	v_mfma_f32_16x16x32_bf16 v[92:95], v[140:143], v[198:201], v[92:95]
	v_mfma_f32_16x16x32_bf16 v[88:91], v[158:161], v[198:201], v[88:91]
	v_mfma_f32_16x16x32_bf16 v[76:79], v[140:143], v[208:211], v[76:79]
	v_mfma_f32_16x16x32_bf16 v[72:75], v[158:161], v[208:211], v[72:75]
	v_mfma_f32_16x16x32_bf16 v[124:127], v[144:147], v[186:189], v[124:127]
	v_mfma_f32_16x16x32_bf16 v[120:123], v[162:165], v[186:189], v[120:123]
	v_mfma_f32_16x16x32_bf16 v[108:111], v[144:147], v[194:197], v[108:111]
	v_mfma_f32_16x16x32_bf16 v[104:107], v[162:165], v[194:197], v[104:107]
	v_mfma_f32_16x16x32_bf16 v[92:95], v[144:147], v[202:205], v[92:95]
	v_mfma_f32_16x16x32_bf16 v[88:91], v[162:165], v[202:205], v[88:91]
	v_mfma_f32_16x16x32_bf16 v[76:79], v[144:147], v[212:215], v[76:79]
	v_mfma_f32_16x16x32_bf16 v[72:75], v[162:165], v[212:215], v[72:75]
	v_mfma_f32_16x16x32_bf16 v[116:119], v[166:169], v[182:185], v[116:119]
	v_mfma_f32_16x16x32_bf16 v[112:115], v[174:177], v[182:185], v[112:115]
	v_mfma_f32_16x16x32_bf16 v[100:103], v[166:169], v[190:193], v[100:103]
	v_mfma_f32_16x16x32_bf16 v[96:99], v[174:177], v[190:193], v[96:99]
	v_mfma_f32_16x16x32_bf16 v[84:87], v[166:169], v[198:201], v[84:87]
	v_mfma_f32_16x16x32_bf16 v[80:83], v[174:177], v[198:201], v[80:83]
	v_mfma_f32_16x16x32_bf16 v[68:71], v[166:169], v[208:211], v[68:71]
	v_mfma_f32_16x16x32_bf16 v[64:67], v[174:177], v[208:211], v[64:67]
	v_mfma_f32_16x16x32_bf16 v[116:119], v[170:173], v[186:189], v[116:119]
	v_mfma_f32_16x16x32_bf16 v[112:115], v[178:181], v[186:189], v[112:115]
	v_mfma_f32_16x16x32_bf16 v[100:103], v[170:173], v[194:197], v[100:103]
	v_mfma_f32_16x16x32_bf16 v[96:99], v[178:181], v[194:197], v[96:99]
	v_mfma_f32_16x16x32_bf16 v[84:87], v[170:173], v[202:205], v[84:87]
	v_mfma_f32_16x16x32_bf16 v[80:83], v[178:181], v[202:205], v[80:83]
	v_mfma_f32_16x16x32_bf16 v[68:71], v[170:173], v[212:215], v[68:71]
	v_mfma_f32_16x16x32_bf16 v[64:67], v[178:181], v[212:215], v[64:67]
	s_barrier
	s_add_i32 s40, s62, s45
	s_mov_b32 m0, s40
	ds_read_b128 v[182:185], v155 offset:49152
	ds_read_b128 v[186:189], v155 offset:50176
	ds_read_b128 v[190:193], v155 offset:51200
	ds_read_b128 v[194:197], v155 offset:52224
	ds_read_b128 v[198:201], v155 offset:53248
	ds_read_b128 v[202:205], v155 offset:54272
	ds_read_b128 v[208:211], v155 offset:55296
	ds_read_b128 v[212:215], v155 offset:56320
	global_load_lds_dwordx4 v148, s[38:39]
	s_add_i32 m0, s40, 0x2000
	s_add_u32 s38, s38, 0x40080
	s_addc_u32 s39, s39, 0
	s_add_i32 s40, s63, s45
	global_load_lds_dwordx4 v149, s[98:99]
	s_mov_b32 m0, s40
	s_nop 0
	global_load_lds_dwordx4 v128, s[38:39]
	s_add_i32 m0, s40, 0x2000
	s_nop 0
	global_load_lds_dwordx4 v130, s[38:39]
	s_mov_b32 m0, s51
	s_nop 0
	global_load_lds_dwordx4 v148, s[100:101]
	s_cmp_lg_u32 s61, 12
	s_cbranch_scc1 .Lbal_last_17
	s_mov_b32 m0, s52
	s_nop 0
	global_load_lds_dwordx4 v149, s[100:101]
.Lbal_last_17:
	s_waitcnt vmcnt(7)
	s_waitcnt lgkmcnt(0)
	s_barrier
	s_waitcnt lgkmcnt(0)
	v_mfma_f32_16x16x32_bf16 v[60:63], v[140:143], v[182:185], v[60:63]
	v_mfma_f32_16x16x32_bf16 v[56:59], v[158:161], v[182:185], v[56:59]
	v_mfma_f32_16x16x32_bf16 v[44:47], v[140:143], v[190:193], v[44:47]
	v_mfma_f32_16x16x32_bf16 v[40:43], v[158:161], v[190:193], v[40:43]
	v_mfma_f32_16x16x32_bf16 v[28:31], v[140:143], v[198:201], v[28:31]
	v_mfma_f32_16x16x32_bf16 v[24:27], v[158:161], v[198:201], v[24:27]
	v_mfma_f32_16x16x32_bf16 v[12:15], v[140:143], v[208:211], v[12:15]
	v_mfma_f32_16x16x32_bf16 v[8:11], v[158:161], v[208:211], v[8:11]
	v_mfma_f32_16x16x32_bf16 v[60:63], v[144:147], v[186:189], v[60:63]
	v_mfma_f32_16x16x32_bf16 v[56:59], v[162:165], v[186:189], v[56:59]
	v_mfma_f32_16x16x32_bf16 v[44:47], v[144:147], v[194:197], v[44:47]
	v_mfma_f32_16x16x32_bf16 v[40:43], v[162:165], v[194:197], v[40:43]
	v_mfma_f32_16x16x32_bf16 v[28:31], v[144:147], v[202:205], v[28:31]
	v_mfma_f32_16x16x32_bf16 v[24:27], v[162:165], v[202:205], v[24:27]
	v_mfma_f32_16x16x32_bf16 v[12:15], v[144:147], v[212:215], v[12:15]
	v_mfma_f32_16x16x32_bf16 v[8:11], v[162:165], v[212:215], v[8:11]
	v_mfma_f32_16x16x32_bf16 v[52:55], v[166:169], v[182:185], v[52:55]
	v_mfma_f32_16x16x32_bf16 v[48:51], v[174:177], v[182:185], v[48:51]
	v_mfma_f32_16x16x32_bf16 v[36:39], v[166:169], v[190:193], v[36:39]
	v_mfma_f32_16x16x32_bf16 v[32:35], v[174:177], v[190:193], v[32:35]
	v_mfma_f32_16x16x32_bf16 v[20:23], v[166:169], v[198:201], v[20:23]
	v_mfma_f32_16x16x32_bf16 v[16:19], v[174:177], v[198:201], v[16:19]
	v_mfma_f32_16x16x32_bf16 v[4:7], v[166:169], v[208:211], v[4:7]
	v_mfma_f32_16x16x32_bf16 v[0:3], v[174:177], v[208:211], v[0:3]
	v_mfma_f32_16x16x32_bf16 v[52:55], v[170:173], v[186:189], v[52:55]
	v_mfma_f32_16x16x32_bf16 v[48:51], v[178:181], v[186:189], v[48:51]
	v_mfma_f32_16x16x32_bf16 v[36:39], v[170:173], v[194:197], v[36:39]
	v_mfma_f32_16x16x32_bf16 v[32:35], v[178:181], v[194:197], v[32:35]
	v_mfma_f32_16x16x32_bf16 v[20:23], v[170:173], v[202:205], v[20:23]
	v_mfma_f32_16x16x32_bf16 v[16:19], v[178:181], v[202:205], v[16:19]
	v_mfma_f32_16x16x32_bf16 v[4:7], v[170:173], v[212:215], v[4:7]
	v_mfma_f32_16x16x32_bf16 v[0:3], v[178:181], v[212:215], v[0:3]
	s_barrier
	s_add_i32 s61, s61, 2
	s_add_u32 s59, s59, 0x100
	s_addc_u32 s60, s60, 0
	s_add_u32 s36, s36, 0x100
	s_addc_u32 s37, s37, 0
	s_cmp_gt_u32 s61, 13
	s_cbranch_scc0 .LBB0_895
	s_setprio 0
	s_and_b64 vcc, exec, s[24:25]
	s_cbranch_vccz .LBB0_898
	s_barrier

.LBB0_988:
	s_cmp_eq_i32 s53, -2
	s_cbranch_scc1 .Lbal_first_16
	s_mov_b32 m0, s44
	s_nop 0
	global_load_lds_dwordx4 v220, s[100:101]
.Lbal_first_16:
	ds_read_b128 v[144:147], v151
	ds_read_b128 v[156:159], v151 offset:1024
	ds_read_b128 v[160:163], v151 offset:2048
	ds_read_b128 v[164:167], v151 offset:3072
	ds_read_b128 v[168:171], v152
	ds_read_b128 v[172:175], v152 offset:1024
	ds_read_b128 v[176:179], v152 offset:2048
	ds_read_b128 v[180:183], v152 offset:3072
	s_add_u32 s26, s6, 0xfffc0080
	s_addc_u32 s27, s7, -1
	s_cmp_eq_u32 s53, 12
	s_cselect_b32 s29, s19, s27
	s_cselect_b32 s28, s49, s26
	s_cselect_b32 s27, s17, s52
	s_cselect_b32 s26, s50, s51
	s_add_i32 m0, s25, 0xc000
	ds_read_b128 v[184:187], v153
	ds_read_b128 v[188:191], v153 offset:1024
	ds_read_b128 v[192:195], v153 offset:2048
	ds_read_b128 v[196:199], v153 offset:3072
	ds_read_b128 v[200:203], v153 offset:4096
	ds_read_b128 v[208:211], v153 offset:5120
	ds_read_b128 v[212:215], v153 offset:6144
	ds_read_b128 v[216:219], v153 offset:7168
	global_load_lds_dwordx4 v138, s[6:7]
	s_add_i32 m0, s25, 0xe000
	s_nop 0
	global_load_lds_dwordx4 v136, s[6:7]
	s_waitcnt vmcnt(8)
	s_waitcnt lgkmcnt(0)
	s_barrier
	s_waitcnt lgkmcnt(0)
	v_mfma_f32_16x16x32_bf16 v[124:127], v[144:147], v[184:187], v[124:127]
	v_mfma_f32_16x16x32_bf16 v[120:123], v[160:163], v[184:187], v[120:123]
	v_mfma_f32_16x16x32_bf16 v[108:111], v[144:147], v[192:195], v[108:111]
	v_mfma_f32_16x16x32_bf16 v[104:107], v[160:163], v[192:195], v[104:107]
	v_mfma_f32_16x16x32_bf16 v[92:95], v[144:147], v[200:203], v[92:95]
	v_mfma_f32_16x16x32_bf16 v[88:91], v[160:163], v[200:203], v[88:91]
	v_mfma_f32_16x16x32_bf16 v[76:79], v[144:147], v[212:215], v[76:79]
	v_mfma_f32_16x16x32_bf16 v[72:75], v[160:163], v[212:215], v[72:75]
	v_mfma_f32_16x16x32_bf16 v[124:127], v[156:159], v[188:191], v[124:127]
	v_mfma_f32_16x16x32_bf16 v[120:123], v[164:167], v[188:191], v[120:123]
	v_mfma_f32_16x16x32_bf16 v[108:111], v[156:159], v[196:199], v[108:111]
	v_mfma_f32_16x16x32_bf16 v[104:107], v[164:167], v[196:199], v[104:107]
	v_mfma_f32_16x16x32_bf16 v[92:95], v[156:159], v[208:211], v[92:95]
	v_mfma_f32_16x16x32_bf16 v[88:91], v[164:167], v[208:211], v[88:91]
	v_mfma_f32_16x16x32_bf16 v[76:79], v[156:159], v[216:219], v[76:79]
	v_mfma_f32_16x16x32_bf16 v[72:75], v[164:167], v[216:219], v[72:75]
	v_mfma_f32_16x16x32_bf16 v[116:119], v[168:171], v[184:187], v[116:119]
	v_mfma_f32_16x16x32_bf16 v[112:115], v[176:179], v[184:187], v[112:115]
	v_mfma_f32_16x16x32_bf16 v[100:103], v[168:171], v[192:195], v[100:103]
	v_mfma_f32_16x16x32_bf16 v[96:99], v[176:179], v[192:195], v[96:99]
	v_mfma_f32_16x16x32_bf16 v[84:87], v[168:171], v[200:203], v[84:87]
	v_mfma_f32_16x16x32_bf16 v[80:83], v[176:179], v[200:203], v[80:83]
	v_mfma_f32_16x16x32_bf16 v[68:71], v[168:171], v[212:215], v[68:71]
	v_mfma_f32_16x16x32_bf16 v[64:67], v[176:179], v[212:215], v[64:67]
	v_mfma_f32_16x16x32_bf16 v[116:119], v[172:175], v[188:191], v[116:119]
	v_mfma_f32_16x16x32_bf16 v[112:115], v[180:183], v[188:191], v[112:115]
	v_mfma_f32_16x16x32_bf16 v[100:103], v[172:175], v[196:199], v[100:103]
	v_mfma_f32_16x16x32_bf16 v[96:99], v[180:183], v[196:199], v[96:99]
	v_mfma_f32_16x16x32_bf16 v[84:87], v[172:175], v[208:211], v[84:87]
	v_mfma_f32_16x16x32_bf16 v[80:83], v[180:183], v[208:211], v[80:83]
	v_mfma_f32_16x16x32_bf16 v[68:71], v[172:175], v[216:219], v[68:71]
	v_mfma_f32_16x16x32_bf16 v[64:67], v[180:183], v[216:219], v[64:67]
	s_barrier
	s_add_i32 s54, s45, s38
	s_mov_b32 m0, s54
	ds_read_b128 v[184:187], v153 offset:16384
	ds_read_b128 v[188:191], v153 offset:17408
	ds_read_b128 v[192:195], v153 offset:18432
	ds_read_b128 v[196:199], v153 offset:19456
	ds_read_b128 v[200:203], v153 offset:20480
	ds_read_b128 v[208:211], v153 offset:21504
	ds_read_b128 v[212:215], v153 offset:22528
	ds_read_b128 v[216:219], v153 offset:23552
	global_load_lds_dwordx4 v130, s[26:27]
	s_add_i32 m0, s54, 0x2000
	s_add_u32 s54, s26, 0x40000
	s_mov_b64 s[98:99], s[26:27]
	s_addc_u32 s55, s27, 0
	s_add_i32 s56, s46, s38
	global_load_lds_dwordx4 v134, s[26:27]
	s_mov_b32 m0, s56
	s_mov_b64 s[100:101], s[28:29]
	global_load_lds_dwordx4 v130, s[54:55]
	s_add_i32 m0, s56, 0x2000
	s_nop 0
	global_load_lds_dwordx4 v134, s[54:55]
	s_mov_b32 m0, s25
	s_nop 0
	global_load_lds_dwordx4 v128, s[28:29]
	s_waitcnt vmcnt(7)
	s_waitcnt lgkmcnt(0)
	s_barrier
	s_waitcnt lgkmcnt(0)
	v_mfma_f32_16x16x32_bf16 v[60:63], v[144:147], v[184:187], v[60:63]
	v_mfma_f32_16x16x32_bf16 v[56:59], v[160:163], v[184:187], v[56:59]
	v_mfma_f32_16x16x32_bf16 v[44:47], v[144:147], v[192:195], v[44:47]
	v_mfma_f32_16x16x32_bf16 v[40:43], v[160:163], v[192:195], v[40:43]
	v_mfma_f32_16x16x32_bf16 v[28:31], v[144:147], v[200:203], v[28:31]
	v_mfma_f32_16x16x32_bf16 v[24:27], v[160:163], v[200:203], v[24:27]
	v_mfma_f32_16x16x32_bf16 v[12:15], v[144:147], v[212:215], v[12:15]
	v_mfma_f32_16x16x32_bf16 v[8:11], v[160:163], v[212:215], v[8:11]
	v_mfma_f32_16x16x32_bf16 v[60:63], v[156:159], v[188:191], v[60:63]
	v_mfma_f32_16x16x32_bf16 v[56:59], v[164:167], v[188:191], v[56:59]
	v_mfma_f32_16x16x32_bf16 v[44:47], v[156:159], v[196:199], v[44:47]
	v_mfma_f32_16x16x32_bf16 v[40:43], v[164:167], v[196:199], v[40:43]
	v_mfma_f32_16x16x32_bf16 v[28:31], v[156:159], v[208:211], v[28:31]
	v_mfma_f32_16x16x32_bf16 v[24:27], v[164:167], v[208:211], v[24:27]
	v_mfma_f32_16x16x32_bf16 v[12:15], v[156:159], v[216:219], v[12:15]
	v_mfma_f32_16x16x32_bf16 v[8:11], v[164:167], v[216:219], v[8:11]
	v_mfma_f32_16x16x32_bf16 v[52:55], v[168:171], v[184:187], v[52:55]
	v_mfma_f32_16x16x32_bf16 v[48:51], v[176:179], v[184:187], v[48:51]
	v_mfma_f32_16x16x32_bf16 v[36:39], v[168:171], v[192:195], v[36:39]
	v_mfma_f32_16x16x32_bf16 v[32:35], v[176:179], v[192:195], v[32:35]
	v_mfma_f32_16x16x32_bf16 v[20:23], v[168:171], v[200:203], v[20:23]
	v_mfma_f32_16x16x32_bf16 v[16:19], v[176:179], v[200:203], v[16:19]
	v_mfma_f32_16x16x32_bf16 v[4:7], v[168:171], v[212:215], v[4:7]
	v_mfma_f32_16x16x32_bf16 v[0:3], v[176:179], v[212:215], v[0:3]
	v_mfma_f32_16x16x32_bf16 v[52:55], v[172:175], v[188:191], v[52:55]
	v_mfma_f32_16x16x32_bf16 v[48:51], v[180:183], v[188:191], v[48:51]
	v_mfma_f32_16x16x32_bf16 v[36:39], v[172:175], v[196:199], v[36:39]
	v_mfma_f32_16x16x32_bf16 v[32:35], v[180:183], v[196:199], v[32:35]
	v_mfma_f32_16x16x32_bf16 v[20:23], v[172:175], v[208:211], v[20:23]
	v_mfma_f32_16x16x32_bf16 v[16:19], v[180:183], v[208:211], v[16:19]
	v_mfma_f32_16x16x32_bf16 v[4:7], v[172:175], v[216:219], v[4:7]
	v_mfma_f32_16x16x32_bf16 v[0:3], v[180:183], v[216:219], v[0:3]
	s_barrier
	s_mov_b32 m0, s39
	s_nop 0
	global_load_lds_dwordx4 v132, s[28:29]
	s_add_i32 s54, 0, 0x18000
	v_add_u32_e32 v155, s54, v149
	s_add_i32 s55, 0, 0x1c000
	ds_read_b128 v[144:147], v155
	ds_read_b128 v[156:159], v155 offset:1024
	ds_read_b128 v[160:163], v155 offset:2048
	ds_read_b128 v[164:167], v155 offset:3072
	v_add_u32_e32 v155, s55, v149
	ds_read_b128 v[168:171], v155
	ds_read_b128 v[172:175], v155 offset:1024
	ds_read_b128 v[176:179], v155 offset:2048
	ds_read_b128 v[180:183], v155 offset:3072
	s_add_u32 s28, s28, 0x40000
	s_addc_u32 s29, s29, 0
	s_mov_b32 m0, s40
	ds_read_b128 v[184:187], v153 offset:32768
	ds_read_b128 v[188:191], v153 offset:33792
	ds_read_b128 v[192:195], v153 offset:34816
	ds_read_b128 v[196:199], v153 offset:35840
	ds_read_b128 v[200:203], v153 offset:36864
	ds_read_b128 v[208:211], v153 offset:37888
	ds_read_b128 v[212:215], v153 offset:38912
	ds_read_b128 v[216:219], v153 offset:39936
	global_load_lds_dwordx4 v128, s[28:29]
	s_mov_b32 m0, s41
	s_nop 0
	global_load_lds_dwordx4 v132, s[28:29]
	s_waitcnt vmcnt(8)
	s_waitcnt lgkmcnt(0)
	s_barrier
	s_waitcnt lgkmcnt(0)
	v_mfma_f32_16x16x32_bf16 v[124:127], v[144:147], v[184:187], v[124:127]
	v_mfma_f32_16x16x32_bf16 v[120:123], v[160:163], v[184:187], v[120:123]
	v_mfma_f32_16x16x32_bf16 v[108:111], v[144:147], v[192:195], v[108:111]
	v_mfma_f32_16x16x32_bf16 v[104:107], v[160:163], v[192:195], v[104:107]
	v_mfma_f32_16x16x32_bf16 v[92:95], v[144:147], v[200:203], v[92:95]
	v_mfma_f32_16x16x32_bf16 v[88:91], v[160:163], v[200:203], v[88:91]
	v_mfma_f32_16x16x32_bf16 v[76:79], v[144:147], v[212:215], v[76:79]
	v_mfma_f32_16x16x32_bf16 v[72:75], v[160:163], v[212:215], v[72:75]
	v_mfma_f32_16x16x32_bf16 v[124:127], v[156:159], v[188:191], v[124:127]
	v_mfma_f32_16x16x32_bf16 v[120:123], v[164:167], v[188:191], v[120:123]
	v_mfma_f32_16x16x32_bf16 v[108:111], v[156:159], v[196:199], v[108:111]
	v_mfma_f32_16x16x32_bf16 v[104:107], v[164:167], v[196:199], v[104:107]
	v_mfma_f32_16x16x32_bf16 v[92:95], v[156:159], v[208:211], v[92:95]
	v_mfma_f32_16x16x32_bf16 v[88:91], v[164:167], v[208:211], v[88:91]
	v_mfma_f32_16x16x32_bf16 v[76:79], v[156:159], v[216:219], v[76:79]
	v_mfma_f32_16x16x32_bf16 v[72:75], v[164:167], v[216:219], v[72:75]
	v_mfma_f32_16x16x32_bf16 v[116:119], v[168:171], v[184:187], v[116:119]
	v_mfma_f32_16x16x32_bf16 v[112:115], v[176:179], v[184:187], v[112:115]
	v_mfma_f32_16x16x32_bf16 v[100:103], v[168:171], v[192:195], v[100:103]
	v_mfma_f32_16x16x32_bf16 v[96:99], v[176:179], v[192:195], v[96:99]
	v_mfma_f32_16x16x32_bf16 v[84:87], v[168:171], v[200:203], v[84:87]
	v_mfma_f32_16x16x32_bf16 v[80:83], v[176:179], v[200:203], v[80:83]
	v_mfma_f32_16x16x32_bf16 v[68:71], v[168:171], v[212:215], v[68:71]
	v_mfma_f32_16x16x32_bf16 v[64:67], v[176:179], v[212:215], v[64:67]
	v_mfma_f32_16x16x32_bf16 v[116:119], v[172:175], v[188:191], v[116:119]
	v_mfma_f32_16x16x32_bf16 v[112:115], v[180:183], v[188:191], v[112:115]
	v_mfma_f32_16x16x32_bf16 v[100:103], v[172:175], v[196:199], v[100:103]
	v_mfma_f32_16x16x32_bf16 v[96:99], v[180:183], v[196:199], v[96:99]
	v_mfma_f32_16x16x32_bf16 v[84:87], v[172:175], v[208:211], v[84:87]
	v_mfma_f32_16x16x32_bf16 v[80:83], v[180:183], v[208:211], v[80:83]
	v_mfma_f32_16x16x32_bf16 v[68:71], v[172:175], v[216:219], v[68:71]
	v_mfma_f32_16x16x32_bf16 v[64:67], v[180:183], v[216:219], v[64:67]
	s_barrier
	s_add_i32 s28, s54, s38
	s_mov_b32 m0, s28
	ds_read_b128 v[184:187], v153 offset:49152
	ds_read_b128 v[188:191], v153 offset:50176
	ds_read_b128 v[192:195], v153 offset:51200
	ds_read_b128 v[196:199], v153 offset:52224
	ds_read_b128 v[200:203], v153 offset:53248
	ds_read_b128 v[208:211], v153 offset:54272
	ds_read_b128 v[212:215], v153 offset:55296
	ds_read_b128 v[216:219], v153 offset:56320
	global_load_lds_dwordx4 v205, s[26:27]
	s_add_i32 m0, s28, 0x2000
	s_add_u32 s26, s26, 0x40080
	s_addc_u32 s27, s27, 0
	s_add_i32 s28, s55, s38
	global_load_lds_dwordx4 v221, s[98:99]
	s_mov_b32 m0, s28
	s_nop 0
	global_load_lds_dwordx4 v130, s[26:27]
	s_add_i32 m0, s28, 0x2000
	s_nop 0
	global_load_lds_dwordx4 v134, s[26:27]
	s_mov_b32 m0, s43
	s_nop 0
	global_load_lds_dwordx4 v204, s[100:101]
	s_cmp_lg_u32 s53, 12
	s_cbranch_scc1 .Lbal_last_16
	s_mov_b32 m0, s44
	s_nop 0
	global_load_lds_dwordx4 v220, s[100:101]
.Lbal_last_16:
	s_waitcnt vmcnt(7)
	s_waitcnt lgkmcnt(0)
	s_barrier
	s_waitcnt lgkmcnt(0)
	v_mfma_f32_16x16x32_bf16 v[60:63], v[144:147], v[184:187], v[60:63]
	v_mfma_f32_16x16x32_bf16 v[56:59], v[160:163], v[184:187], v[56:59]
	v_mfma_f32_16x16x32_bf16 v[44:47], v[144:147], v[192:195], v[44:47]
	v_mfma_f32_16x16x32_bf16 v[40:43], v[160:163], v[192:195], v[40:43]
	v_mfma_f32_16x16x32_bf16 v[28:31], v[144:147], v[200:203], v[28:31]
	v_mfma_f32_16x16x32_bf16 v[24:27], v[160:163], v[200:203], v[24:27]
	v_mfma_f32_16x16x32_bf16 v[12:15], v[144:147], v[212:215], v[12:15]
	v_mfma_f32_16x16x32_bf16 v[8:11], v[160:163], v[212:215], v[8:11]
	v_mfma_f32_16x16x32_bf16 v[60:63], v[156:159], v[188:191], v[60:63]
	v_mfma_f32_16x16x32_bf16 v[56:59], v[164:167], v[188:191], v[56:59]
	v_mfma_f32_16x16x32_bf16 v[44:47], v[156:159], v[196:199], v[44:47]
	v_mfma_f32_16x16x32_bf16 v[40:43], v[164:167], v[196:199], v[40:43]
	v_mfma_f32_16x16x32_bf16 v[28:31], v[156:159], v[208:211], v[28:31]
	v_mfma_f32_16x16x32_bf16 v[24:27], v[164:167], v[208:211], v[24:27]
	v_mfma_f32_16x16x32_bf16 v[12:15], v[156:159], v[216:219], v[12:15]
	v_mfma_f32_16x16x32_bf16 v[8:11], v[164:167], v[216:219], v[8:11]
	v_mfma_f32_16x16x32_bf16 v[52:55], v[168:171], v[184:187], v[52:55]
	v_mfma_f32_16x16x32_bf16 v[48:51], v[176:179], v[184:187], v[48:51]
	v_mfma_f32_16x16x32_bf16 v[36:39], v[168:171], v[192:195], v[36:39]
	v_mfma_f32_16x16x32_bf16 v[32:35], v[176:179], v[192:195], v[32:35]
	v_mfma_f32_16x16x32_bf16 v[20:23], v[168:171], v[200:203], v[20:23]
	v_mfma_f32_16x16x32_bf16 v[16:19], v[176:179], v[200:203], v[16:19]
	v_mfma_f32_16x16x32_bf16 v[4:7], v[168:171], v[212:215], v[4:7]
	v_mfma_f32_16x16x32_bf16 v[0:3], v[176:179], v[212:215], v[0:3]
	v_mfma_f32_16x16x32_bf16 v[52:55], v[172:175], v[188:191], v[52:55]
	v_mfma_f32_16x16x32_bf16 v[48:51], v[180:183], v[188:191], v[48:51]
	v_mfma_f32_16x16x32_bf16 v[36:39], v[172:175], v[196:199], v[36:39]
	v_mfma_f32_16x16x32_bf16 v[32:35], v[180:183], v[196:199], v[32:35]
	v_mfma_f32_16x16x32_bf16 v[20:23], v[172:175], v[208:211], v[20:23]
	v_mfma_f32_16x16x32_bf16 v[16:19], v[180:183], v[208:211], v[16:19]
	v_mfma_f32_16x16x32_bf16 v[4:7], v[172:175], v[216:219], v[4:7]
	v_mfma_f32_16x16x32_bf16 v[0:3], v[180:183], v[216:219], v[0:3]
	s_barrier
	s_add_i32 s53, s53, 2
	s_add_u32 s51, s51, 0x100
	s_addc_u32 s52, s52, 0
	s_add_u32 s6, s6, 0x100
	s_addc_u32 s7, s7, 0
	s_cmp_gt_u32 s53, 13
	s_cbranch_scc0 .LBB0_988
	s_setprio 0
	s_and_b64 vcc, exec, s[14:15]
	s_cbranch_vccz .LBB0_991
	s_barrier

.LBB0_1193:
	s_cmp_eq_i32 s50, -2
	s_cbranch_scc1 .Lbal_first_15
	s_mov_b32 m0, s42
	s_nop 0
	global_load_lds_dwordx4 v218, s[100:101]
.Lbal_first_15:
	ds_read_b128 v[144:147], v151
	ds_read_b128 v[154:157], v151 offset:1024
	ds_read_b128 v[158:161], v151 offset:2048
	ds_read_b128 v[162:165], v151 offset:3072
	ds_read_b128 v[166:169], v152
	ds_read_b128 v[170:173], v152 offset:1024
	ds_read_b128 v[174:177], v152 offset:2048
	ds_read_b128 v[178:181], v152 offset:3072
	s_add_u32 s26, s24, 0xfffe0080
	s_addc_u32 s27, s25, -1
	s_cmp_eq_u32 s50, 4
	s_cselect_b32 s29, s17, s27
	s_cselect_b32 s28, s46, s26
	s_cselect_b32 s27, s15, s49
	s_cselect_b32 s26, s47, s48
	s_add_i32 m0, s23, 0xc000
	ds_read_b128 v[182:185], v153
	ds_read_b128 v[186:189], v153 offset:1024
	ds_read_b128 v[190:193], v153 offset:2048
	ds_read_b128 v[194:197], v153 offset:3072
	ds_read_b128 v[198:201], v153 offset:4096
	ds_read_b128 v[202:205], v153 offset:5120
	ds_read_b128 v[208:211], v153 offset:6144
	ds_read_b128 v[212:215], v153 offset:7168
	global_load_lds_dwordx4 v138, s[24:25]
	s_add_i32 m0, s23, 0xe000
	s_nop 0
	global_load_lds_dwordx4 v136, s[24:25]
	s_waitcnt vmcnt(8)
	s_waitcnt lgkmcnt(0)
	s_barrier
	s_waitcnt lgkmcnt(0)
	v_mfma_f32_16x16x32_bf16 v[124:127], v[144:147], v[182:185], v[124:127]
	v_mfma_f32_16x16x32_bf16 v[120:123], v[158:161], v[182:185], v[120:123]
	v_mfma_f32_16x16x32_bf16 v[108:111], v[144:147], v[190:193], v[108:111]
	v_mfma_f32_16x16x32_bf16 v[104:107], v[158:161], v[190:193], v[104:107]
	v_mfma_f32_16x16x32_bf16 v[92:95], v[144:147], v[198:201], v[92:95]
	v_mfma_f32_16x16x32_bf16 v[88:91], v[158:161], v[198:201], v[88:91]
	v_mfma_f32_16x16x32_bf16 v[76:79], v[144:147], v[208:211], v[76:79]
	v_mfma_f32_16x16x32_bf16 v[72:75], v[158:161], v[208:211], v[72:75]
	v_mfma_f32_16x16x32_bf16 v[124:127], v[154:157], v[186:189], v[124:127]
	v_mfma_f32_16x16x32_bf16 v[120:123], v[162:165], v[186:189], v[120:123]
	v_mfma_f32_16x16x32_bf16 v[108:111], v[154:157], v[194:197], v[108:111]
	v_mfma_f32_16x16x32_bf16 v[104:107], v[162:165], v[194:197], v[104:107]
	v_mfma_f32_16x16x32_bf16 v[92:95], v[154:157], v[202:205], v[92:95]
	v_mfma_f32_16x16x32_bf16 v[88:91], v[162:165], v[202:205], v[88:91]
	v_mfma_f32_16x16x32_bf16 v[76:79], v[154:157], v[212:215], v[76:79]
	v_mfma_f32_16x16x32_bf16 v[72:75], v[162:165], v[212:215], v[72:75]
	v_mfma_f32_16x16x32_bf16 v[116:119], v[166:169], v[182:185], v[116:119]
	v_mfma_f32_16x16x32_bf16 v[112:115], v[174:177], v[182:185], v[112:115]
	v_mfma_f32_16x16x32_bf16 v[100:103], v[166:169], v[190:193], v[100:103]
	v_mfma_f32_16x16x32_bf16 v[96:99], v[174:177], v[190:193], v[96:99]
	v_mfma_f32_16x16x32_bf16 v[84:87], v[166:169], v[198:201], v[84:87]
	v_mfma_f32_16x16x32_bf16 v[80:83], v[174:177], v[198:201], v[80:83]
	v_mfma_f32_16x16x32_bf16 v[68:71], v[166:169], v[208:211], v[68:71]
	v_mfma_f32_16x16x32_bf16 v[64:67], v[174:177], v[208:211], v[64:67]
	v_mfma_f32_16x16x32_bf16 v[116:119], v[170:173], v[186:189], v[116:119]
	v_mfma_f32_16x16x32_bf16 v[112:115], v[178:181], v[186:189], v[112:115]
	v_mfma_f32_16x16x32_bf16 v[100:103], v[170:173], v[194:197], v[100:103]
	v_mfma_f32_16x16x32_bf16 v[96:99], v[178:181], v[194:197], v[96:99]
	v_mfma_f32_16x16x32_bf16 v[84:87], v[170:173], v[202:205], v[84:87]
	v_mfma_f32_16x16x32_bf16 v[80:83], v[178:181], v[202:205], v[80:83]
	v_mfma_f32_16x16x32_bf16 v[68:71], v[170:173], v[212:215], v[68:71]
	v_mfma_f32_16x16x32_bf16 v[64:67], v[178:181], v[212:215], v[64:67]
	s_barrier
	s_add_i32 s51, s43, s36
	s_mov_b32 m0, s51
	ds_read_b128 v[182:185], v153 offset:16384
	ds_read_b128 v[186:189], v153 offset:17408
	ds_read_b128 v[190:193], v153 offset:18432
	ds_read_b128 v[194:197], v153 offset:19456
	ds_read_b128 v[198:201], v153 offset:20480
	ds_read_b128 v[202:205], v153 offset:21504
	ds_read_b128 v[208:211], v153 offset:22528
	ds_read_b128 v[212:215], v153 offset:23552
	global_load_lds_dwordx4 v130, s[26:27]
	s_add_i32 m0, s51, 0x2000
	s_add_u32 s52, s26, 0x20000
	s_mov_b64 s[98:99], s[26:27]
	s_addc_u32 s53, s27, 0
	s_add_i32 s51, s44, s36
	global_load_lds_dwordx4 v134, s[26:27]
	s_mov_b32 m0, s51
	s_mov_b64 s[100:101], s[28:29]
	global_load_lds_dwordx4 v130, s[52:53]
	s_add_i32 m0, s51, 0x2000
	s_nop 0
	global_load_lds_dwordx4 v134, s[52:53]
	s_mov_b32 m0, s23
	s_nop 0
	global_load_lds_dwordx4 v128, s[28:29]
	s_waitcnt vmcnt(7)
	s_waitcnt lgkmcnt(0)
	s_barrier
	s_waitcnt lgkmcnt(0)
	v_mfma_f32_16x16x32_bf16 v[60:63], v[144:147], v[182:185], v[60:63]
	v_mfma_f32_16x16x32_bf16 v[56:59], v[158:161], v[182:185], v[56:59]
	v_mfma_f32_16x16x32_bf16 v[44:47], v[144:147], v[190:193], v[44:47]
	v_mfma_f32_16x16x32_bf16 v[40:43], v[158:161], v[190:193], v[40:43]
	v_mfma_f32_16x16x32_bf16 v[28:31], v[144:147], v[198:201], v[28:31]
	v_mfma_f32_16x16x32_bf16 v[24:27], v[158:161], v[198:201], v[24:27]
	v_mfma_f32_16x16x32_bf16 v[12:15], v[144:147], v[208:211], v[12:15]
	v_mfma_f32_16x16x32_bf16 v[8:11], v[158:161], v[208:211], v[8:11]
	v_mfma_f32_16x16x32_bf16 v[60:63], v[154:157], v[186:189], v[60:63]
	v_mfma_f32_16x16x32_bf16 v[56:59], v[162:165], v[186:189], v[56:59]
	v_mfma_f32_16x16x32_bf16 v[44:47], v[154:157], v[194:197], v[44:47]
	v_mfma_f32_16x16x32_bf16 v[40:43], v[162:165], v[194:197], v[40:43]
	v_mfma_f32_16x16x32_bf16 v[28:31], v[154:157], v[202:205], v[28:31]
	v_mfma_f32_16x16x32_bf16 v[24:27], v[162:165], v[202:205], v[24:27]
	v_mfma_f32_16x16x32_bf16 v[12:15], v[154:157], v[212:215], v[12:15]
	v_mfma_f32_16x16x32_bf16 v[8:11], v[162:165], v[212:215], v[8:11]
	v_mfma_f32_16x16x32_bf16 v[52:55], v[166:169], v[182:185], v[52:55]
	v_mfma_f32_16x16x32_bf16 v[48:51], v[174:177], v[182:185], v[48:51]
	v_mfma_f32_16x16x32_bf16 v[36:39], v[166:169], v[190:193], v[36:39]
	v_mfma_f32_16x16x32_bf16 v[32:35], v[174:177], v[190:193], v[32:35]
	v_mfma_f32_16x16x32_bf16 v[20:23], v[166:169], v[198:201], v[20:23]
	v_mfma_f32_16x16x32_bf16 v[16:19], v[174:177], v[198:201], v[16:19]
	v_mfma_f32_16x16x32_bf16 v[4:7], v[166:169], v[208:211], v[4:7]
	v_mfma_f32_16x16x32_bf16 v[0:3], v[174:177], v[208:211], v[0:3]
	v_mfma_f32_16x16x32_bf16 v[52:55], v[170:173], v[186:189], v[52:55]
	v_mfma_f32_16x16x32_bf16 v[48:51], v[178:181], v[186:189], v[48:51]
	v_mfma_f32_16x16x32_bf16 v[36:39], v[170:173], v[194:197], v[36:39]
	v_mfma_f32_16x16x32_bf16 v[32:35], v[178:181], v[194:197], v[32:35]
	v_mfma_f32_16x16x32_bf16 v[20:23], v[170:173], v[202:205], v[20:23]
	v_mfma_f32_16x16x32_bf16 v[16:19], v[178:181], v[202:205], v[16:19]
	v_mfma_f32_16x16x32_bf16 v[4:7], v[170:173], v[212:215], v[4:7]
	v_mfma_f32_16x16x32_bf16 v[0:3], v[178:181], v[212:215], v[0:3]
	s_barrier
	s_mov_b32 m0, s37
	s_nop 0
	global_load_lds_dwordx4 v132, s[28:29]
	s_add_i32 s51, 0, 0x18000
	s_add_i32 s52, 0, 0x1c000
	v_add_u32_e32 v162, s51, v149
	v_add_u32_e32 v178, s52, v149
	ds_read_b128 v[144:147], v162
	ds_read_b128 v[154:157], v162 offset:1024
	ds_read_b128 v[158:161], v162 offset:2048
	ds_read_b128 v[162:165], v162 offset:3072
	ds_read_b128 v[166:169], v178
	ds_read_b128 v[170:173], v178 offset:1024
	ds_read_b128 v[174:177], v178 offset:2048
	ds_read_b128 v[178:181], v178 offset:3072
	s_add_u32 s28, s28, 0x20000
	s_addc_u32 s29, s29, 0
	s_mov_b32 m0, s38
	ds_read_b128 v[182:185], v153 offset:32768
	ds_read_b128 v[186:189], v153 offset:33792
	ds_read_b128 v[190:193], v153 offset:34816
	ds_read_b128 v[194:197], v153 offset:35840
	ds_read_b128 v[198:201], v153 offset:36864
	ds_read_b128 v[202:205], v153 offset:37888
	ds_read_b128 v[208:211], v153 offset:38912
	ds_read_b128 v[212:215], v153 offset:39936
	global_load_lds_dwordx4 v128, s[28:29]
	s_mov_b32 m0, s39
	s_nop 0
	global_load_lds_dwordx4 v132, s[28:29]
	s_waitcnt vmcnt(8)
	s_waitcnt lgkmcnt(0)
	s_barrier
	s_waitcnt lgkmcnt(0)
	v_mfma_f32_16x16x32_bf16 v[124:127], v[144:147], v[182:185], v[124:127]
	v_mfma_f32_16x16x32_bf16 v[120:123], v[158:161], v[182:185], v[120:123]
	v_mfma_f32_16x16x32_bf16 v[108:111], v[144:147], v[190:193], v[108:111]
	v_mfma_f32_16x16x32_bf16 v[104:107], v[158:161], v[190:193], v[104:107]
	v_mfma_f32_16x16x32_bf16 v[92:95], v[144:147], v[198:201], v[92:95]
	v_mfma_f32_16x16x32_bf16 v[88:91], v[158:161], v[198:201], v[88:91]
	v_mfma_f32_16x16x32_bf16 v[76:79], v[144:147], v[208:211], v[76:79]
	v_mfma_f32_16x16x32_bf16 v[72:75], v[158:161], v[208:211], v[72:75]
	v_mfma_f32_16x16x32_bf16 v[124:127], v[154:157], v[186:189], v[124:127]
	v_mfma_f32_16x16x32_bf16 v[120:123], v[162:165], v[186:189], v[120:123]
	v_mfma_f32_16x16x32_bf16 v[108:111], v[154:157], v[194:197], v[108:111]
	v_mfma_f32_16x16x32_bf16 v[104:107], v[162:165], v[194:197], v[104:107]
	v_mfma_f32_16x16x32_bf16 v[92:95], v[154:157], v[202:205], v[92:95]
	v_mfma_f32_16x16x32_bf16 v[88:91], v[162:165], v[202:205], v[88:91]
	v_mfma_f32_16x16x32_bf16 v[76:79], v[154:157], v[212:215], v[76:79]
	v_mfma_f32_16x16x32_bf16 v[72:75], v[162:165], v[212:215], v[72:75]
	v_mfma_f32_16x16x32_bf16 v[116:119], v[166:169], v[182:185], v[116:119]
	v_mfma_f32_16x16x32_bf16 v[112:115], v[174:177], v[182:185], v[112:115]
	v_mfma_f32_16x16x32_bf16 v[100:103], v[166:169], v[190:193], v[100:103]
	v_mfma_f32_16x16x32_bf16 v[96:99], v[174:177], v[190:193], v[96:99]
	v_mfma_f32_16x16x32_bf16 v[84:87], v[166:169], v[198:201], v[84:87]
	v_mfma_f32_16x16x32_bf16 v[80:83], v[174:177], v[198:201], v[80:83]
	v_mfma_f32_16x16x32_bf16 v[68:71], v[166:169], v[208:211], v[68:71]
	v_mfma_f32_16x16x32_bf16 v[64:67], v[174:177], v[208:211], v[64:67]
	v_mfma_f32_16x16x32_bf16 v[116:119], v[170:173], v[186:189], v[116:119]
	v_mfma_f32_16x16x32_bf16 v[112:115], v[178:181], v[186:189], v[112:115]
	v_mfma_f32_16x16x32_bf16 v[100:103], v[170:173], v[194:197], v[100:103]
	v_mfma_f32_16x16x32_bf16 v[96:99], v[178:181], v[194:197], v[96:99]
	v_mfma_f32_16x16x32_bf16 v[84:87], v[170:173], v[202:205], v[84:87]
	v_mfma_f32_16x16x32_bf16 v[80:83], v[178:181], v[202:205], v[80:83]
	v_mfma_f32_16x16x32_bf16 v[68:71], v[170:173], v[212:215], v[68:71]
	v_mfma_f32_16x16x32_bf16 v[64:67], v[178:181], v[212:215], v[64:67]
	s_barrier
	s_add_i32 s28, s51, s36
	s_mov_b32 m0, s28
	ds_read_b128 v[182:185], v153 offset:49152
	ds_read_b128 v[186:189], v153 offset:50176
	ds_read_b128 v[190:193], v153 offset:51200
	ds_read_b128 v[194:197], v153 offset:52224
	ds_read_b128 v[198:201], v153 offset:53248
	ds_read_b128 v[202:205], v153 offset:54272
	ds_read_b128 v[208:211], v153 offset:55296
	ds_read_b128 v[212:215], v153 offset:56320
	global_load_lds_dwordx4 v217, s[26:27]
	s_add_i32 m0, s28, 0x2000
	s_add_u32 s26, s26, 0x20080
	s_addc_u32 s27, s27, 0
	s_add_i32 s28, s52, s36
	global_load_lds_dwordx4 v219, s[98:99]
	s_mov_b32 m0, s28
	s_nop 0
	global_load_lds_dwordx4 v130, s[26:27]
	s_add_i32 m0, s28, 0x2000
	s_nop 0
	global_load_lds_dwordx4 v134, s[26:27]
	s_mov_b32 m0, s41
	s_nop 0
	global_load_lds_dwordx4 v216, s[100:101]
	s_cmp_lg_u32 s50, 4
	s_cbranch_scc1 .Lbal_last_15
	s_mov_b32 m0, s42
	s_nop 0
	global_load_lds_dwordx4 v218, s[100:101]
.Lbal_last_15:
	s_waitcnt vmcnt(7)
	s_waitcnt lgkmcnt(0)
	s_barrier
	s_waitcnt lgkmcnt(0)
	v_mfma_f32_16x16x32_bf16 v[60:63], v[144:147], v[182:185], v[60:63]
	v_mfma_f32_16x16x32_bf16 v[56:59], v[158:161], v[182:185], v[56:59]
	v_mfma_f32_16x16x32_bf16 v[44:47], v[144:147], v[190:193], v[44:47]
	v_mfma_f32_16x16x32_bf16 v[40:43], v[158:161], v[190:193], v[40:43]
	v_mfma_f32_16x16x32_bf16 v[28:31], v[144:147], v[198:201], v[28:31]
	v_mfma_f32_16x16x32_bf16 v[24:27], v[158:161], v[198:201], v[24:27]
	v_mfma_f32_16x16x32_bf16 v[12:15], v[144:147], v[208:211], v[12:15]
	v_mfma_f32_16x16x32_bf16 v[8:11], v[158:161], v[208:211], v[8:11]
	v_mfma_f32_16x16x32_bf16 v[60:63], v[154:157], v[186:189], v[60:63]
	v_mfma_f32_16x16x32_bf16 v[56:59], v[162:165], v[186:189], v[56:59]
	v_mfma_f32_16x16x32_bf16 v[44:47], v[154:157], v[194:197], v[44:47]
	v_mfma_f32_16x16x32_bf16 v[40:43], v[162:165], v[194:197], v[40:43]
	v_mfma_f32_16x16x32_bf16 v[28:31], v[154:157], v[202:205], v[28:31]
	v_mfma_f32_16x16x32_bf16 v[24:27], v[162:165], v[202:205], v[24:27]
	v_mfma_f32_16x16x32_bf16 v[12:15], v[154:157], v[212:215], v[12:15]
	v_mfma_f32_16x16x32_bf16 v[8:11], v[162:165], v[212:215], v[8:11]
	v_mfma_f32_16x16x32_bf16 v[52:55], v[166:169], v[182:185], v[52:55]
	v_mfma_f32_16x16x32_bf16 v[48:51], v[174:177], v[182:185], v[48:51]
	v_mfma_f32_16x16x32_bf16 v[36:39], v[166:169], v[190:193], v[36:39]
	v_mfma_f32_16x16x32_bf16 v[32:35], v[174:177], v[190:193], v[32:35]
	v_mfma_f32_16x16x32_bf16 v[20:23], v[166:169], v[198:201], v[20:23]
	v_mfma_f32_16x16x32_bf16 v[16:19], v[174:177], v[198:201], v[16:19]
	v_mfma_f32_16x16x32_bf16 v[4:7], v[166:169], v[208:211], v[4:7]
	v_mfma_f32_16x16x32_bf16 v[0:3], v[174:177], v[208:211], v[0:3]
	v_mfma_f32_16x16x32_bf16 v[52:55], v[170:173], v[186:189], v[52:55]
	v_mfma_f32_16x16x32_bf16 v[48:51], v[178:181], v[186:189], v[48:51]
	v_mfma_f32_16x16x32_bf16 v[36:39], v[170:173], v[194:197], v[36:39]
	v_mfma_f32_16x16x32_bf16 v[32:35], v[178:181], v[194:197], v[32:35]
	v_mfma_f32_16x16x32_bf16 v[20:23], v[170:173], v[202:205], v[20:23]
	v_mfma_f32_16x16x32_bf16 v[16:19], v[178:181], v[202:205], v[16:19]
	v_mfma_f32_16x16x32_bf16 v[4:7], v[170:173], v[212:215], v[4:7]
	v_mfma_f32_16x16x32_bf16 v[0:3], v[178:181], v[212:215], v[0:3]
	s_barrier
	s_add_i32 s50, s50, 2
	s_add_u32 s48, s48, 0x100
	s_addc_u32 s49, s49, 0
	s_add_u32 s24, s24, 0x100
	s_addc_u32 s25, s25, 0
	s_cmp_gt_u32 s50, 5
	s_cbranch_scc0 .LBB0_1193
	s_setprio 0
	s_and_b64 vcc, exec, s[12:13]
	s_cbranch_vccz .LBB0_1196
	s_barrier

.Lbal_first_13:
	ds_read_b128 v[144:147], v151
	ds_read_b128 v[156:159], v151 offset:1024
	ds_read_b128 v[160:163], v151 offset:2048
	ds_read_b128 v[164:167], v151 offset:3072
	ds_read_b128 v[168:171], v152
	ds_read_b128 v[172:175], v152 offset:1024
	ds_read_b128 v[176:179], v152 offset:2048
	ds_read_b128 v[180:183], v152 offset:3072
	s_add_u32 s26, s24, 0xfffc0080
	s_addc_u32 s27, s25, -1
	s_cmp_eq_u32 s53, 12
	s_cselect_b32 s29, s19, s27
	s_cselect_b32 s28, s49, s26
	s_cselect_b32 s27, s17, s52
	s_cselect_b32 s26, s50, s51
	s_add_i32 m0, s39, 0xc000
	ds_read_b128 v[184:187], v153
	ds_read_b128 v[188:191], v153 offset:1024
	ds_read_b128 v[192:195], v153 offset:2048
	ds_read_b128 v[196:199], v153 offset:3072
	ds_read_b128 v[200:203], v153 offset:4096
	ds_read_b128 v[208:211], v153 offset:5120
	ds_read_b128 v[212:215], v153 offset:6144
	ds_read_b128 v[216:219], v153 offset:7168
	global_load_lds_dwordx4 v138, s[24:25]
	s_add_i32 m0, s39, 0xe000
	s_nop 0
	global_load_lds_dwordx4 v136, s[24:25]
	s_waitcnt vmcnt(8)
	s_waitcnt lgkmcnt(0)
	s_barrier
	s_waitcnt lgkmcnt(0)
	v_mfma_f32_16x16x32_bf16 v[124:127], v[144:147], v[184:187], v[124:127]
	v_mfma_f32_16x16x32_bf16 v[120:123], v[160:163], v[184:187], v[120:123]
	v_mfma_f32_16x16x32_bf16 v[108:111], v[144:147], v[192:195], v[108:111]
	v_mfma_f32_16x16x32_bf16 v[104:107], v[160:163], v[192:195], v[104:107]
	v_mfma_f32_16x16x32_bf16 v[92:95], v[144:147], v[200:203], v[92:95]
	v_mfma_f32_16x16x32_bf16 v[88:91], v[160:163], v[200:203], v[88:91]
	v_mfma_f32_16x16x32_bf16 v[76:79], v[144:147], v[212:215], v[76:79]
	v_mfma_f32_16x16x32_bf16 v[72:75], v[160:163], v[212:215], v[72:75]
	v_mfma_f32_16x16x32_bf16 v[124:127], v[156:159], v[188:191], v[124:127]
	v_mfma_f32_16x16x32_bf16 v[120:123], v[164:167], v[188:191], v[120:123]
	v_mfma_f32_16x16x32_bf16 v[108:111], v[156:159], v[196:199], v[108:111]
	v_mfma_f32_16x16x32_bf16 v[104:107], v[164:167], v[196:199], v[104:107]
	v_mfma_f32_16x16x32_bf16 v[92:95], v[156:159], v[208:211], v[92:95]
	v_mfma_f32_16x16x32_bf16 v[88:91], v[164:167], v[208:211], v[88:91]
	v_mfma_f32_16x16x32_bf16 v[76:79], v[156:159], v[216:219], v[76:79]
	v_mfma_f32_16x16x32_bf16 v[72:75], v[164:167], v[216:219], v[72:75]
	v_mfma_f32_16x16x32_bf16 v[116:119], v[168:171], v[184:187], v[116:119]
	v_mfma_f32_16x16x32_bf16 v[112:115], v[176:179], v[184:187], v[112:115]
	v_mfma_f32_16x16x32_bf16 v[100:103], v[168:171], v[192:195], v[100:103]
	v_mfma_f32_16x16x32_bf16 v[96:99], v[176:179], v[192:195], v[96:99]
	v_mfma_f32_16x16x32_bf16 v[84:87], v[168:171], v[200:203], v[84:87]
	v_mfma_f32_16x16x32_bf16 v[80:83], v[176:179], v[200:203], v[80:83]
	v_mfma_f32_16x16x32_bf16 v[68:71], v[168:171], v[212:215], v[68:71]
	v_mfma_f32_16x16x32_bf16 v[64:67], v[176:179], v[212:215], v[64:67]
	v_mfma_f32_16x16x32_bf16 v[116:119], v[172:175], v[188:191], v[116:119]
	v_mfma_f32_16x16x32_bf16 v[112:115], v[180:183], v[188:191], v[112:115]
	v_mfma_f32_16x16x32_bf16 v[100:103], v[172:175], v[196:199], v[100:103]
	v_mfma_f32_16x16x32_bf16 v[96:99], v[180:183], v[196:199], v[96:99]
	v_mfma_f32_16x16x32_bf16 v[84:87], v[172:175], v[208:211], v[84:87]
	v_mfma_f32_16x16x32_bf16 v[80:83], v[180:183], v[208:211], v[80:83]
	v_mfma_f32_16x16x32_bf16 v[68:71], v[172:175], v[216:219], v[68:71]
	v_mfma_f32_16x16x32_bf16 v[64:67], v[180:183], v[216:219], v[64:67]
	s_barrier
	s_add_i32 s54, s46, s38
	s_mov_b32 m0, s54
	ds_read_b128 v[184:187], v153 offset:16384
	ds_read_b128 v[188:191], v153 offset:17408
	ds_read_b128 v[192:195], v153 offset:18432
	ds_read_b128 v[196:199], v153 offset:19456
	ds_read_b128 v[200:203], v153 offset:20480
	ds_read_b128 v[208:211], v153 offset:21504
	ds_read_b128 v[212:215], v153 offset:22528
	ds_read_b128 v[216:219], v153 offset:23552
	global_load_lds_dwordx4 v130, s[26:27]
	s_add_i32 m0, s54, 0x2000
	s_add_u32 s54, s26, 0x40000
	s_mov_b64 s[98:99], s[26:27]
	s_addc_u32 s55, s27, 0
	s_add_i32 s56, s47, s38
	global_load_lds_dwordx4 v134, s[26:27]
	s_mov_b32 m0, s56
	s_mov_b64 s[100:101], s[28:29]
	global_load_lds_dwordx4 v130, s[54:55]
	s_add_i32 m0, s56, 0x2000
	s_nop 0
	global_load_lds_dwordx4 v134, s[54:55]
	s_mov_b32 m0, s39
	s_nop 0
	global_load_lds_dwordx4 v128, s[28:29]
	s_waitcnt vmcnt(7)
	s_waitcnt lgkmcnt(0)
	s_barrier
	s_waitcnt lgkmcnt(0)
	v_mfma_f32_16x16x32_bf16 v[60:63], v[144:147], v[184:187], v[60:63]
	v_mfma_f32_16x16x32_bf16 v[56:59], v[160:163], v[184:187], v[56:59]
	v_mfma_f32_16x16x32_bf16 v[44:47], v[144:147], v[192:195], v[44:47]
	v_mfma_f32_16x16x32_bf16 v[40:43], v[160:163], v[192:195], v[40:43]
	v_mfma_f32_16x16x32_bf16 v[28:31], v[144:147], v[200:203], v[28:31]
	v_mfma_f32_16x16x32_bf16 v[24:27], v[160:163], v[200:203], v[24:27]
	v_mfma_f32_16x16x32_bf16 v[12:15], v[144:147], v[212:215], v[12:15]
	v_mfma_f32_16x16x32_bf16 v[8:11], v[160:163], v[212:215], v[8:11]
	v_mfma_f32_16x16x32_bf16 v[60:63], v[156:159], v[188:191], v[60:63]
	v_mfma_f32_16x16x32_bf16 v[56:59], v[164:167], v[188:191], v[56:59]
	v_mfma_f32_16x16x32_bf16 v[44:47], v[156:159], v[196:199], v[44:47]
	v_mfma_f32_16x16x32_bf16 v[40:43], v[164:167], v[196:199], v[40:43]
	v_mfma_f32_16x16x32_bf16 v[28:31], v[156:159], v[208:211], v[28:31]
	v_mfma_f32_16x16x32_bf16 v[24:27], v[164:167], v[208:211], v[24:27]
	v_mfma_f32_16x16x32_bf16 v[12:15], v[156:159], v[216:219], v[12:15]
	v_mfma_f32_16x16x32_bf16 v[8:11], v[164:167], v[216:219], v[8:11]
	v_mfma_f32_16x16x32_bf16 v[52:55], v[168:171], v[184:187], v[52:55]
	v_mfma_f32_16x16x32_bf16 v[48:51], v[176:179], v[184:187], v[48:51]
	v_mfma_f32_16x16x32_bf16 v[36:39], v[168:171], v[192:195], v[36:39]
	v_mfma_f32_16x16x32_bf16 v[32:35], v[176:179], v[192:195], v[32:35]
	v_mfma_f32_16x16x32_bf16 v[20:23], v[168:171], v[200:203], v[20:23]
	v_mfma_f32_16x16x32_bf16 v[16:19], v[176:179], v[200:203], v[16:19]
	v_mfma_f32_16x16x32_bf16 v[4:7], v[168:171], v[212:215], v[4:7]
	v_mfma_f32_16x16x32_bf16 v[0:3], v[176:179], v[212:215], v[0:3]
	v_mfma_f32_16x16x32_bf16 v[52:55], v[172:175], v[188:191], v[52:55]
	v_mfma_f32_16x16x32_bf16 v[48:51], v[180:183], v[188:191], v[48:51]
	v_mfma_f32_16x16x32_bf16 v[36:39], v[172:175], v[196:199], v[36:39]
	v_mfma_f32_16x16x32_bf16 v[32:35], v[180:183], v[196:199], v[32:35]
	v_mfma_f32_16x16x32_bf16 v[20:23], v[172:175], v[208:211], v[20:23]
	v_mfma_f32_16x16x32_bf16 v[16:19], v[180:183], v[208:211], v[16:19]
	v_mfma_f32_16x16x32_bf16 v[4:7], v[172:175], v[216:219], v[4:7]
	v_mfma_f32_16x16x32_bf16 v[0:3], v[180:183], v[216:219], v[0:3]
	s_barrier
	s_mov_b32 m0, s40
	s_nop 0
	global_load_lds_dwordx4 v132, s[28:29]
	s_add_i32 s54, 0, 0x18000
	v_add_u32_e32 v155, s54, v149
	s_add_i32 s55, 0, 0x1c000
	ds_read_b128 v[144:147], v155
	ds_read_b128 v[156:159], v155 offset:1024
	ds_read_b128 v[160:163], v155 offset:2048
	ds_read_b128 v[164:167], v155 offset:3072
	v_add_u32_e32 v155, s55, v149
	ds_read_b128 v[168:171], v155
	ds_read_b128 v[172:175], v155 offset:1024
	ds_read_b128 v[176:179], v155 offset:2048
	ds_read_b128 v[180:183], v155 offset:3072
	s_add_u32 s28, s28, 0x40000
	s_addc_u32 s29, s29, 0
	s_mov_b32 m0, s41
	ds_read_b128 v[184:187], v153 offset:32768
	ds_read_b128 v[188:191], v153 offset:33792
	ds_read_b128 v[192:195], v153 offset:34816
	ds_read_b128 v[196:199], v153 offset:35840
	ds_read_b128 v[200:203], v153 offset:36864
	ds_read_b128 v[208:211], v153 offset:37888
	ds_read_b128 v[212:215], v153 offset:38912
	ds_read_b128 v[216:219], v153 offset:39936
	global_load_lds_dwordx4 v128, s[28:29]
	s_mov_b32 m0, s42
	s_nop 0
	global_load_lds_dwordx4 v132, s[28:29]
	s_waitcnt vmcnt(8)
	s_waitcnt lgkmcnt(0)
	s_barrier
	s_waitcnt lgkmcnt(0)
	v_mfma_f32_16x16x32_bf16 v[124:127], v[144:147], v[184:187], v[124:127]
	v_mfma_f32_16x16x32_bf16 v[120:123], v[160:163], v[184:187], v[120:123]
	v_mfma_f32_16x16x32_bf16 v[108:111], v[144:147], v[192:195], v[108:111]
	v_mfma_f32_16x16x32_bf16 v[104:107], v[160:163], v[192:195], v[104:107]
	v_mfma_f32_16x16x32_bf16 v[92:95], v[144:147], v[200:203], v[92:95]
	v_mfma_f32_16x16x32_bf16 v[88:91], v[160:163], v[200:203], v[88:91]
	v_mfma_f32_16x16x32_bf16 v[76:79], v[144:147], v[212:215], v[76:79]
	v_mfma_f32_16x16x32_bf16 v[72:75], v[160:163], v[212:215], v[72:75]
	v_mfma_f32_16x16x32_bf16 v[124:127], v[156:159], v[188:191], v[124:127]
	v_mfma_f32_16x16x32_bf16 v[120:123], v[164:167], v[188:191], v[120:123]
	v_mfma_f32_16x16x32_bf16 v[108:111], v[156:159], v[196:199], v[108:111]
	v_mfma_f32_16x16x32_bf16 v[104:107], v[164:167], v[196:199], v[104:107]
	v_mfma_f32_16x16x32_bf16 v[92:95], v[156:159], v[208:211], v[92:95]
	v_mfma_f32_16x16x32_bf16 v[88:91], v[164:167], v[208:211], v[88:91]
	v_mfma_f32_16x16x32_bf16 v[76:79], v[156:159], v[216:219], v[76:79]
	v_mfma_f32_16x16x32_bf16 v[72:75], v[164:167], v[216:219], v[72:75]
	v_mfma_f32_16x16x32_bf16 v[116:119], v[168:171], v[184:187], v[116:119]
	v_mfma_f32_16x16x32_bf16 v[112:115], v[176:179], v[184:187], v[112:115]
	v_mfma_f32_16x16x32_bf16 v[100:103], v[168:171], v[192:195], v[100:103]
	v_mfma_f32_16x16x32_bf16 v[96:99], v[176:179], v[192:195], v[96:99]
	v_mfma_f32_16x16x32_bf16 v[84:87], v[168:171], v[200:203], v[84:87]
	v_mfma_f32_16x16x32_bf16 v[80:83], v[176:179], v[200:203], v[80:83]
	v_mfma_f32_16x16x32_bf16 v[68:71], v[168:171], v[212:215], v[68:71]
	v_mfma_f32_16x16x32_bf16 v[64:67], v[176:179], v[212:215], v[64:67]
	v_mfma_f32_16x16x32_bf16 v[116:119], v[172:175], v[188:191], v[116:119]
	v_mfma_f32_16x16x32_bf16 v[112:115], v[180:183], v[188:191], v[112:115]
	v_mfma_f32_16x16x32_bf16 v[100:103], v[172:175], v[196:199], v[100:103]
	v_mfma_f32_16x16x32_bf16 v[96:99], v[180:183], v[196:199], v[96:99]
	v_mfma_f32_16x16x32_bf16 v[84:87], v[172:175], v[208:211], v[84:87]
	v_mfma_f32_16x16x32_bf16 v[80:83], v[180:183], v[208:211], v[80:83]
	v_mfma_f32_16x16x32_bf16 v[68:71], v[172:175], v[216:219], v[68:71]
	v_mfma_f32_16x16x32_bf16 v[64:67], v[180:183], v[216:219], v[64:67]
	s_barrier
	s_add_i32 s28, s54, s38
	s_mov_b32 m0, s28
	ds_read_b128 v[184:187], v153 offset:49152
	ds_read_b128 v[188:191], v153 offset:50176
	ds_read_b128 v[192:195], v153 offset:51200
	ds_read_b128 v[196:199], v153 offset:52224
	ds_read_b128 v[200:203], v153 offset:53248
	ds_read_b128 v[208:211], v153 offset:54272
	ds_read_b128 v[212:215], v153 offset:55296
	ds_read_b128 v[216:219], v153 offset:56320
	global_load_lds_dwordx4 v205, s[26:27]
	s_add_i32 m0, s28, 0x2000
	s_add_u32 s26, s26, 0x40080
	s_addc_u32 s27, s27, 0
	s_add_i32 s28, s55, s38
	global_load_lds_dwordx4 v221, s[98:99]
	s_mov_b32 m0, s28
	s_nop 0
	global_load_lds_dwordx4 v130, s[26:27]
	s_add_i32 m0, s28, 0x2000
	s_nop 0
	global_load_lds_dwordx4 v134, s[26:27]
	s_mov_b32 m0, s44
	s_nop 0
	global_load_lds_dwordx4 v204, s[100:101]
	s_cmp_lg_u32 s53, 12
	s_cbranch_scc1 .Lbal_last_13
	s_mov_b32 m0, s45
	s_nop 0
	global_load_lds_dwordx4 v220, s[100:101]
.Lbal_last_13:
	s_waitcnt vmcnt(7)
	s_waitcnt lgkmcnt(0)
	s_barrier
	s_waitcnt lgkmcnt(0)
	v_mfma_f32_16x16x32_bf16 v[60:63], v[144:147], v[184:187], v[60:63]
	v_mfma_f32_16x16x32_bf16 v[56:59], v[160:163], v[184:187], v[56:59]
	v_mfma_f32_16x16x32_bf16 v[44:47], v[144:147], v[192:195], v[44:47]
	v_mfma_f32_16x16x32_bf16 v[40:43], v[160:163], v[192:195], v[40:43]
	v_mfma_f32_16x16x32_bf16 v[28:31], v[144:147], v[200:203], v[28:31]
	v_mfma_f32_16x16x32_bf16 v[24:27], v[160:163], v[200:203], v[24:27]
	v_mfma_f32_16x16x32_bf16 v[12:15], v[144:147], v[212:215], v[12:15]
	v_mfma_f32_16x16x32_bf16 v[8:11], v[160:163], v[212:215], v[8:11]
	v_mfma_f32_16x16x32_bf16 v[60:63], v[156:159], v[188:191], v[60:63]
	v_mfma_f32_16x16x32_bf16 v[56:59], v[164:167], v[188:191], v[56:59]
	v_mfma_f32_16x16x32_bf16 v[44:47], v[156:159], v[196:199], v[44:47]
	v_mfma_f32_16x16x32_bf16 v[40:43], v[164:167], v[196:199], v[40:43]
	v_mfma_f32_16x16x32_bf16 v[28:31], v[156:159], v[208:211], v[28:31]
	v_mfma_f32_16x16x32_bf16 v[24:27], v[164:167], v[208:211], v[24:27]
	v_mfma_f32_16x16x32_bf16 v[12:15], v[156:159], v[216:219], v[12:15]
	v_mfma_f32_16x16x32_bf16 v[8:11], v[164:167], v[216:219], v[8:11]
	v_mfma_f32_16x16x32_bf16 v[52:55], v[168:171], v[184:187], v[52:55]
	v_mfma_f32_16x16x32_bf16 v[48:51], v[176:179], v[184:187], v[48:51]
	v_mfma_f32_16x16x32_bf16 v[36:39], v[168:171], v[192:195], v[36:39]
	v_mfma_f32_16x16x32_bf16 v[32:35], v[176:179], v[192:195], v[32:35]
	v_mfma_f32_16x16x32_bf16 v[20:23], v[168:171], v[200:203], v[20:23]
	v_mfma_f32_16x16x32_bf16 v[16:19], v[176:179], v[200:203], v[16:19]
	v_mfma_f32_16x16x32_bf16 v[4:7], v[168:171], v[212:215], v[4:7]
	v_mfma_f32_16x16x32_bf16 v[0:3], v[176:179], v[212:215], v[0:3]
	v_mfma_f32_16x16x32_bf16 v[52:55], v[172:175], v[188:191], v[52:55]
	v_mfma_f32_16x16x32_bf16 v[48:51], v[180:183], v[188:191], v[48:51]
	v_mfma_f32_16x16x32_bf16 v[36:39], v[172:175], v[196:199], v[36:39]
	v_mfma_f32_16x16x32_bf16 v[32:35], v[180:183], v[196:199], v[32:35]
	v_mfma_f32_16x16x32_bf16 v[20:23], v[172:175], v[208:211], v[20:23]
	v_mfma_f32_16x16x32_bf16 v[16:19], v[180:183], v[208:211], v[16:19]
	v_mfma_f32_16x16x32_bf16 v[4:7], v[172:175], v[216:219], v[4:7]
	v_mfma_f32_16x16x32_bf16 v[0:3], v[180:183], v[216:219], v[0:3]
	s_barrier
	s_add_i32 s53, s53, 2
	s_add_u32 s51, s51, 0x100
	s_addc_u32 s52, s52, 0
	s_add_u32 s24, s24, 0x100
	s_addc_u32 s25, s25, 0
	s_cmp_gt_u32 s53, 13
	s_cbranch_scc0 .LBB0_1365
	s_setprio 0
	s_and_b64 vcc, exec, s[14:15]
	s_cbranch_vccz .LBB0_1368
	s_barrier

.LBB0_1561:
	s_cmp_eq_i32 s61, -2
	s_cbranch_scc1 .Lbal_first_11
	s_mov_b32 m0, s52
	s_nop 0
	global_load_lds_dwordx4 v205, s[100:101]
.Lbal_first_11:
	ds_read_b128 v[140:143], v151
	ds_read_b128 v[144:147], v151 offset:1024
	ds_read_b128 v[156:159], v151 offset:2048
	ds_read_b128 v[160:163], v151 offset:3072
	ds_read_b128 v[164:167], v152
	ds_read_b128 v[168:171], v152 offset:1024
	ds_read_b128 v[172:175], v152 offset:2048
	ds_read_b128 v[176:179], v152 offset:3072
	s_add_u32 s38, s36, 0xfffc0080
	s_addc_u32 s39, s37, -1
	s_cmp_eq_u32 s61, 12
	s_cselect_b32 s41, s3, s39
	s_cselect_b32 s40, s29, s38
	s_cselect_b32 s39, s27, s60
	s_cselect_b32 s38, s58, s59
	s_add_i32 m0, s46, 0xc000
	ds_read_b128 v[180:183], v153
	ds_read_b128 v[184:187], v153 offset:1024
	ds_read_b128 v[188:191], v153 offset:2048
	ds_read_b128 v[192:195], v153 offset:3072
	ds_read_b128 v[196:199], v153 offset:4096
	ds_read_b128 v[200:203], v153 offset:5120
	ds_read_b128 v[208:211], v153 offset:6144
	ds_read_b128 v[212:215], v153 offset:7168
	global_load_lds_dwordx4 v134, s[36:37]
	s_add_i32 m0, s46, 0xe000
	s_nop 0
	global_load_lds_dwordx4 v132, s[36:37]
	s_waitcnt vmcnt(8)
	s_waitcnt lgkmcnt(0)
	s_barrier
	s_waitcnt lgkmcnt(0)
	v_mfma_f32_16x16x32_bf16 v[124:127], v[140:143], v[180:183], v[124:127]
	v_mfma_f32_16x16x32_bf16 v[120:123], v[156:159], v[180:183], v[120:123]
	v_mfma_f32_16x16x32_bf16 v[108:111], v[140:143], v[188:191], v[108:111]
	v_mfma_f32_16x16x32_bf16 v[104:107], v[156:159], v[188:191], v[104:107]
	v_mfma_f32_16x16x32_bf16 v[92:95], v[140:143], v[196:199], v[92:95]
	v_mfma_f32_16x16x32_bf16 v[88:91], v[156:159], v[196:199], v[88:91]
	v_mfma_f32_16x16x32_bf16 v[76:79], v[140:143], v[208:211], v[76:79]
	v_mfma_f32_16x16x32_bf16 v[72:75], v[156:159], v[208:211], v[72:75]
	v_mfma_f32_16x16x32_bf16 v[124:127], v[144:147], v[184:187], v[124:127]
	v_mfma_f32_16x16x32_bf16 v[120:123], v[160:163], v[184:187], v[120:123]
	v_mfma_f32_16x16x32_bf16 v[108:111], v[144:147], v[192:195], v[108:111]
	v_mfma_f32_16x16x32_bf16 v[104:107], v[160:163], v[192:195], v[104:107]
	v_mfma_f32_16x16x32_bf16 v[92:95], v[144:147], v[200:203], v[92:95]
	v_mfma_f32_16x16x32_bf16 v[88:91], v[160:163], v[200:203], v[88:91]
	v_mfma_f32_16x16x32_bf16 v[76:79], v[144:147], v[212:215], v[76:79]
	v_mfma_f32_16x16x32_bf16 v[72:75], v[160:163], v[212:215], v[72:75]
	v_mfma_f32_16x16x32_bf16 v[116:119], v[164:167], v[180:183], v[116:119]
	v_mfma_f32_16x16x32_bf16 v[112:115], v[172:175], v[180:183], v[112:115]
	v_mfma_f32_16x16x32_bf16 v[100:103], v[164:167], v[188:191], v[100:103]
	v_mfma_f32_16x16x32_bf16 v[96:99], v[172:175], v[188:191], v[96:99]
	v_mfma_f32_16x16x32_bf16 v[84:87], v[164:167], v[196:199], v[84:87]
	v_mfma_f32_16x16x32_bf16 v[80:83], v[172:175], v[196:199], v[80:83]
	v_mfma_f32_16x16x32_bf16 v[68:71], v[164:167], v[208:211], v[68:71]
	v_mfma_f32_16x16x32_bf16 v[64:67], v[172:175], v[208:211], v[64:67]
	v_mfma_f32_16x16x32_bf16 v[116:119], v[168:171], v[184:187], v[116:119]
	v_mfma_f32_16x16x32_bf16 v[112:115], v[176:179], v[184:187], v[112:115]
	v_mfma_f32_16x16x32_bf16 v[100:103], v[168:171], v[192:195], v[100:103]
	v_mfma_f32_16x16x32_bf16 v[96:99], v[176:179], v[192:195], v[96:99]
	v_mfma_f32_16x16x32_bf16 v[84:87], v[168:171], v[200:203], v[84:87]
	v_mfma_f32_16x16x32_bf16 v[80:83], v[176:179], v[200:203], v[80:83]
	v_mfma_f32_16x16x32_bf16 v[68:71], v[168:171], v[212:215], v[68:71]
	v_mfma_f32_16x16x32_bf16 v[64:67], v[176:179], v[212:215], v[64:67]
	s_barrier
	s_add_i32 s62, s54, s45
	s_mov_b32 m0, s62
	ds_read_b128 v[180:183], v153 offset:16384
	ds_read_b128 v[184:187], v153 offset:17408
	ds_read_b128 v[188:191], v153 offset:18432
	ds_read_b128 v[192:195], v153 offset:19456
	ds_read_b128 v[196:199], v153 offset:20480
	ds_read_b128 v[200:203], v153 offset:21504
	ds_read_b128 v[208:211], v153 offset:22528
	ds_read_b128 v[212:215], v153 offset:23552
	global_load_lds_dwordx4 v128, s[38:39]
	s_add_i32 m0, s62, 0x2000
	s_add_u32 s62, s38, 0x40000
	s_mov_b64 s[98:99], s[38:39]
	s_addc_u32 s63, s39, 0
	s_add_i32 s64, s55, s45
	global_load_lds_dwordx4 v130, s[38:39]
	s_mov_b32 m0, s64
	s_mov_b64 s[100:101], s[40:41]
	global_load_lds_dwordx4 v128, s[62:63]
	s_add_i32 m0, s64, 0x2000
	s_nop 0
	global_load_lds_dwordx4 v130, s[62:63]
	s_mov_b32 m0, s46
	s_nop 0
	global_load_lds_dwordx4 v128, s[40:41]
	s_waitcnt vmcnt(7)
	s_waitcnt lgkmcnt(0)
	s_barrier
	s_waitcnt lgkmcnt(0)
	v_mfma_f32_16x16x32_bf16 v[60:63], v[140:143], v[180:183], v[60:63]
	v_mfma_f32_16x16x32_bf16 v[56:59], v[156:159], v[180:183], v[56:59]
	v_mfma_f32_16x16x32_bf16 v[44:47], v[140:143], v[188:191], v[44:47]
	v_mfma_f32_16x16x32_bf16 v[40:43], v[156:159], v[188:191], v[40:43]
	v_mfma_f32_16x16x32_bf16 v[28:31], v[140:143], v[196:199], v[28:31]
	v_mfma_f32_16x16x32_bf16 v[24:27], v[156:159], v[196:199], v[24:27]
	v_mfma_f32_16x16x32_bf16 v[12:15], v[140:143], v[208:211], v[12:15]
	v_mfma_f32_16x16x32_bf16 v[8:11], v[156:159], v[208:211], v[8:11]
	v_mfma_f32_16x16x32_bf16 v[60:63], v[144:147], v[184:187], v[60:63]
	v_mfma_f32_16x16x32_bf16 v[56:59], v[160:163], v[184:187], v[56:59]
	v_mfma_f32_16x16x32_bf16 v[44:47], v[144:147], v[192:195], v[44:47]
	v_mfma_f32_16x16x32_bf16 v[40:43], v[160:163], v[192:195], v[40:43]
	v_mfma_f32_16x16x32_bf16 v[28:31], v[144:147], v[200:203], v[28:31]
	v_mfma_f32_16x16x32_bf16 v[24:27], v[160:163], v[200:203], v[24:27]
	v_mfma_f32_16x16x32_bf16 v[12:15], v[144:147], v[212:215], v[12:15]
	v_mfma_f32_16x16x32_bf16 v[8:11], v[160:163], v[212:215], v[8:11]
	v_mfma_f32_16x16x32_bf16 v[52:55], v[164:167], v[180:183], v[52:55]
	v_mfma_f32_16x16x32_bf16 v[48:51], v[172:175], v[180:183], v[48:51]
	v_mfma_f32_16x16x32_bf16 v[36:39], v[164:167], v[188:191], v[36:39]
	v_mfma_f32_16x16x32_bf16 v[32:35], v[172:175], v[188:191], v[32:35]
	v_mfma_f32_16x16x32_bf16 v[20:23], v[164:167], v[196:199], v[20:23]
	v_mfma_f32_16x16x32_bf16 v[16:19], v[172:175], v[196:199], v[16:19]
	v_mfma_f32_16x16x32_bf16 v[4:7], v[164:167], v[208:211], v[4:7]
	v_mfma_f32_16x16x32_bf16 v[0:3], v[172:175], v[208:211], v[0:3]
	v_mfma_f32_16x16x32_bf16 v[52:55], v[168:171], v[184:187], v[52:55]
	v_mfma_f32_16x16x32_bf16 v[48:51], v[176:179], v[184:187], v[48:51]
	v_mfma_f32_16x16x32_bf16 v[36:39], v[168:171], v[192:195], v[36:39]
	v_mfma_f32_16x16x32_bf16 v[32:35], v[176:179], v[192:195], v[32:35]
	v_mfma_f32_16x16x32_bf16 v[20:23], v[168:171], v[200:203], v[20:23]
	v_mfma_f32_16x16x32_bf16 v[16:19], v[176:179], v[200:203], v[16:19]
	v_mfma_f32_16x16x32_bf16 v[4:7], v[168:171], v[212:215], v[4:7]
	v_mfma_f32_16x16x32_bf16 v[0:3], v[176:179], v[212:215], v[0:3]
	s_barrier
	s_mov_b32 m0, s47
	s_nop 0
	global_load_lds_dwordx4 v130, s[40:41]
	s_add_i32 s62, 0, 0x18000
	v_add_u32_e32 v155, s62, v149
	s_add_i32 s63, 0, 0x1c000
	ds_read_b128 v[140:143], v155
	ds_read_b128 v[144:147], v155 offset:1024
	ds_read_b128 v[156:159], v155 offset:2048
	ds_read_b128 v[160:163], v155 offset:3072
	v_add_u32_e32 v155, s63, v149
	ds_read_b128 v[164:167], v155
	ds_read_b128 v[168:171], v155 offset:1024
	ds_read_b128 v[172:175], v155 offset:2048
	ds_read_b128 v[176:179], v155 offset:3072
	s_add_u32 s40, s40, 0x40000
	s_addc_u32 s41, s41, 0
	s_mov_b32 m0, s48
	ds_read_b128 v[180:183], v153 offset:32768
	ds_read_b128 v[184:187], v153 offset:33792
	ds_read_b128 v[188:191], v153 offset:34816
	ds_read_b128 v[192:195], v153 offset:35840
	ds_read_b128 v[196:199], v153 offset:36864
	ds_read_b128 v[200:203], v153 offset:37888
	ds_read_b128 v[208:211], v153 offset:38912
	ds_read_b128 v[212:215], v153 offset:39936
	global_load_lds_dwordx4 v128, s[40:41]
	s_mov_b32 m0, s49
	s_nop 0
	global_load_lds_dwordx4 v130, s[40:41]
	s_waitcnt vmcnt(8)
	s_waitcnt lgkmcnt(0)
	s_barrier
	s_waitcnt lgkmcnt(0)
	v_mfma_f32_16x16x32_bf16 v[124:127], v[140:143], v[180:183], v[124:127]
	v_mfma_f32_16x16x32_bf16 v[120:123], v[156:159], v[180:183], v[120:123]
	v_mfma_f32_16x16x32_bf16 v[108:111], v[140:143], v[188:191], v[108:111]
	v_mfma_f32_16x16x32_bf16 v[104:107], v[156:159], v[188:191], v[104:107]
	v_mfma_f32_16x16x32_bf16 v[92:95], v[140:143], v[196:199], v[92:95]
	v_mfma_f32_16x16x32_bf16 v[88:91], v[156:159], v[196:199], v[88:91]
	v_mfma_f32_16x16x32_bf16 v[76:79], v[140:143], v[208:211], v[76:79]
	v_mfma_f32_16x16x32_bf16 v[72:75], v[156:159], v[208:211], v[72:75]
	v_mfma_f32_16x16x32_bf16 v[124:127], v[144:147], v[184:187], v[124:127]
	v_mfma_f32_16x16x32_bf16 v[120:123], v[160:163], v[184:187], v[120:123]
	v_mfma_f32_16x16x32_bf16 v[108:111], v[144:147], v[192:195], v[108:111]
	v_mfma_f32_16x16x32_bf16 v[104:107], v[160:163], v[192:195], v[104:107]
	v_mfma_f32_16x16x32_bf16 v[92:95], v[144:147], v[200:203], v[92:95]
	v_mfma_f32_16x16x32_bf16 v[88:91], v[160:163], v[200:203], v[88:91]
	v_mfma_f32_16x16x32_bf16 v[76:79], v[144:147], v[212:215], v[76:79]
	v_mfma_f32_16x16x32_bf16 v[72:75], v[160:163], v[212:215], v[72:75]
	v_mfma_f32_16x16x32_bf16 v[116:119], v[164:167], v[180:183], v[116:119]
	v_mfma_f32_16x16x32_bf16 v[112:115], v[172:175], v[180:183], v[112:115]
	v_mfma_f32_16x16x32_bf16 v[100:103], v[164:167], v[188:191], v[100:103]
	v_mfma_f32_16x16x32_bf16 v[96:99], v[172:175], v[188:191], v[96:99]
	v_mfma_f32_16x16x32_bf16 v[84:87], v[164:167], v[196:199], v[84:87]
	v_mfma_f32_16x16x32_bf16 v[80:83], v[172:175], v[196:199], v[80:83]
	v_mfma_f32_16x16x32_bf16 v[68:71], v[164:167], v[208:211], v[68:71]
	v_mfma_f32_16x16x32_bf16 v[64:67], v[172:175], v[208:211], v[64:67]
	v_mfma_f32_16x16x32_bf16 v[116:119], v[168:171], v[184:187], v[116:119]
	v_mfma_f32_16x16x32_bf16 v[112:115], v[176:179], v[184:187], v[112:115]
	v_mfma_f32_16x16x32_bf16 v[100:103], v[168:171], v[192:195], v[100:103]
	v_mfma_f32_16x16x32_bf16 v[96:99], v[176:179], v[192:195], v[96:99]
	v_mfma_f32_16x16x32_bf16 v[84:87], v[168:171], v[200:203], v[84:87]
	v_mfma_f32_16x16x32_bf16 v[80:83], v[176:179], v[200:203], v[80:83]
	v_mfma_f32_16x16x32_bf16 v[68:71], v[168:171], v[212:215], v[68:71]
	v_mfma_f32_16x16x32_bf16 v[64:67], v[176:179], v[212:215], v[64:67]
	s_barrier
	s_add_i32 s40, s62, s45
	s_mov_b32 m0, s40
	ds_read_b128 v[180:183], v153 offset:49152
	ds_read_b128 v[184:187], v153 offset:50176
	ds_read_b128 v[188:191], v153 offset:51200
	ds_read_b128 v[192:195], v153 offset:52224
	ds_read_b128 v[196:199], v153 offset:53248
	ds_read_b128 v[200:203], v153 offset:54272
	ds_read_b128 v[208:211], v153 offset:55296
	ds_read_b128 v[212:215], v153 offset:56320
	global_load_lds_dwordx4 v204, s[38:39]
	s_add_i32 m0, s40, 0x2000
	s_add_u32 s38, s38, 0x40080
	s_addc_u32 s39, s39, 0
	s_add_i32 s40, s63, s45
	global_load_lds_dwordx4 v205, s[98:99]
	s_mov_b32 m0, s40
	s_nop 0
	global_load_lds_dwordx4 v128, s[38:39]
	s_add_i32 m0, s40, 0x2000
	s_nop 0
	global_load_lds_dwordx4 v130, s[38:39]
	s_mov_b32 m0, s51
	s_nop 0
	global_load_lds_dwordx4 v204, s[100:101]
	s_cmp_lg_u32 s61, 12
	s_cbranch_scc1 .Lbal_last_11
	s_mov_b32 m0, s52
	s_nop 0
	global_load_lds_dwordx4 v205, s[100:101]
.Lbal_last_11:
	s_waitcnt vmcnt(7)
	s_waitcnt lgkmcnt(0)
	s_barrier
	s_waitcnt lgkmcnt(0)
	v_mfma_f32_16x16x32_bf16 v[60:63], v[140:143], v[180:183], v[60:63]
	v_mfma_f32_16x16x32_bf16 v[56:59], v[156:159], v[180:183], v[56:59]
	v_mfma_f32_16x16x32_bf16 v[44:47], v[140:143], v[188:191], v[44:47]
	v_mfma_f32_16x16x32_bf16 v[40:43], v[156:159], v[188:191], v[40:43]
	v_mfma_f32_16x16x32_bf16 v[28:31], v[140:143], v[196:199], v[28:31]
	v_mfma_f32_16x16x32_bf16 v[24:27], v[156:159], v[196:199], v[24:27]
	v_mfma_f32_16x16x32_bf16 v[12:15], v[140:143], v[208:211], v[12:15]
	v_mfma_f32_16x16x32_bf16 v[8:11], v[156:159], v[208:211], v[8:11]
	v_mfma_f32_16x16x32_bf16 v[60:63], v[144:147], v[184:187], v[60:63]
	v_mfma_f32_16x16x32_bf16 v[56:59], v[160:163], v[184:187], v[56:59]
	v_mfma_f32_16x16x32_bf16 v[44:47], v[144:147], v[192:195], v[44:47]
	v_mfma_f32_16x16x32_bf16 v[40:43], v[160:163], v[192:195], v[40:43]
	v_mfma_f32_16x16x32_bf16 v[28:31], v[144:147], v[200:203], v[28:31]
	v_mfma_f32_16x16x32_bf16 v[24:27], v[160:163], v[200:203], v[24:27]
	v_mfma_f32_16x16x32_bf16 v[12:15], v[144:147], v[212:215], v[12:15]
	v_mfma_f32_16x16x32_bf16 v[8:11], v[160:163], v[212:215], v[8:11]
	v_mfma_f32_16x16x32_bf16 v[52:55], v[164:167], v[180:183], v[52:55]
	v_mfma_f32_16x16x32_bf16 v[48:51], v[172:175], v[180:183], v[48:51]
	v_mfma_f32_16x16x32_bf16 v[36:39], v[164:167], v[188:191], v[36:39]
	v_mfma_f32_16x16x32_bf16 v[32:35], v[172:175], v[188:191], v[32:35]
	v_mfma_f32_16x16x32_bf16 v[20:23], v[164:167], v[196:199], v[20:23]
	v_mfma_f32_16x16x32_bf16 v[16:19], v[172:175], v[196:199], v[16:19]
	v_mfma_f32_16x16x32_bf16 v[4:7], v[164:167], v[208:211], v[4:7]
	v_mfma_f32_16x16x32_bf16 v[0:3], v[172:175], v[208:211], v[0:3]
	v_mfma_f32_16x16x32_bf16 v[52:55], v[168:171], v[184:187], v[52:55]
	v_mfma_f32_16x16x32_bf16 v[48:51], v[176:179], v[184:187], v[48:51]
	v_mfma_f32_16x16x32_bf16 v[36:39], v[168:171], v[192:195], v[36:39]
	v_mfma_f32_16x16x32_bf16 v[32:35], v[176:179], v[192:195], v[32:35]
	v_mfma_f32_16x16x32_bf16 v[20:23], v[168:171], v[200:203], v[20:23]
	v_mfma_f32_16x16x32_bf16 v[16:19], v[176:179], v[200:203], v[16:19]
	v_mfma_f32_16x16x32_bf16 v[4:7], v[168:171], v[212:215], v[4:7]
	v_mfma_f32_16x16x32_bf16 v[0:3], v[176:179], v[212:215], v[0:3]
	s_barrier
	s_add_i32 s61, s61, 2
	s_add_u32 s59, s59, 0x100
	s_addc_u32 s60, s60, 0
	s_add_u32 s36, s36, 0x100
	s_addc_u32 s37, s37, 0
	s_cmp_gt_u32 s61, 13
	s_cbranch_scc0 .LBB0_1561
	s_setprio 0
	s_and_b64 vcc, exec, s[24:25]
	s_cbranch_vccz .LBB0_1564
	s_barrier

.LBB0_1646:
	s_cmp_eq_i32 s54, -2
	s_cbranch_scc1 .Lbal_first_10
	s_mov_b32 m0, s46
	s_nop 0
	global_load_lds_dwordx4 v205, s[100:101]
.Lbal_first_10:
	ds_read_b128 v[144:147], v151
	ds_read_b128 v[156:159], v151 offset:1024
	ds_read_b128 v[160:163], v151 offset:2048
	ds_read_b128 v[164:167], v151 offset:3072
	ds_read_b128 v[168:171], v152
	ds_read_b128 v[172:175], v152 offset:1024
	ds_read_b128 v[176:179], v152 offset:2048
	ds_read_b128 v[180:183], v152 offset:3072
	s_add_u32 s26, s24, 0xfffc0080
	s_addc_u32 s27, s25, -1
	s_cmp_eq_u32 s54, 12
	s_cselect_b32 s29, s19, s27
	s_cselect_b32 s28, s50, s26
	s_cselect_b32 s27, s17, s53
	s_cselect_b32 s26, s51, s52
	s_add_i32 m0, s38, 0xc000
	ds_read_b128 v[184:187], v153
	ds_read_b128 v[188:191], v153 offset:1024
	ds_read_b128 v[192:195], v153 offset:2048
	ds_read_b128 v[196:199], v153 offset:3072
	ds_read_b128 v[200:203], v153 offset:4096
	ds_read_b128 v[208:211], v153 offset:5120
	ds_read_b128 v[212:215], v153 offset:6144
	ds_read_b128 v[216:219], v153 offset:7168
	global_load_lds_dwordx4 v138, s[24:25]
	s_add_i32 m0, s38, 0xe000
	s_nop 0
	global_load_lds_dwordx4 v136, s[24:25]
	s_waitcnt vmcnt(8)
	s_waitcnt lgkmcnt(0)
	s_barrier
	s_waitcnt lgkmcnt(0)
	v_mfma_f32_16x16x32_bf16 v[124:127], v[144:147], v[184:187], v[124:127]
	v_mfma_f32_16x16x32_bf16 v[120:123], v[160:163], v[184:187], v[120:123]
	v_mfma_f32_16x16x32_bf16 v[108:111], v[144:147], v[192:195], v[108:111]
	v_mfma_f32_16x16x32_bf16 v[104:107], v[160:163], v[192:195], v[104:107]
	v_mfma_f32_16x16x32_bf16 v[92:95], v[144:147], v[200:203], v[92:95]
	v_mfma_f32_16x16x32_bf16 v[88:91], v[160:163], v[200:203], v[88:91]
	v_mfma_f32_16x16x32_bf16 v[76:79], v[144:147], v[212:215], v[76:79]
	v_mfma_f32_16x16x32_bf16 v[72:75], v[160:163], v[212:215], v[72:75]
	v_mfma_f32_16x16x32_bf16 v[124:127], v[156:159], v[188:191], v[124:127]
	v_mfma_f32_16x16x32_bf16 v[120:123], v[164:167], v[188:191], v[120:123]
	v_mfma_f32_16x16x32_bf16 v[108:111], v[156:159], v[196:199], v[108:111]
	v_mfma_f32_16x16x32_bf16 v[104:107], v[164:167], v[196:199], v[104:107]
	v_mfma_f32_16x16x32_bf16 v[92:95], v[156:159], v[208:211], v[92:95]
	v_mfma_f32_16x16x32_bf16 v[88:91], v[164:167], v[208:211], v[88:91]
	v_mfma_f32_16x16x32_bf16 v[76:79], v[156:159], v[216:219], v[76:79]
	v_mfma_f32_16x16x32_bf16 v[72:75], v[164:167], v[216:219], v[72:75]
	v_mfma_f32_16x16x32_bf16 v[116:119], v[168:171], v[184:187], v[116:119]
	v_mfma_f32_16x16x32_bf16 v[112:115], v[176:179], v[184:187], v[112:115]
	v_mfma_f32_16x16x32_bf16 v[100:103], v[168:171], v[192:195], v[100:103]
	v_mfma_f32_16x16x32_bf16 v[96:99], v[176:179], v[192:195], v[96:99]
	v_mfma_f32_16x16x32_bf16 v[84:87], v[168:171], v[200:203], v[84:87]
	v_mfma_f32_16x16x32_bf16 v[80:83], v[176:179], v[200:203], v[80:83]
	v_mfma_f32_16x16x32_bf16 v[68:71], v[168:171], v[212:215], v[68:71]
	v_mfma_f32_16x16x32_bf16 v[64:67], v[176:179], v[212:215], v[64:67]
	v_mfma_f32_16x16x32_bf16 v[116:119], v[172:175], v[188:191], v[116:119]
	v_mfma_f32_16x16x32_bf16 v[112:115], v[180:183], v[188:191], v[112:115]
	v_mfma_f32_16x16x32_bf16 v[100:103], v[172:175], v[196:199], v[100:103]
	v_mfma_f32_16x16x32_bf16 v[96:99], v[180:183], v[196:199], v[96:99]
	v_mfma_f32_16x16x32_bf16 v[84:87], v[172:175], v[208:211], v[84:87]
	v_mfma_f32_16x16x32_bf16 v[80:83], v[180:183], v[208:211], v[80:83]
	v_mfma_f32_16x16x32_bf16 v[68:71], v[172:175], v[216:219], v[68:71]
	v_mfma_f32_16x16x32_bf16 v[64:67], v[180:183], v[216:219], v[64:67]
	s_barrier
	s_add_i32 s55, s47, s35
	s_mov_b32 m0, s55
	ds_read_b128 v[184:187], v153 offset:16384
	ds_read_b128 v[188:191], v153 offset:17408
	ds_read_b128 v[192:195], v153 offset:18432
	ds_read_b128 v[196:199], v153 offset:19456
	ds_read_b128 v[200:203], v153 offset:20480
	ds_read_b128 v[208:211], v153 offset:21504
	ds_read_b128 v[212:215], v153 offset:22528
	ds_read_b128 v[216:219], v153 offset:23552
	global_load_lds_dwordx4 v132, s[26:27]
	s_add_i32 m0, s55, 0x2000
	s_add_u32 s56, s26, 0x40000
	s_mov_b64 s[98:99], s[26:27]
	s_addc_u32 s57, s27, 0
	s_add_i32 s55, s48, s35
	global_load_lds_dwordx4 v128, s[26:27]
	s_mov_b32 m0, s55
	s_mov_b64 s[100:101], s[28:29]
	global_load_lds_dwordx4 v132, s[56:57]
	s_add_i32 m0, s55, 0x2000
	s_nop 0
	global_load_lds_dwordx4 v128, s[56:57]
	s_mov_b32 m0, s38
	s_nop 0
	global_load_lds_dwordx4 v134, s[28:29]
	s_waitcnt vmcnt(7)
	s_waitcnt lgkmcnt(0)
	s_barrier
	s_waitcnt lgkmcnt(0)
	v_mfma_f32_16x16x32_bf16 v[60:63], v[144:147], v[184:187], v[60:63]
	v_mfma_f32_16x16x32_bf16 v[56:59], v[160:163], v[184:187], v[56:59]
	v_mfma_f32_16x16x32_bf16 v[44:47], v[144:147], v[192:195], v[44:47]
	v_mfma_f32_16x16x32_bf16 v[40:43], v[160:163], v[192:195], v[40:43]
	v_mfma_f32_16x16x32_bf16 v[28:31], v[144:147], v[200:203], v[28:31]
	v_mfma_f32_16x16x32_bf16 v[24:27], v[160:163], v[200:203], v[24:27]
	v_mfma_f32_16x16x32_bf16 v[12:15], v[144:147], v[212:215], v[12:15]
	v_mfma_f32_16x16x32_bf16 v[8:11], v[160:163], v[212:215], v[8:11]
	v_mfma_f32_16x16x32_bf16 v[60:63], v[156:159], v[188:191], v[60:63]
	v_mfma_f32_16x16x32_bf16 v[56:59], v[164:167], v[188:191], v[56:59]
	v_mfma_f32_16x16x32_bf16 v[44:47], v[156:159], v[196:199], v[44:47]
	v_mfma_f32_16x16x32_bf16 v[40:43], v[164:167], v[196:199], v[40:43]
	v_mfma_f32_16x16x32_bf16 v[28:31], v[156:159], v[208:211], v[28:31]
	v_mfma_f32_16x16x32_bf16 v[24:27], v[164:167], v[208:211], v[24:27]
	v_mfma_f32_16x16x32_bf16 v[12:15], v[156:159], v[216:219], v[12:15]
	v_mfma_f32_16x16x32_bf16 v[8:11], v[164:167], v[216:219], v[8:11]
	v_mfma_f32_16x16x32_bf16 v[52:55], v[168:171], v[184:187], v[52:55]
	v_mfma_f32_16x16x32_bf16 v[48:51], v[176:179], v[184:187], v[48:51]
	v_mfma_f32_16x16x32_bf16 v[36:39], v[168:171], v[192:195], v[36:39]
	v_mfma_f32_16x16x32_bf16 v[32:35], v[176:179], v[192:195], v[32:35]
	v_mfma_f32_16x16x32_bf16 v[20:23], v[168:171], v[200:203], v[20:23]
	v_mfma_f32_16x16x32_bf16 v[16:19], v[176:179], v[200:203], v[16:19]
	v_mfma_f32_16x16x32_bf16 v[4:7], v[168:171], v[212:215], v[4:7]
	v_mfma_f32_16x16x32_bf16 v[0:3], v[176:179], v[212:215], v[0:3]
	v_mfma_f32_16x16x32_bf16 v[52:55], v[172:175], v[188:191], v[52:55]
	v_mfma_f32_16x16x32_bf16 v[48:51], v[180:183], v[188:191], v[48:51]
	v_mfma_f32_16x16x32_bf16 v[36:39], v[172:175], v[196:199], v[36:39]
	v_mfma_f32_16x16x32_bf16 v[32:35], v[180:183], v[196:199], v[32:35]
	v_mfma_f32_16x16x32_bf16 v[20:23], v[172:175], v[208:211], v[20:23]
	v_mfma_f32_16x16x32_bf16 v[16:19], v[180:183], v[208:211], v[16:19]
	v_mfma_f32_16x16x32_bf16 v[4:7], v[172:175], v[216:219], v[4:7]
	v_mfma_f32_16x16x32_bf16 v[0:3], v[180:183], v[216:219], v[0:3]
	s_barrier
	s_mov_b32 m0, s39
	s_nop 0
	global_load_lds_dwordx4 v130, s[28:29]
	s_add_i32 s55, 0, 0x18000
	s_add_i32 s56, 0, 0x1c000
	v_add_u32_e32 v164, s55, v149
	v_add_u32_e32 v180, s56, v149
	ds_read_b128 v[144:147], v164
	ds_read_b128 v[156:159], v164 offset:1024
	ds_read_b128 v[160:163], v164 offset:2048
	ds_read_b128 v[164:167], v164 offset:3072
	ds_read_b128 v[168:171], v180
	ds_read_b128 v[172:175], v180 offset:1024
	ds_read_b128 v[176:179], v180 offset:2048
	ds_read_b128 v[180:183], v180 offset:3072
	s_add_u32 s28, s28, 0x40000
	s_addc_u32 s29, s29, 0
	s_mov_b32 m0, s40
	ds_read_b128 v[184:187], v153 offset:32768
	ds_read_b128 v[188:191], v153 offset:33792
	ds_read_b128 v[192:195], v153 offset:34816
	ds_read_b128 v[196:199], v153 offset:35840
	ds_read_b128 v[200:203], v153 offset:36864
	ds_read_b128 v[208:211], v153 offset:37888
	ds_read_b128 v[212:215], v153 offset:38912
	ds_read_b128 v[216:219], v153 offset:39936
	global_load_lds_dwordx4 v134, s[28:29]
	s_mov_b32 m0, s41
	s_nop 0
	global_load_lds_dwordx4 v130, s[28:29]
	s_waitcnt vmcnt(8)
	s_waitcnt lgkmcnt(0)
	s_barrier
	s_waitcnt lgkmcnt(0)
	v_mfma_f32_16x16x32_bf16 v[124:127], v[144:147], v[184:187], v[124:127]
	v_mfma_f32_16x16x32_bf16 v[120:123], v[160:163], v[184:187], v[120:123]
	v_mfma_f32_16x16x32_bf16 v[108:111], v[144:147], v[192:195], v[108:111]
	v_mfma_f32_16x16x32_bf16 v[104:107], v[160:163], v[192:195], v[104:107]
	v_mfma_f32_16x16x32_bf16 v[92:95], v[144:147], v[200:203], v[92:95]
	v_mfma_f32_16x16x32_bf16 v[88:91], v[160:163], v[200:203], v[88:91]
	v_mfma_f32_16x16x32_bf16 v[76:79], v[144:147], v[212:215], v[76:79]
	v_mfma_f32_16x16x32_bf16 v[72:75], v[160:163], v[212:215], v[72:75]
	v_mfma_f32_16x16x32_bf16 v[124:127], v[156:159], v[188:191], v[124:127]
	v_mfma_f32_16x16x32_bf16 v[120:123], v[164:167], v[188:191], v[120:123]
	v_mfma_f32_16x16x32_bf16 v[108:111], v[156:159], v[196:199], v[108:111]
	v_mfma_f32_16x16x32_bf16 v[104:107], v[164:167], v[196:199], v[104:107]
	v_mfma_f32_16x16x32_bf16 v[92:95], v[156:159], v[208:211], v[92:95]
	v_mfma_f32_16x16x32_bf16 v[88:91], v[164:167], v[208:211], v[88:91]
	v_mfma_f32_16x16x32_bf16 v[76:79], v[156:159], v[216:219], v[76:79]
	v_mfma_f32_16x16x32_bf16 v[72:75], v[164:167], v[216:219], v[72:75]
	v_mfma_f32_16x16x32_bf16 v[116:119], v[168:171], v[184:187], v[116:119]
	v_mfma_f32_16x16x32_bf16 v[112:115], v[176:179], v[184:187], v[112:115]
	v_mfma_f32_16x16x32_bf16 v[100:103], v[168:171], v[192:195], v[100:103]
	v_mfma_f32_16x16x32_bf16 v[96:99], v[176:179], v[192:195], v[96:99]
	v_mfma_f32_16x16x32_bf16 v[84:87], v[168:171], v[200:203], v[84:87]
	v_mfma_f32_16x16x32_bf16 v[80:83], v[176:179], v[200:203], v[80:83]
	v_mfma_f32_16x16x32_bf16 v[68:71], v[168:171], v[212:215], v[68:71]
	v_mfma_f32_16x16x32_bf16 v[64:67], v[176:179], v[212:215], v[64:67]
	v_mfma_f32_16x16x32_bf16 v[116:119], v[172:175], v[188:191], v[116:119]
	v_mfma_f32_16x16x32_bf16 v[112:115], v[180:183], v[188:191], v[112:115]
	v_mfma_f32_16x16x32_bf16 v[100:103], v[172:175], v[196:199], v[100:103]
	v_mfma_f32_16x16x32_bf16 v[96:99], v[180:183], v[196:199], v[96:99]
	v_mfma_f32_16x16x32_bf16 v[84:87], v[172:175], v[208:211], v[84:87]
	v_mfma_f32_16x16x32_bf16 v[80:83], v[180:183], v[208:211], v[80:83]
	v_mfma_f32_16x16x32_bf16 v[68:71], v[172:175], v[216:219], v[68:71]
	v_mfma_f32_16x16x32_bf16 v[64:67], v[180:183], v[216:219], v[64:67]
	s_barrier
	s_add_i32 s28, s55, s35
	s_mov_b32 m0, s28
	ds_read_b128 v[184:187], v153 offset:49152
	ds_read_b128 v[188:191], v153 offset:50176
	ds_read_b128 v[192:195], v153 offset:51200
	ds_read_b128 v[196:199], v153 offset:52224
	ds_read_b128 v[200:203], v153 offset:53248
	ds_read_b128 v[208:211], v153 offset:54272
	ds_read_b128 v[212:215], v153 offset:55296
	ds_read_b128 v[216:219], v153 offset:56320
	global_load_lds_dwordx4 v220, s[26:27]
	s_add_i32 m0, s28, 0x2000
	s_add_u32 s26, s26, 0x40080
	s_addc_u32 s27, s27, 0
	s_add_i32 s28, s56, s35
	global_load_lds_dwordx4 v204, s[98:99]
	s_mov_b32 m0, s28
	s_nop 0
	global_load_lds_dwordx4 v132, s[26:27]
	s_add_i32 m0, s28, 0x2000
	s_nop 0
	global_load_lds_dwordx4 v128, s[26:27]
	s_mov_b32 m0, s45
	s_nop 0
	global_load_lds_dwordx4 v221, s[100:101]
	s_cmp_lg_u32 s54, 12
	s_cbranch_scc1 .Lbal_last_10
	s_mov_b32 m0, s46
	s_nop 0
	global_load_lds_dwordx4 v205, s[100:101]
.Lbal_last_10:
	s_waitcnt vmcnt(7)
	s_waitcnt lgkmcnt(0)
	s_barrier
	s_waitcnt lgkmcnt(0)
	v_mfma_f32_16x16x32_bf16 v[60:63], v[144:147], v[184:187], v[60:63]
	v_mfma_f32_16x16x32_bf16 v[56:59], v[160:163], v[184:187], v[56:59]
	v_mfma_f32_16x16x32_bf16 v[44:47], v[144:147], v[192:195], v[44:47]
	v_mfma_f32_16x16x32_bf16 v[40:43], v[160:163], v[192:195], v[40:43]
	v_mfma_f32_16x16x32_bf16 v[28:31], v[144:147], v[200:203], v[28:31]
	v_mfma_f32_16x16x32_bf16 v[24:27], v[160:163], v[200:203], v[24:27]
	v_mfma_f32_16x16x32_bf16 v[12:15], v[144:147], v[212:215], v[12:15]
	v_mfma_f32_16x16x32_bf16 v[8:11], v[160:163], v[212:215], v[8:11]
	v_mfma_f32_16x16x32_bf16 v[60:63], v[156:159], v[188:191], v[60:63]
	v_mfma_f32_16x16x32_bf16 v[56:59], v[164:167], v[188:191], v[56:59]
	v_mfma_f32_16x16x32_bf16 v[44:47], v[156:159], v[196:199], v[44:47]
	v_mfma_f32_16x16x32_bf16 v[40:43], v[164:167], v[196:199], v[40:43]
	v_mfma_f32_16x16x32_bf16 v[28:31], v[156:159], v[208:211], v[28:31]
	v_mfma_f32_16x16x32_bf16 v[24:27], v[164:167], v[208:211], v[24:27]
	v_mfma_f32_16x16x32_bf16 v[12:15], v[156:159], v[216:219], v[12:15]
	v_mfma_f32_16x16x32_bf16 v[8:11], v[164:167], v[216:219], v[8:11]
	v_mfma_f32_16x16x32_bf16 v[52:55], v[168:171], v[184:187], v[52:55]
	v_mfma_f32_16x16x32_bf16 v[48:51], v[176:179], v[184:187], v[48:51]
	v_mfma_f32_16x16x32_bf16 v[36:39], v[168:171], v[192:195], v[36:39]
	v_mfma_f32_16x16x32_bf16 v[32:35], v[176:179], v[192:195], v[32:35]
	v_mfma_f32_16x16x32_bf16 v[20:23], v[168:171], v[200:203], v[20:23]
	v_mfma_f32_16x16x32_bf16 v[16:19], v[176:179], v[200:203], v[16:19]
	v_mfma_f32_16x16x32_bf16 v[4:7], v[168:171], v[212:215], v[4:7]
	v_mfma_f32_16x16x32_bf16 v[0:3], v[176:179], v[212:215], v[0:3]
	v_mfma_f32_16x16x32_bf16 v[52:55], v[172:175], v[188:191], v[52:55]
	v_mfma_f32_16x16x32_bf16 v[48:51], v[180:183], v[188:191], v[48:51]
	v_mfma_f32_16x16x32_bf16 v[36:39], v[172:175], v[196:199], v[36:39]
	v_mfma_f32_16x16x32_bf16 v[32:35], v[180:183], v[196:199], v[32:35]
	v_mfma_f32_16x16x32_bf16 v[20:23], v[172:175], v[208:211], v[20:23]
	v_mfma_f32_16x16x32_bf16 v[16:19], v[180:183], v[208:211], v[16:19]
	v_mfma_f32_16x16x32_bf16 v[4:7], v[172:175], v[216:219], v[4:7]
	v_mfma_f32_16x16x32_bf16 v[0:3], v[180:183], v[216:219], v[0:3]
	s_barrier
	s_add_i32 s54, s54, 2
	s_add_u32 s52, s52, 0x100
	s_addc_u32 s53, s53, 0
	s_add_u32 s24, s24, 0x100
	s_addc_u32 s25, s25, 0
	s_cmp_gt_u32 s54, 13
	s_cbranch_scc0 .LBB0_1646
	s_setprio 0
	s_and_b64 vcc, exec, s[14:15]
	s_cbranch_vccz .LBB0_1649
	s_barrier
